# stack + first K-loop iteration peeled in all ten GEMM instances (accumulators start from SrcC=0, the 64 clearing moves per tile dropped)
# speedup vs baseline: 1.0041x; 1.0041x over previous
; #define PG8_STAGE(bufoff, gbase, voff) do { _Pragma("unroll") for (int _i = 0; _i < 2; ++_i) \
;         __builtin_amdgcn_global_load_lds((const unsigned*)((const char*)(gbase) + (voff)[_i]), (PG8_LAS unsigned*)(lds + (bufoff) + ldsw + _i * 8192), 16, 0, 0); } while (0)
; #define PG8_LDA(dst, b, h) do { _Pragma("unroll") for (int m = 0; m < 4; ++m) _Pragma("unroll") for (int k = 0; k < 2; ++k) dst[m][k] = *(const PG8_LAS bf16x8*)(lds + PG8_SA(b, h) + aoff + m * 2048 + k * 1024); } while (0)
; #define PG8_LDB(dst, b, h) do { _Pragma("unroll") for (int n = 0; n < 2; ++n) _Pragma("unroll") for (int k = 0; k < 2; ++k) dst[n][k] = *(const PG8_LAS bf16x8*)(lds + PG8_SB(b, h) + boff + n * 2048 + k * 1024); } while (0)
; #define PG8_WAIT_V(n) asm volatile("s_waitcnt vmcnt(" #n ")" ::: "memory")
; #define PG8_WAIT_L(n) asm volatile("s_waitcnt lgkmcnt(" #n ")" ::: "memory")
; #define PG8_BAR __builtin_amdgcn_s_barrier()
;     ...
;     f32x4 acc[2][2][4][2];
; #pragma unroll
;     for (int a = 0; a < 2; ++a)
; #pragma unroll
;         for (int b = 0; b < 2; ++b)
; #pragma unroll
;             for (int m = 0; m < 4; ++m)
; #pragma unroll
;                 for (int n = 0; n < 2; ++n) acc[a][b][m][n] = (f32x4){0.f, 0.f, 0.f, 0.f};
;     ...
;         const char* nA = has_next ? (const char*)g.A + (size_t)nxt.pm * tstep : cA; const char* nB = has_next ? (const char*)g.Bt + (size_t)nxt.pn * tstep : cB;
;         for (int t = 0; t < nt; t += 2) {
;             if constexpr (Epi::MIDK) { if (t == nt / 2) E.midk(acc, cur, wr, wc, fr, fq); }
;             const bool last = (t == nt - 2);
;             const char* a1 = PG8_KADV(cA, (size_t)(t + 1) * kstep);
;             const char* a2 = last ? nA : PG8_KADV(cA, (size_t)(t + 2) * kstep); const char* b2 = last ? nB : PG8_KADV(cB, (size_t)(t + 2) * kstep);
;             const char* a3 = PG8_KADV(a2, kstep); const char* b3 = PG8_KADV(b2, kstep);
;             if (last && has_next) S.a_ready(nxt);
;             if constexpr (SP2) {
;             PG8_LDB(B0, 0, 0); PG8_LDB(B1, 0, 1); PG8_SCHED; PG8_LDA(At, 0, 0); PG8_STAGE(PG8_SA(1, 1), a1 + hstep, voffA);
;             PG8_WAIT_V(8); PG8_WAIT_L(0); PG8_BAR; PG8_MMA(0, 0, At, B0); PG8_MMA(0, 1, At, B1); PG8_BAR; PG8_SCHED;
;             PG8_LDA(At, 0, 1); PG8_STAGE(PG8_SB(0, 0), b2, voffB); PG8_STAGE(PG8_SB(0, 1), b2 + hstep, voffB); PG8_STAGE(PG8_SA(0, 0), a2, voffA);
.LBB0_229:
	s_ashr_i32 s73, s72, 31
	s_lshl_b64 s[20:21], s[72:73], 20
	s_add_u32 s74, s54, s20
	s_addc_u32 s75, s55, s21
	s_and_b64 s[20:21], s[4:5], exec
	s_cselect_b32 s15, s75, s81
	s_cselect_b32 s20, s74, s80
	s_ashr_i32 s71, s70, 31
	s_lshl_b64 s[22:23], s[70:71], 20
	s_add_u32 s76, s31, s22
	v_readlane_b32 s12, v255, 48
	s_addc_u32 s77, s12, s23
	s_and_b64 s[22:23], s[4:5], exec
	s_cselect_b32 s21, s77, s83
	s_cselect_b32 s22, s76, s82
	s_add_u32 s80, s80, 0x80080
	s_addc_u32 s81, s81, 0
	s_add_u32 s23, s82, 0x100
	s_addc_u32 s25, s83, 0
	s_mov_b32 s28, -2
	s_add_u32 s12, s80, 0xfff80080
	s_addc_u32 s13, s81, -1
	s_add_i32 s30, 0, 0x10000
	s_cmp_eq_u32 s28, 28
	s_cselect_b32 s85, s15, s13
	s_cselect_b32 s84, s20, s12
	s_cselect_b32 s83, s21, s25
	s_cselect_b32 s82, s22, s23
	s_add_i32 s12, 0, 0x14000
	v_add_u32_e32 v156, s30, v141
	v_add_u32_e32 v168, s12, v141
	ds_read_b128 v[144:147], v156
	ds_read_b128 v[148:151], v156 offset:1024
	ds_read_b128 v[152:155], v156 offset:2048
	ds_read_b128 v[156:159], v156 offset:3072
	ds_read_b128 v[160:163], v168
	ds_read_b128 v[164:167], v168 offset:1024
	ds_read_b128 v[182:185], v168 offset:2048
	ds_read_b128 v[186:189], v168 offset:3072
	s_add_i32 m0, s1, 0xc000
	ds_read_b128 v[190:193], v143
	ds_read_b128 v[194:197], v143 offset:1024
	ds_read_b128 v[198:201], v143 offset:2048
	ds_read_b128 v[202:205], v143 offset:3072
	ds_read_b128 v[206:209], v143 offset:4096
	ds_read_b128 v[210:213], v143 offset:5120
	ds_read_b128 v[214:217], v143 offset:6144
	ds_read_b128 v[218:221], v143 offset:7168
	global_load_lds_dwordx4 v136, s[80:81]
	s_add_i32 m0, s1, 0xe000
	s_nop 0
	global_load_lds_dwordx4 v138, s[80:81]
	s_waitcnt vmcnt(8)
	s_waitcnt lgkmcnt(0)
	s_setprio 1
	s_barrier
	v_mfma_f32_16x16x32_bf16 v[124:127], v[144:147], v[190:193], 0
	v_mfma_f32_16x16x32_bf16 v[124:127], v[148:151], v[194:197], v[124:127]
	v_mfma_f32_16x16x32_bf16 v[108:111], v[144:147], v[198:201], 0
	v_mfma_f32_16x16x32_bf16 v[108:111], v[148:151], v[202:205], v[108:111]
	v_mfma_f32_16x16x32_bf16 v[92:95], v[144:147], v[206:209], 0
	v_mfma_f32_16x16x32_bf16 v[92:95], v[148:151], v[210:213], v[92:95]
	v_mfma_f32_16x16x32_bf16 v[76:79], v[144:147], v[214:217], 0
	v_mfma_f32_16x16x32_bf16 v[76:79], v[148:151], v[218:221], v[76:79]
	v_mfma_f32_16x16x32_bf16 v[120:123], v[152:155], v[190:193], 0
	v_mfma_f32_16x16x32_bf16 v[120:123], v[156:159], v[194:197], v[120:123]
	v_mfma_f32_16x16x32_bf16 v[104:107], v[152:155], v[198:201], 0
	v_mfma_f32_16x16x32_bf16 v[104:107], v[156:159], v[202:205], v[104:107]
	v_mfma_f32_16x16x32_bf16 v[88:91], v[152:155], v[206:209], 0
	v_mfma_f32_16x16x32_bf16 v[88:91], v[156:159], v[210:213], v[88:91]
	v_mfma_f32_16x16x32_bf16 v[72:75], v[152:155], v[214:217], 0
	v_mfma_f32_16x16x32_bf16 v[72:75], v[156:159], v[218:221], v[72:75]
	v_mfma_f32_16x16x32_bf16 v[116:119], v[160:163], v[190:193], 0
	v_mfma_f32_16x16x32_bf16 v[116:119], v[164:167], v[194:197], v[116:119]
	v_mfma_f32_16x16x32_bf16 v[100:103], v[160:163], v[198:201], 0
	v_mfma_f32_16x16x32_bf16 v[100:103], v[164:167], v[202:205], v[100:103]
	v_mfma_f32_16x16x32_bf16 v[84:87], v[160:163], v[206:209], 0
	v_mfma_f32_16x16x32_bf16 v[84:87], v[164:167], v[210:213], v[84:87]
	v_mfma_f32_16x16x32_bf16 v[68:71], v[160:163], v[214:217], 0
	v_mfma_f32_16x16x32_bf16 v[68:71], v[164:167], v[218:221], v[68:71]
	v_mfma_f32_16x16x32_bf16 v[112:115], v[182:185], v[190:193], 0
	v_mfma_f32_16x16x32_bf16 v[112:115], v[186:189], v[194:197], v[112:115]
	v_mfma_f32_16x16x32_bf16 v[96:99], v[182:185], v[198:201], 0
	v_mfma_f32_16x16x32_bf16 v[96:99], v[186:189], v[202:205], v[96:99]
	v_mfma_f32_16x16x32_bf16 v[80:83], v[182:185], v[206:209], 0
	v_mfma_f32_16x16x32_bf16 v[80:83], v[186:189], v[210:213], v[80:83]
	v_mfma_f32_16x16x32_bf16 v[64:67], v[182:185], v[214:217], 0
	v_mfma_f32_16x16x32_bf16 v[64:67], v[186:189], v[218:221], v[64:67]
	s_barrier
	s_setprio 0
	s_add_i32 s13, s30, s0
	s_mov_b32 m0, s13
	ds_read_b128 v[190:193], v143 offset:16384
	ds_read_b128 v[194:197], v143 offset:17408
	ds_read_b128 v[198:201], v143 offset:18432
	ds_read_b128 v[202:205], v143 offset:19456
	ds_read_b128 v[206:209], v143 offset:20480
	ds_read_b128 v[210:213], v143 offset:21504
	ds_read_b128 v[214:217], v143 offset:22528
	ds_read_b128 v[218:221], v143 offset:23552
	global_load_lds_dwordx4 v132, s[82:83]
	s_add_i32 m0, s13, 0x2000
	s_add_u32 s42, s82, 0x80000
	s_addc_u32 s43, s83, 0
	s_add_i32 s12, s12, s0
	global_load_lds_dwordx4 v128, s[82:83]
	s_mov_b32 m0, s12
	s_nop 0
	global_load_lds_dwordx4 v132, s[42:43]
	s_add_i32 m0, s12, 0x2000
	s_nop 0
	global_load_lds_dwordx4 v128, s[42:43]
	s_mov_b32 m0, s1
	s_nop 0
	global_load_lds_dwordx4 v134, s[84:85]
	s_mov_b32 m0, s2
	s_nop 0
	global_load_lds_dwordx4 v130, s[84:85]
	s_waitcnt vmcnt(8)
	s_waitcnt lgkmcnt(0)
	s_setprio 1
	s_barrier
; #define PG8_STAGE(bufoff, gbase, voff) do { _Pragma("unroll") for (int _i = 0; _i < 2; ++_i) \
;         __builtin_amdgcn_global_load_lds((const unsigned*)((const char*)(gbase) + (voff)[_i]), (PG8_LAS unsigned*)(lds + (bufoff) + ldsw + _i * 8192), 16, 0, 0); } while (0)
; #define PG8_LDA(dst, b, h) do { _Pragma("unroll") for (int m = 0; m < 4; ++m) _Pragma("unroll") for (int k = 0; k < 2; ++k) dst[m][k] = *(const PG8_LAS bf16x8*)(lds + PG8_SA(b, h) + aoff + m * 2048 + k * 1024); } while (0)
; #define PG8_LDB(dst, b, h) do { _Pragma("unroll") for (int n = 0; n < 2; ++n) _Pragma("unroll") for (int k = 0; k < 2; ++k) dst[n][k] = *(const PG8_LAS bf16x8*)(lds + PG8_SB(b, h) + boff + n * 2048 + k * 1024); } while (0)
; #define PG8_MMA(ai, bj, At, Bt) do { __builtin_amdgcn_s_setprio(1); _Pragma("unroll") for (int m = 0; m < 4; ++m) _Pragma("unroll") for (int n = 0; n < 2; ++n) _Pragma("unroll") for (int k = 0; k < 2; ++k) \
;         acc[ai][bj][m][n] = __builtin_amdgcn_mfma_f32_16x16x32_bf16(Bt[n][k], At[m][k], acc[ai][bj][m][n], 0, 0, 0); __builtin_amdgcn_s_setprio(0); } while (0)
; #define PG8_WAIT_V(n) asm volatile("s_waitcnt vmcnt(" #n ")" ::: "memory")
; #define PG8_WAIT_L(n) asm volatile("s_waitcnt lgkmcnt(" #n ")" ::: "memory")
; #define PG8_BAR __builtin_amdgcn_s_barrier()
; #define PG8_SCHED __builtin_amdgcn_sched_barrier(0)
;     ...
;             PG8_WAIT_V(8); PG8_WAIT_L(0); PG8_BAR; PG8_MMA(0, 0, At, B0); PG8_MMA(0, 1, At, B1); PG8_BAR; PG8_SCHED;
;             PG8_LDA(At, 0, 1); PG8_STAGE(PG8_SB(0, 0), b2, voffB); PG8_STAGE(PG8_SB(0, 1), b2 + hstep, voffB); PG8_STAGE(PG8_SA(0, 0), a2, voffA);
;             PG8_WAIT_V(8); PG8_WAIT_L(0); PG8_BAR; PG8_MMA(1, 0, At, B0); PG8_MMA(1, 1, At, B1); PG8_BAR; PG8_SCHED;
;             PG8_LDB(B0, 1, 0); PG8_LDB(B1, 1, 1); PG8_SCHED; PG8_LDA(At, 1, 0); PG8_STAGE(PG8_SA(0, 1), a2 + hstep, voffA);
;             PG8_WAIT_V(8); PG8_WAIT_L(0); PG8_BAR; PG8_MMA(0, 0, At, B0); PG8_MMA(0, 1, At, B1); PG8_BAR; PG8_SCHED;
	v_mfma_f32_16x16x32_bf16 v[60:63], v[144:147], v[190:193], 0
	v_mfma_f32_16x16x32_bf16 v[60:63], v[148:151], v[194:197], v[60:63]
	v_mfma_f32_16x16x32_bf16 v[44:47], v[144:147], v[198:201], 0
	v_mfma_f32_16x16x32_bf16 v[44:47], v[148:151], v[202:205], v[44:47]
	v_mfma_f32_16x16x32_bf16 v[28:31], v[144:147], v[206:209], 0
	v_mfma_f32_16x16x32_bf16 v[28:31], v[148:151], v[210:213], v[28:31]
	v_mfma_f32_16x16x32_bf16 v[12:15], v[144:147], v[214:217], 0
	v_mfma_f32_16x16x32_bf16 v[12:15], v[148:151], v[218:221], v[12:15]
	v_mfma_f32_16x16x32_bf16 v[56:59], v[152:155], v[190:193], 0
	v_mfma_f32_16x16x32_bf16 v[56:59], v[156:159], v[194:197], v[56:59]
	v_mfma_f32_16x16x32_bf16 v[40:43], v[152:155], v[198:201], 0
	v_mfma_f32_16x16x32_bf16 v[40:43], v[156:159], v[202:205], v[40:43]
	v_mfma_f32_16x16x32_bf16 v[24:27], v[152:155], v[206:209], 0
	v_mfma_f32_16x16x32_bf16 v[24:27], v[156:159], v[210:213], v[24:27]
	v_mfma_f32_16x16x32_bf16 v[8:11], v[152:155], v[214:217], 0
	v_mfma_f32_16x16x32_bf16 v[8:11], v[156:159], v[218:221], v[8:11]
	v_mfma_f32_16x16x32_bf16 v[52:55], v[160:163], v[190:193], 0
	v_mfma_f32_16x16x32_bf16 v[52:55], v[164:167], v[194:197], v[52:55]
	v_mfma_f32_16x16x32_bf16 v[36:39], v[160:163], v[198:201], 0
	v_mfma_f32_16x16x32_bf16 v[36:39], v[164:167], v[202:205], v[36:39]
	v_mfma_f32_16x16x32_bf16 v[20:23], v[160:163], v[206:209], 0
	v_mfma_f32_16x16x32_bf16 v[20:23], v[164:167], v[210:213], v[20:23]
	v_mfma_f32_16x16x32_bf16 v[4:7], v[160:163], v[214:217], 0
	v_mfma_f32_16x16x32_bf16 v[4:7], v[164:167], v[218:221], v[4:7]
	v_mfma_f32_16x16x32_bf16 v[48:51], v[182:185], v[190:193], 0
	v_mfma_f32_16x16x32_bf16 v[48:51], v[186:189], v[194:197], v[48:51]
	v_mfma_f32_16x16x32_bf16 v[32:35], v[182:185], v[198:201], 0
	v_mfma_f32_16x16x32_bf16 v[32:35], v[186:189], v[202:205], v[32:35]
	v_mfma_f32_16x16x32_bf16 v[16:19], v[182:185], v[206:209], 0
	v_mfma_f32_16x16x32_bf16 v[16:19], v[186:189], v[210:213], v[16:19]
	v_mfma_f32_16x16x32_bf16 v[0:3], v[182:185], v[214:217], 0
	v_mfma_f32_16x16x32_bf16 v[0:3], v[186:189], v[218:221], v[0:3]
	s_barrier
	s_setprio 0
	s_add_i32 s12, 0, 0x18000
	s_add_i32 s13, 0, 0x1c000
	v_add_u32_e32 v156, s12, v141
	v_add_u32_e32 v168, s13, v141
	ds_read_b128 v[144:147], v156
	ds_read_b128 v[148:151], v156 offset:1024
	ds_read_b128 v[152:155], v156 offset:2048
	ds_read_b128 v[156:159], v156 offset:3072
	ds_read_b128 v[160:163], v168
	ds_read_b128 v[164:167], v168 offset:1024
	ds_read_b128 v[182:185], v168 offset:2048
	ds_read_b128 v[186:189], v168 offset:3072
	s_add_u32 s42, s84, 0x80000
	s_addc_u32 s43, s85, 0
	s_mov_b32 m0, s3
	ds_read_b128 v[190:193], v143 offset:32768
	ds_read_b128 v[194:197], v143 offset:33792
	ds_read_b128 v[198:201], v143 offset:34816
	ds_read_b128 v[202:205], v143 offset:35840
	ds_read_b128 v[206:209], v143 offset:36864
	ds_read_b128 v[210:213], v143 offset:37888
	ds_read_b128 v[214:217], v143 offset:38912
	ds_read_b128 v[218:221], v143 offset:39936
	global_load_lds_dwordx4 v134, s[42:43]
	s_mov_b32 m0, s8
	s_nop 0
	global_load_lds_dwordx4 v130, s[42:43]
	s_waitcnt vmcnt(8)
	s_waitcnt lgkmcnt(0)
	s_setprio 1
	s_barrier
	v_mfma_f32_16x16x32_bf16 v[124:127], v[144:147], v[190:193], v[124:127]
	v_mfma_f32_16x16x32_bf16 v[124:127], v[148:151], v[194:197], v[124:127]
	v_mfma_f32_16x16x32_bf16 v[108:111], v[144:147], v[198:201], v[108:111]
	v_mfma_f32_16x16x32_bf16 v[108:111], v[148:151], v[202:205], v[108:111]
	v_mfma_f32_16x16x32_bf16 v[92:95], v[144:147], v[206:209], v[92:95]
	v_mfma_f32_16x16x32_bf16 v[92:95], v[148:151], v[210:213], v[92:95]
	v_mfma_f32_16x16x32_bf16 v[76:79], v[144:147], v[214:217], v[76:79]
	v_mfma_f32_16x16x32_bf16 v[76:79], v[148:151], v[218:221], v[76:79]
	v_mfma_f32_16x16x32_bf16 v[120:123], v[152:155], v[190:193], v[120:123]
	v_mfma_f32_16x16x32_bf16 v[120:123], v[156:159], v[194:197], v[120:123]
	v_mfma_f32_16x16x32_bf16 v[104:107], v[152:155], v[198:201], v[104:107]
	v_mfma_f32_16x16x32_bf16 v[104:107], v[156:159], v[202:205], v[104:107]
	v_mfma_f32_16x16x32_bf16 v[88:91], v[152:155], v[206:209], v[88:91]
	v_mfma_f32_16x16x32_bf16 v[88:91], v[156:159], v[210:213], v[88:91]
	v_mfma_f32_16x16x32_bf16 v[72:75], v[152:155], v[214:217], v[72:75]
	v_mfma_f32_16x16x32_bf16 v[72:75], v[156:159], v[218:221], v[72:75]
	v_mfma_f32_16x16x32_bf16 v[116:119], v[160:163], v[190:193], v[116:119]
	v_mfma_f32_16x16x32_bf16 v[116:119], v[164:167], v[194:197], v[116:119]
	v_mfma_f32_16x16x32_bf16 v[100:103], v[160:163], v[198:201], v[100:103]
	v_mfma_f32_16x16x32_bf16 v[100:103], v[164:167], v[202:205], v[100:103]
	v_mfma_f32_16x16x32_bf16 v[84:87], v[160:163], v[206:209], v[84:87]
	v_mfma_f32_16x16x32_bf16 v[84:87], v[164:167], v[210:213], v[84:87]
	v_mfma_f32_16x16x32_bf16 v[68:71], v[160:163], v[214:217], v[68:71]
	v_mfma_f32_16x16x32_bf16 v[68:71], v[164:167], v[218:221], v[68:71]
	v_mfma_f32_16x16x32_bf16 v[112:115], v[182:185], v[190:193], v[112:115]
	v_mfma_f32_16x16x32_bf16 v[112:115], v[186:189], v[194:197], v[112:115]
	v_mfma_f32_16x16x32_bf16 v[96:99], v[182:185], v[198:201], v[96:99]
	v_mfma_f32_16x16x32_bf16 v[96:99], v[186:189], v[202:205], v[96:99]
	v_mfma_f32_16x16x32_bf16 v[80:83], v[182:185], v[206:209], v[80:83]
	v_mfma_f32_16x16x32_bf16 v[80:83], v[186:189], v[210:213], v[80:83]
	v_mfma_f32_16x16x32_bf16 v[64:67], v[182:185], v[214:217], v[64:67]
	v_mfma_f32_16x16x32_bf16 v[64:67], v[186:189], v[218:221], v[64:67]
	s_barrier
; #define PG8_STAGE(bufoff, gbase, voff) do { _Pragma("unroll") for (int _i = 0; _i < 2; ++_i) \
;         __builtin_amdgcn_global_load_lds((const unsigned*)((const char*)(gbase) + (voff)[_i]), (PG8_LAS unsigned*)(lds + (bufoff) + ldsw + _i * 8192), 16, 0, 0); } while (0)
; #define PG8_LDA(dst, b, h) do { _Pragma("unroll") for (int m = 0; m < 4; ++m) _Pragma("unroll") for (int k = 0; k < 2; ++k) dst[m][k] = *(const PG8_LAS bf16x8*)(lds + PG8_SA(b, h) + aoff + m * 2048 + k * 1024); } while (0)
; #define PG8_MMA(ai, bj, At, Bt) do { __builtin_amdgcn_s_setprio(1); _Pragma("unroll") for (int m = 0; m < 4; ++m) _Pragma("unroll") for (int n = 0; n < 2; ++n) _Pragma("unroll") for (int k = 0; k < 2; ++k) \
;         acc[ai][bj][m][n] = __builtin_amdgcn_mfma_f32_16x16x32_bf16(Bt[n][k], At[m][k], acc[ai][bj][m][n], 0, 0, 0); __builtin_amdgcn_s_setprio(0); } while (0)
; #define PG8_WAIT_V(n) asm volatile("s_waitcnt vmcnt(" #n ")" ::: "memory")
; #define PG8_WAIT_L(n) asm volatile("s_waitcnt lgkmcnt(" #n ")" ::: "memory")
; #define PG8_BAR __builtin_amdgcn_s_barrier()
; #define PG8_SCHED __builtin_amdgcn_sched_barrier(0)
;     ...
;             PG8_WAIT_V(8); PG8_WAIT_L(0); PG8_BAR; PG8_MMA(0, 0, At, B0); PG8_MMA(0, 1, At, B1); PG8_BAR; PG8_SCHED;
;             PG8_LDA(At, 1, 1); PG8_STAGE(PG8_SB(1, 0), b3, voffB); PG8_STAGE(PG8_SB(1, 1), b3 + hstep, voffB); PG8_STAGE(PG8_SA(1, 0), a3, voffA);
;             PG8_WAIT_V(8); PG8_WAIT_L(0); PG8_BAR; PG8_MMA(1, 0, At, B0); PG8_MMA(1, 1, At, B1); PG8_BAR; PG8_SCHED;
	s_setprio 0
	s_add_i32 s12, s12, s0
	s_mov_b32 m0, s12
	ds_read_b128 v[190:193], v143 offset:49152
	ds_read_b128 v[194:197], v143 offset:50176
	ds_read_b128 v[198:201], v143 offset:51200
	ds_read_b128 v[202:205], v143 offset:52224
	ds_read_b128 v[206:209], v143 offset:53248
	ds_read_b128 v[210:213], v143 offset:54272
	ds_read_b128 v[214:217], v143 offset:55296
	ds_read_b128 v[218:221], v143 offset:56320
	s_add_u32 s100, s82, s16
	s_addc_u32 s101, s83, s17
	global_load_lds_dwordx4 v132, s[100:101]
	s_add_i32 m0, s12, 0x2000
	s_add_u32 s42, s82, 0x80080
	s_addc_u32 s43, s83, 0
	s_add_i32 s12, s13, s0
	global_load_lds_dwordx4 v128, s[100:101]
	s_mov_b32 m0, s12
	s_nop 0
	global_load_lds_dwordx4 v132, s[42:43]
	s_add_i32 m0, s12, 0x2000
	s_nop 0
	global_load_lds_dwordx4 v128, s[42:43]
	s_mov_b32 m0, s9
	s_nop 0
	s_add_u32 s100, s84, s16
	s_addc_u32 s101, s85, s17
	global_load_lds_dwordx4 v134, s[100:101]
	s_mov_b32 m0, s10
	s_nop 0
	global_load_lds_dwordx4 v130, s[100:101]
	s_waitcnt vmcnt(8)
	s_waitcnt lgkmcnt(0)
	s_setprio 1
	s_barrier
	v_mfma_f32_16x16x32_bf16 v[60:63], v[144:147], v[190:193], v[60:63]
	v_mfma_f32_16x16x32_bf16 v[60:63], v[148:151], v[194:197], v[60:63]
	v_mfma_f32_16x16x32_bf16 v[44:47], v[144:147], v[198:201], v[44:47]
	v_mfma_f32_16x16x32_bf16 v[44:47], v[148:151], v[202:205], v[44:47]
	v_mfma_f32_16x16x32_bf16 v[28:31], v[144:147], v[206:209], v[28:31]
	v_mfma_f32_16x16x32_bf16 v[28:31], v[148:151], v[210:213], v[28:31]
	v_mfma_f32_16x16x32_bf16 v[12:15], v[144:147], v[214:217], v[12:15]
	v_mfma_f32_16x16x32_bf16 v[12:15], v[148:151], v[218:221], v[12:15]
	v_mfma_f32_16x16x32_bf16 v[56:59], v[152:155], v[190:193], v[56:59]
	v_mfma_f32_16x16x32_bf16 v[56:59], v[156:159], v[194:197], v[56:59]
	v_mfma_f32_16x16x32_bf16 v[40:43], v[152:155], v[198:201], v[40:43]
	v_mfma_f32_16x16x32_bf16 v[40:43], v[156:159], v[202:205], v[40:43]
	v_mfma_f32_16x16x32_bf16 v[24:27], v[152:155], v[206:209], v[24:27]
	v_mfma_f32_16x16x32_bf16 v[24:27], v[156:159], v[210:213], v[24:27]
	v_mfma_f32_16x16x32_bf16 v[8:11], v[152:155], v[214:217], v[8:11]
	v_mfma_f32_16x16x32_bf16 v[8:11], v[156:159], v[218:221], v[8:11]
	v_mfma_f32_16x16x32_bf16 v[52:55], v[160:163], v[190:193], v[52:55]
	v_mfma_f32_16x16x32_bf16 v[52:55], v[164:167], v[194:197], v[52:55]
	v_mfma_f32_16x16x32_bf16 v[36:39], v[160:163], v[198:201], v[36:39]
	v_mfma_f32_16x16x32_bf16 v[36:39], v[164:167], v[202:205], v[36:39]
	v_mfma_f32_16x16x32_bf16 v[20:23], v[160:163], v[206:209], v[20:23]
	v_mfma_f32_16x16x32_bf16 v[20:23], v[164:167], v[210:213], v[20:23]
	v_mfma_f32_16x16x32_bf16 v[4:7], v[160:163], v[214:217], v[4:7]
	v_mfma_f32_16x16x32_bf16 v[4:7], v[164:167], v[218:221], v[4:7]
	v_mfma_f32_16x16x32_bf16 v[48:51], v[182:185], v[190:193], v[48:51]
	v_mfma_f32_16x16x32_bf16 v[48:51], v[186:189], v[194:197], v[48:51]
	v_mfma_f32_16x16x32_bf16 v[32:35], v[182:185], v[198:201], v[32:35]
	v_mfma_f32_16x16x32_bf16 v[32:35], v[186:189], v[202:205], v[32:35]
	v_mfma_f32_16x16x32_bf16 v[16:19], v[182:185], v[206:209], v[16:19]
	v_mfma_f32_16x16x32_bf16 v[16:19], v[186:189], v[210:213], v[16:19]
	v_mfma_f32_16x16x32_bf16 v[0:3], v[182:185], v[214:217], v[0:3]
	v_mfma_f32_16x16x32_bf16 v[0:3], v[186:189], v[218:221], v[0:3]
	s_barrier
	s_setprio 0
	s_add_i32 s28, s28, 2
	s_add_u32 s80, s80, 0x100
	s_addc_u32 s81, s81, 0
	s_add_u32 s23, s23, 0x100
	s_addc_u32 s25, s25, 0
	s_cmp_gt_u32 s28, 29

; #define PG8_STAGE(bufoff, gbase, voff) do { _Pragma("unroll") for (int _i = 0; _i < 2; ++_i) \
;         __builtin_amdgcn_global_load_lds((const unsigned*)((const char*)(gbase) + (voff)[_i]), (PG8_LAS unsigned*)(lds + (bufoff) + ldsw + _i * 8192), 16, 0, 0); } while (0)
; #define PG8_LDA(dst, b, h) do { _Pragma("unroll") for (int m = 0; m < 4; ++m) _Pragma("unroll") for (int k = 0; k < 2; ++k) dst[m][k] = *(const PG8_LAS bf16x8*)(lds + PG8_SA(b, h) + aoff + m * 2048 + k * 1024); } while (0)
; #define PG8_LDB(dst, b, h) do { _Pragma("unroll") for (int n = 0; n < 2; ++n) _Pragma("unroll") for (int k = 0; k < 2; ++k) dst[n][k] = *(const PG8_LAS bf16x8*)(lds + PG8_SB(b, h) + boff + n * 2048 + k * 1024); } while (0)
; #define PG8_MMA(ai, bj, At, Bt) do { __builtin_amdgcn_s_setprio(1); _Pragma("unroll") for (int m = 0; m < 4; ++m) _Pragma("unroll") for (int n = 0; n < 2; ++n) _Pragma("unroll") for (int k = 0; k < 2; ++k) \
;         acc[ai][bj][m][n] = __builtin_amdgcn_mfma_f32_16x16x32_bf16(Bt[n][k], At[m][k], acc[ai][bj][m][n], 0, 0, 0); __builtin_amdgcn_s_setprio(0); } while (0)
; #define PG8_WAIT_V(n) asm volatile("s_waitcnt vmcnt(" #n ")" ::: "memory")
; #define PG8_WAIT_L(n) asm volatile("s_waitcnt lgkmcnt(" #n ")" ::: "memory")
; #define PG8_BAR __builtin_amdgcn_s_barrier()
;     ...
;         for (int t = 0; t < nt; t += 2) {
;             if constexpr (Epi::MIDK) { if (t == nt / 2) E.midk(acc, cur, wr, wc, fr, fq); }
;             const bool last = (t == nt - 2);
;             const char* a1 = PG8_KADV(cA, (size_t)(t + 1) * kstep);
;             const char* a2 = last ? nA : PG8_KADV(cA, (size_t)(t + 2) * kstep); const char* b2 = last ? nB : PG8_KADV(cB, (size_t)(t + 2) * kstep);
;             const char* a3 = PG8_KADV(a2, kstep); const char* b3 = PG8_KADV(b2, kstep);
;             if (last && has_next) S.a_ready(nxt);
;             if constexpr (SP2) {
;             PG8_LDB(B0, 0, 0); PG8_LDB(B1, 0, 1); PG8_SCHED; PG8_LDA(At, 0, 0); PG8_STAGE(PG8_SA(1, 1), a1 + hstep, voffA);
;             PG8_WAIT_V(8); PG8_WAIT_L(0); PG8_BAR; PG8_MMA(0, 0, At, B0); PG8_MMA(0, 1, At, B1); PG8_BAR; PG8_SCHED;
;             PG8_LDA(At, 0, 1); PG8_STAGE(PG8_SB(0, 0), b2, voffB); PG8_STAGE(PG8_SB(0, 1), b2 + hstep, voffB); PG8_STAGE(PG8_SA(0, 0), a2, voffA);
;             PG8_WAIT_V(8); PG8_WAIT_L(0); PG8_BAR; PG8_MMA(1, 0, At, B0); PG8_MMA(1, 1, At, B1); PG8_BAR; PG8_SCHED;
.LBB0_312:
	s_add_u32 s2, s78, 0xffffff00
	s_addc_u32 s30, s79, -1
	s_mov_b32 s3, -2
	s_add_u32 s78, s76, 0xffffff00
	s_addc_u32 s79, s77, -1
	s_add_i32 s12, 0, 0x10000
	s_cmpk_eq_i32 s3, 0x54
	s_cselect_b32 s83, s7, s79
	s_cselect_b32 s82, s6, s78
	s_cselect_b32 s81, s75, s30
	s_cselect_b32 s80, s74, s2
	s_add_i32 s13, 0, 0x14000
	v_add_u32_e32 v152, s12, v166
	v_add_u32_e32 v164, s13, v166
	ds_read_b128 v[128:131], v152
	ds_read_b128 v[132:135], v152 offset:1024
	ds_read_b128 v[148:151], v152 offset:2048
	ds_read_b128 v[152:155], v152 offset:3072
	ds_read_b128 v[156:159], v164
	ds_read_b128 v[160:163], v164 offset:1024
	ds_read_b128 v[170:173], v164 offset:2048
	ds_read_b128 v[178:181], v164 offset:3072
	s_add_i32 m0, s9, 0xc000
	ds_read_b128 v[184:187], v183
	ds_read_b128 v[188:191], v183 offset:1024
	ds_read_b128 v[192:195], v183 offset:2048
	ds_read_b128 v[196:199], v183 offset:3072
	ds_read_b128 v[200:203], v183 offset:4096
	ds_read_b128 v[204:207], v183 offset:5120
	ds_read_b128 v[208:211], v183 offset:6144
	ds_read_b128 v[212:215], v183 offset:7168
	global_load_lds_dwordx4 v144, s[76:77]
	s_add_i32 m0, s9, 0xe000
	s_nop 0
	global_load_lds_dwordx4 v146, s[76:77]
	s_waitcnt vmcnt(8)
	s_waitcnt lgkmcnt(0)
	s_setprio 1
	s_barrier
	v_mfma_f32_16x16x32_bf16 v[124:127], v[128:131], v[184:187], 0
	v_mfma_f32_16x16x32_bf16 v[124:127], v[132:135], v[188:191], v[124:127]
	v_mfma_f32_16x16x32_bf16 v[112:115], v[128:131], v[192:195], 0
	v_mfma_f32_16x16x32_bf16 v[112:115], v[132:135], v[196:199], v[112:115]
	v_mfma_f32_16x16x32_bf16 v[92:95], v[128:131], v[200:203], 0
	v_mfma_f32_16x16x32_bf16 v[92:95], v[132:135], v[204:207], v[92:95]
	v_mfma_f32_16x16x32_bf16 v[80:83], v[128:131], v[208:211], 0
	v_mfma_f32_16x16x32_bf16 v[80:83], v[132:135], v[212:215], v[80:83]
	v_mfma_f32_16x16x32_bf16 v[120:123], v[148:151], v[184:187], 0
	v_mfma_f32_16x16x32_bf16 v[120:123], v[152:155], v[188:191], v[120:123]
	v_mfma_f32_16x16x32_bf16 v[104:107], v[148:151], v[192:195], 0
	v_mfma_f32_16x16x32_bf16 v[104:107], v[152:155], v[196:199], v[104:107]
	v_mfma_f32_16x16x32_bf16 v[88:91], v[148:151], v[200:203], 0
	v_mfma_f32_16x16x32_bf16 v[88:91], v[152:155], v[204:207], v[88:91]
	v_mfma_f32_16x16x32_bf16 v[72:75], v[148:151], v[208:211], 0
	v_mfma_f32_16x16x32_bf16 v[72:75], v[152:155], v[212:215], v[72:75]
	v_mfma_f32_16x16x32_bf16 v[116:119], v[156:159], v[184:187], 0
	v_mfma_f32_16x16x32_bf16 v[116:119], v[160:163], v[188:191], v[116:119]
	v_mfma_f32_16x16x32_bf16 v[100:103], v[156:159], v[192:195], 0
	v_mfma_f32_16x16x32_bf16 v[100:103], v[160:163], v[196:199], v[100:103]
	v_mfma_f32_16x16x32_bf16 v[84:87], v[156:159], v[200:203], 0
	v_mfma_f32_16x16x32_bf16 v[84:87], v[160:163], v[204:207], v[84:87]
	v_mfma_f32_16x16x32_bf16 v[68:71], v[156:159], v[208:211], 0
	v_mfma_f32_16x16x32_bf16 v[68:71], v[160:163], v[212:215], v[68:71]
	v_mfma_f32_16x16x32_bf16 v[108:111], v[170:173], v[184:187], 0
	v_mfma_f32_16x16x32_bf16 v[108:111], v[178:181], v[188:191], v[108:111]
	v_mfma_f32_16x16x32_bf16 v[96:99], v[170:173], v[192:195], 0
	v_mfma_f32_16x16x32_bf16 v[96:99], v[178:181], v[196:199], v[96:99]
	v_mfma_f32_16x16x32_bf16 v[76:79], v[170:173], v[200:203], 0
	v_mfma_f32_16x16x32_bf16 v[76:79], v[178:181], v[204:207], v[76:79]
	v_mfma_f32_16x16x32_bf16 v[64:67], v[170:173], v[208:211], 0
	v_mfma_f32_16x16x32_bf16 v[64:67], v[178:181], v[212:215], v[64:67]
	s_barrier
	s_setprio 0
	s_add_i32 s12, s12, s8
	s_mov_b32 m0, s12
	ds_read_b128 v[184:187], v183 offset:16384
	ds_read_b128 v[188:191], v183 offset:17408
	ds_read_b128 v[192:195], v183 offset:18432
	ds_read_b128 v[196:199], v183 offset:19456
	ds_read_b128 v[200:203], v183 offset:20480
	ds_read_b128 v[204:207], v183 offset:21504
	ds_read_b128 v[208:211], v183 offset:22528
	ds_read_b128 v[212:215], v183 offset:23552
	global_load_lds_dwordx4 v138, s[80:81]
	s_add_i32 m0, s12, 0x2000
	s_add_u32 s42, s80, 0x160000
	s_addc_u32 s43, s81, 0
	s_add_i32 s12, s13, s8
	global_load_lds_dwordx4 v142, s[80:81]
	s_mov_b32 m0, s12
	s_nop 0
	global_load_lds_dwordx4 v138, s[42:43]
	s_add_i32 m0, s12, 0x2000
	s_nop 0
	global_load_lds_dwordx4 v142, s[42:43]
	s_mov_b32 m0, s9
	s_nop 0
	global_load_lds_dwordx4 v136, s[82:83]
	s_mov_b32 m0, s10
	s_nop 0
	global_load_lds_dwordx4 v140, s[82:83]
	s_waitcnt vmcnt(8)
	s_waitcnt lgkmcnt(0)
	s_setprio 1
	s_barrier
	v_mfma_f32_16x16x32_bf16 v[60:63], v[128:131], v[184:187], 0
	v_mfma_f32_16x16x32_bf16 v[60:63], v[132:135], v[188:191], v[60:63]
	v_mfma_f32_16x16x32_bf16 v[48:51], v[128:131], v[192:195], 0
	v_mfma_f32_16x16x32_bf16 v[48:51], v[132:135], v[196:199], v[48:51]
	v_mfma_f32_16x16x32_bf16 v[28:31], v[128:131], v[200:203], 0
	v_mfma_f32_16x16x32_bf16 v[28:31], v[132:135], v[204:207], v[28:31]
	v_mfma_f32_16x16x32_bf16 v[16:19], v[128:131], v[208:211], 0
	v_mfma_f32_16x16x32_bf16 v[16:19], v[132:135], v[212:215], v[16:19]
	v_mfma_f32_16x16x32_bf16 v[56:59], v[148:151], v[184:187], 0
	v_mfma_f32_16x16x32_bf16 v[56:59], v[152:155], v[188:191], v[56:59]
	v_mfma_f32_16x16x32_bf16 v[40:43], v[148:151], v[192:195], 0
	v_mfma_f32_16x16x32_bf16 v[40:43], v[152:155], v[196:199], v[40:43]
	v_mfma_f32_16x16x32_bf16 v[24:27], v[148:151], v[200:203], 0
	v_mfma_f32_16x16x32_bf16 v[24:27], v[152:155], v[204:207], v[24:27]
	v_mfma_f32_16x16x32_bf16 v[8:11], v[148:151], v[208:211], 0
	v_mfma_f32_16x16x32_bf16 v[8:11], v[152:155], v[212:215], v[8:11]
	v_mfma_f32_16x16x32_bf16 v[52:55], v[156:159], v[184:187], 0
	v_mfma_f32_16x16x32_bf16 v[52:55], v[160:163], v[188:191], v[52:55]
	v_mfma_f32_16x16x32_bf16 v[36:39], v[156:159], v[192:195], 0
	v_mfma_f32_16x16x32_bf16 v[36:39], v[160:163], v[196:199], v[36:39]
	v_mfma_f32_16x16x32_bf16 v[20:23], v[156:159], v[200:203], 0
	v_mfma_f32_16x16x32_bf16 v[20:23], v[160:163], v[204:207], v[20:23]
	v_mfma_f32_16x16x32_bf16 v[4:7], v[156:159], v[208:211], 0
	v_mfma_f32_16x16x32_bf16 v[4:7], v[160:163], v[212:215], v[4:7]
	v_mfma_f32_16x16x32_bf16 v[44:47], v[170:173], v[184:187], 0
	v_mfma_f32_16x16x32_bf16 v[44:47], v[178:181], v[188:191], v[44:47]
	v_mfma_f32_16x16x32_bf16 v[32:35], v[170:173], v[192:195], 0
	v_mfma_f32_16x16x32_bf16 v[32:35], v[178:181], v[196:199], v[32:35]
	v_mfma_f32_16x16x32_bf16 v[12:15], v[170:173], v[200:203], 0
	v_mfma_f32_16x16x32_bf16 v[12:15], v[178:181], v[204:207], v[12:15]
	v_mfma_f32_16x16x32_bf16 v[0:3], v[170:173], v[208:211], 0
	v_mfma_f32_16x16x32_bf16 v[0:3], v[178:181], v[212:215], v[0:3]
	s_barrier
; #define PG8_STAGE(bufoff, gbase, voff) do { _Pragma("unroll") for (int _i = 0; _i < 2; ++_i) \
;         __builtin_amdgcn_global_load_lds((const unsigned*)((const char*)(gbase) + (voff)[_i]), (PG8_LAS unsigned*)(lds + (bufoff) + ldsw + _i * 8192), 16, 0, 0); } while (0)
; #define PG8_LDA(dst, b, h) do { _Pragma("unroll") for (int m = 0; m < 4; ++m) _Pragma("unroll") for (int k = 0; k < 2; ++k) dst[m][k] = *(const PG8_LAS bf16x8*)(lds + PG8_SA(b, h) + aoff + m * 2048 + k * 1024); } while (0)
; #define PG8_LDB(dst, b, h) do { _Pragma("unroll") for (int n = 0; n < 2; ++n) _Pragma("unroll") for (int k = 0; k < 2; ++k) dst[n][k] = *(const PG8_LAS bf16x8*)(lds + PG8_SB(b, h) + boff + n * 2048 + k * 1024); } while (0)
; #define PG8_MMA(ai, bj, At, Bt) do { __builtin_amdgcn_s_setprio(1); _Pragma("unroll") for (int m = 0; m < 4; ++m) _Pragma("unroll") for (int n = 0; n < 2; ++n) _Pragma("unroll") for (int k = 0; k < 2; ++k) \
;         acc[ai][bj][m][n] = __builtin_amdgcn_mfma_f32_16x16x32_bf16(Bt[n][k], At[m][k], acc[ai][bj][m][n], 0, 0, 0); __builtin_amdgcn_s_setprio(0); } while (0)
; #define PG8_WAIT_V(n) asm volatile("s_waitcnt vmcnt(" #n ")" ::: "memory")
; #define PG8_WAIT_L(n) asm volatile("s_waitcnt lgkmcnt(" #n ")" ::: "memory")
; #define PG8_BAR __builtin_amdgcn_s_barrier()
; #define PG8_SCHED __builtin_amdgcn_sched_barrier(0)
;     ...
;             PG8_LDB(B0, 1, 0); PG8_LDB(B1, 1, 1); PG8_SCHED; PG8_LDA(At, 1, 0); PG8_STAGE(PG8_SA(0, 1), a2 + hstep, voffA);
;             PG8_WAIT_V(8); PG8_WAIT_L(0); PG8_BAR; PG8_MMA(0, 0, At, B0); PG8_MMA(0, 1, At, B1); PG8_BAR; PG8_SCHED;
;             PG8_LDA(At, 1, 1); PG8_STAGE(PG8_SB(1, 0), b3, voffB); PG8_STAGE(PG8_SB(1, 1), b3 + hstep, voffB); PG8_STAGE(PG8_SA(1, 0), a3, voffA);
;             PG8_WAIT_V(8); PG8_WAIT_L(0); PG8_BAR; PG8_MMA(1, 0, At, B0); PG8_MMA(1, 1, At, B1); PG8_BAR; PG8_SCHED;
	s_setprio 0
	s_add_i32 s12, 0, 0x18000
	s_add_i32 s13, 0, 0x1c000
	v_add_u32_e32 v152, s12, v166
	v_add_u32_e32 v168, s13, v166
	ds_read_b128 v[128:131], v152
	ds_read_b128 v[132:135], v152 offset:1024
	ds_read_b128 v[148:151], v152 offset:2048
	ds_read_b128 v[152:155], v152 offset:3072
	ds_read_b128 v[156:159], v168
	ds_read_b128 v[160:163], v168 offset:1024
	ds_read_b128 v[170:173], v168 offset:2048
	ds_read_b128 v[178:181], v168 offset:3072
	s_add_u32 s42, s82, 0x160000
	s_addc_u32 s43, s83, 0
	s_mov_b32 m0, s18
	ds_read_b128 v[184:187], v183 offset:32768
	ds_read_b128 v[188:191], v183 offset:33792
	ds_read_b128 v[192:195], v183 offset:34816
	ds_read_b128 v[196:199], v183 offset:35840
	ds_read_b128 v[200:203], v183 offset:36864
	ds_read_b128 v[204:207], v183 offset:37888
	ds_read_b128 v[208:211], v183 offset:38912
	ds_read_b128 v[212:215], v183 offset:39936
	global_load_lds_dwordx4 v136, s[42:43]
	s_mov_b32 m0, s19
	s_nop 0
	global_load_lds_dwordx4 v140, s[42:43]
	s_waitcnt vmcnt(8)
	s_waitcnt lgkmcnt(0)
	s_setprio 1
	s_barrier
	v_mfma_f32_16x16x32_bf16 v[124:127], v[128:131], v[184:187], v[124:127]
	v_mfma_f32_16x16x32_bf16 v[124:127], v[132:135], v[188:191], v[124:127]
	v_mfma_f32_16x16x32_bf16 v[112:115], v[128:131], v[192:195], v[112:115]
	v_mfma_f32_16x16x32_bf16 v[112:115], v[132:135], v[196:199], v[112:115]
	v_mfma_f32_16x16x32_bf16 v[92:95], v[128:131], v[200:203], v[92:95]
	v_mfma_f32_16x16x32_bf16 v[92:95], v[132:135], v[204:207], v[92:95]
	v_mfma_f32_16x16x32_bf16 v[80:83], v[128:131], v[208:211], v[80:83]
	v_mfma_f32_16x16x32_bf16 v[80:83], v[132:135], v[212:215], v[80:83]
	v_mfma_f32_16x16x32_bf16 v[120:123], v[148:151], v[184:187], v[120:123]
	v_mfma_f32_16x16x32_bf16 v[120:123], v[152:155], v[188:191], v[120:123]
	v_mfma_f32_16x16x32_bf16 v[104:107], v[148:151], v[192:195], v[104:107]
	v_mfma_f32_16x16x32_bf16 v[104:107], v[152:155], v[196:199], v[104:107]
	v_mfma_f32_16x16x32_bf16 v[88:91], v[148:151], v[200:203], v[88:91]
	v_mfma_f32_16x16x32_bf16 v[88:91], v[152:155], v[204:207], v[88:91]
	v_mfma_f32_16x16x32_bf16 v[72:75], v[148:151], v[208:211], v[72:75]
	v_mfma_f32_16x16x32_bf16 v[72:75], v[152:155], v[212:215], v[72:75]
	v_mfma_f32_16x16x32_bf16 v[116:119], v[156:159], v[184:187], v[116:119]
	v_mfma_f32_16x16x32_bf16 v[116:119], v[160:163], v[188:191], v[116:119]
	v_mfma_f32_16x16x32_bf16 v[100:103], v[156:159], v[192:195], v[100:103]
	v_mfma_f32_16x16x32_bf16 v[100:103], v[160:163], v[196:199], v[100:103]
	v_mfma_f32_16x16x32_bf16 v[84:87], v[156:159], v[200:203], v[84:87]
	v_mfma_f32_16x16x32_bf16 v[84:87], v[160:163], v[204:207], v[84:87]
	v_mfma_f32_16x16x32_bf16 v[68:71], v[156:159], v[208:211], v[68:71]
	v_mfma_f32_16x16x32_bf16 v[68:71], v[160:163], v[212:215], v[68:71]
	v_mfma_f32_16x16x32_bf16 v[108:111], v[170:173], v[184:187], v[108:111]
	v_mfma_f32_16x16x32_bf16 v[108:111], v[178:181], v[188:191], v[108:111]
	v_mfma_f32_16x16x32_bf16 v[96:99], v[170:173], v[192:195], v[96:99]
	v_mfma_f32_16x16x32_bf16 v[96:99], v[178:181], v[196:199], v[96:99]
	v_mfma_f32_16x16x32_bf16 v[76:79], v[170:173], v[200:203], v[76:79]
	v_mfma_f32_16x16x32_bf16 v[76:79], v[178:181], v[204:207], v[76:79]
	v_mfma_f32_16x16x32_bf16 v[64:67], v[170:173], v[208:211], v[64:67]
	v_mfma_f32_16x16x32_bf16 v[64:67], v[178:181], v[212:215], v[64:67]
	s_barrier
	s_setprio 0
	s_add_i32 s12, s12, s8
	s_mov_b32 m0, s12
	ds_read_b128 v[184:187], v183 offset:49152
	ds_read_b128 v[188:191], v183 offset:50176
	ds_read_b128 v[192:195], v183 offset:51200
	ds_read_b128 v[196:199], v183 offset:52224
	ds_read_b128 v[200:203], v183 offset:53248
	ds_read_b128 v[204:207], v183 offset:54272
	ds_read_b128 v[208:211], v183 offset:55296
	ds_read_b128 v[212:215], v183 offset:56320
	s_add_u32 s100, s80, s38
	s_addc_u32 s101, s81, s39
	global_load_lds_dwordx4 v138, s[100:101]
	s_add_i32 m0, s12, 0x2000
	s_add_u32 s42, s80, 0x15ff80
	s_addc_u32 s43, s81, 0
	s_add_i32 s12, s13, s8
	global_load_lds_dwordx4 v142, s[100:101]
	s_mov_b32 m0, s12
	s_nop 0
	global_load_lds_dwordx4 v138, s[42:43]
	s_add_i32 m0, s12, 0x2000
	s_nop 0
	global_load_lds_dwordx4 v142, s[42:43]
	s_mov_b32 m0, s20
	s_nop 0
	s_add_u32 s100, s82, s38
	s_addc_u32 s101, s83, s39
	global_load_lds_dwordx4 v136, s[100:101]
	s_mov_b32 m0, s21
	s_nop 0
	global_load_lds_dwordx4 v140, s[100:101]
	s_waitcnt vmcnt(8)
	s_waitcnt lgkmcnt(0)
	s_setprio 1
	s_barrier
	v_mfma_f32_16x16x32_bf16 v[60:63], v[128:131], v[184:187], v[60:63]
	v_mfma_f32_16x16x32_bf16 v[60:63], v[132:135], v[188:191], v[60:63]
	v_mfma_f32_16x16x32_bf16 v[48:51], v[128:131], v[192:195], v[48:51]
	v_mfma_f32_16x16x32_bf16 v[48:51], v[132:135], v[196:199], v[48:51]
	v_mfma_f32_16x16x32_bf16 v[28:31], v[128:131], v[200:203], v[28:31]
	v_mfma_f32_16x16x32_bf16 v[28:31], v[132:135], v[204:207], v[28:31]
	v_mfma_f32_16x16x32_bf16 v[16:19], v[128:131], v[208:211], v[16:19]
	v_mfma_f32_16x16x32_bf16 v[16:19], v[132:135], v[212:215], v[16:19]
	v_mfma_f32_16x16x32_bf16 v[56:59], v[148:151], v[184:187], v[56:59]
	v_mfma_f32_16x16x32_bf16 v[56:59], v[152:155], v[188:191], v[56:59]
	v_mfma_f32_16x16x32_bf16 v[40:43], v[148:151], v[192:195], v[40:43]
	v_mfma_f32_16x16x32_bf16 v[40:43], v[152:155], v[196:199], v[40:43]
	v_mfma_f32_16x16x32_bf16 v[24:27], v[148:151], v[200:203], v[24:27]
	v_mfma_f32_16x16x32_bf16 v[24:27], v[152:155], v[204:207], v[24:27]
	v_mfma_f32_16x16x32_bf16 v[8:11], v[148:151], v[208:211], v[8:11]
	v_mfma_f32_16x16x32_bf16 v[8:11], v[152:155], v[212:215], v[8:11]
	v_mfma_f32_16x16x32_bf16 v[52:55], v[156:159], v[184:187], v[52:55]
	v_mfma_f32_16x16x32_bf16 v[52:55], v[160:163], v[188:191], v[52:55]
	v_mfma_f32_16x16x32_bf16 v[36:39], v[156:159], v[192:195], v[36:39]
	v_mfma_f32_16x16x32_bf16 v[36:39], v[160:163], v[196:199], v[36:39]
	v_mfma_f32_16x16x32_bf16 v[20:23], v[156:159], v[200:203], v[20:23]
	v_mfma_f32_16x16x32_bf16 v[20:23], v[160:163], v[204:207], v[20:23]
	v_mfma_f32_16x16x32_bf16 v[4:7], v[156:159], v[208:211], v[4:7]
	v_mfma_f32_16x16x32_bf16 v[4:7], v[160:163], v[212:215], v[4:7]
	v_mfma_f32_16x16x32_bf16 v[44:47], v[170:173], v[184:187], v[44:47]
	v_mfma_f32_16x16x32_bf16 v[44:47], v[178:181], v[188:191], v[44:47]
	v_mfma_f32_16x16x32_bf16 v[32:35], v[170:173], v[192:195], v[32:35]
	v_mfma_f32_16x16x32_bf16 v[32:35], v[178:181], v[196:199], v[32:35]
	v_mfma_f32_16x16x32_bf16 v[12:15], v[170:173], v[200:203], v[12:15]
	v_mfma_f32_16x16x32_bf16 v[12:15], v[178:181], v[204:207], v[12:15]
	v_mfma_f32_16x16x32_bf16 v[0:3], v[170:173], v[208:211], v[0:3]
	v_mfma_f32_16x16x32_bf16 v[0:3], v[178:181], v[212:215], v[0:3]
	s_barrier
	s_setprio 0
	s_add_i32 s3, s3, 2
	s_add_u32 s2, s2, 0xffffff00
	s_addc_u32 s30, s30, -1
	s_cmpk_gt_u32 s3, 0x55
	s_mov_b64 s[76:77], s[78:79]

; #define PG8_STAGE(bufoff, gbase, voff) do { _Pragma("unroll") for (int _i = 0; _i < 2; ++_i) \
;         __builtin_amdgcn_global_load_lds((const unsigned*)((const char*)(gbase) + (voff)[_i]), (PG8_LAS unsigned*)(lds + (bufoff) + ldsw + _i * 8192), 16, 0, 0); } while (0)
; #define PG8_LDA(dst, b, h) do { _Pragma("unroll") for (int m = 0; m < 4; ++m) _Pragma("unroll") for (int k = 0; k < 2; ++k) dst[m][k] = *(const PG8_LAS bf16x8*)(lds + PG8_SA(b, h) + aoff + m * 2048 + k * 1024); } while (0)
; #define PG8_LDB(dst, b, h) do { _Pragma("unroll") for (int n = 0; n < 2; ++n) _Pragma("unroll") for (int k = 0; k < 2; ++k) dst[n][k] = *(const PG8_LAS bf16x8*)(lds + PG8_SB(b, h) + boff + n * 2048 + k * 1024); } while (0)
; #define PG8_MMA(ai, bj, At, Bt) do { __builtin_amdgcn_s_setprio(1); _Pragma("unroll") for (int m = 0; m < 4; ++m) _Pragma("unroll") for (int n = 0; n < 2; ++n) _Pragma("unroll") for (int k = 0; k < 2; ++k) \
;         acc[ai][bj][m][n] = __builtin_amdgcn_mfma_f32_16x16x32_bf16(Bt[n][k], At[m][k], acc[ai][bj][m][n], 0, 0, 0); __builtin_amdgcn_s_setprio(0); } while (0)
; #define PG8_WAIT_V(n) asm volatile("s_waitcnt vmcnt(" #n ")" ::: "memory")
; #define PG8_WAIT_L(n) asm volatile("s_waitcnt lgkmcnt(" #n ")" ::: "memory")
; #define PG8_BAR __builtin_amdgcn_s_barrier()
;     ...
;         for (int t = 0; t < nt; t += 2) {
;             if constexpr (Epi::MIDK) { if (t == nt / 2) E.midk(acc, cur, wr, wc, fr, fq); }
;             const bool last = (t == nt - 2);
;             const char* a1 = PG8_KADV(cA, (size_t)(t + 1) * kstep);
;             const char* a2 = last ? nA : PG8_KADV(cA, (size_t)(t + 2) * kstep); const char* b2 = last ? nB : PG8_KADV(cB, (size_t)(t + 2) * kstep);
;             const char* a3 = PG8_KADV(a2, kstep); const char* b3 = PG8_KADV(b2, kstep);
;             if (last && has_next) S.a_ready(nxt);
;             if constexpr (SP2) {
;             PG8_LDB(B0, 0, 0); PG8_LDB(B1, 0, 1); PG8_SCHED; PG8_LDA(At, 0, 0); PG8_STAGE(PG8_SA(1, 1), a1 + hstep, voffA);
;             PG8_WAIT_V(8); PG8_WAIT_L(0); PG8_BAR; PG8_MMA(0, 0, At, B0); PG8_MMA(0, 1, At, B1); PG8_BAR; PG8_SCHED;
;             PG8_LDA(At, 0, 1); PG8_STAGE(PG8_SB(0, 0), b2, voffB); PG8_STAGE(PG8_SB(0, 1), b2 + hstep, voffB); PG8_STAGE(PG8_SA(0, 0), a2, voffA);
;             PG8_WAIT_V(8); PG8_WAIT_L(0); PG8_BAR; PG8_MMA(1, 0, At, B0); PG8_MMA(1, 1, At, B1); PG8_BAR; PG8_SCHED;
.LBB0_342:
	s_add_u32 s2, s78, 0xffffff00
	v_mov_b64_e32 v[176:177], 0x200
	v_mov_b64_e32 v[228:229], 0xaff
	s_addc_u32 s30, s79, -1
	s_mov_b32 s3, -2
	s_add_u32 s78, s76, 0xffffff00
	s_addc_u32 s79, s77, -1
	s_add_i32 s12, 0, 0x10000
	s_cmpk_eq_i32 s3, 0x54
	s_cselect_b32 s83, s7, s79
	s_cselect_b32 s82, s6, s78
	s_cselect_b32 s81, s75, s30
	s_cselect_b32 s80, s74, s2
	s_add_i32 s13, 0, 0x14000
	v_add_u32_e32 v140, s12, v233
	v_add_u32_e32 v156, s13, v233
	ds_read_b128 v[128:131], v140
	ds_read_b128 v[132:135], v140 offset:1024
	ds_read_b128 v[136:139], v140 offset:2048
	ds_read_b128 v[140:143], v140 offset:3072
	ds_read_b128 v[144:147], v156
	ds_read_b128 v[148:151], v156 offset:1024
	ds_read_b128 v[152:155], v156 offset:2048
	ds_read_b128 v[156:159], v156 offset:3072
	s_add_i32 m0, s9, 0xc000
	ds_read_b128 v[160:163], v236
	ds_read_b128 v[164:167], v236 offset:1024
	ds_read_b128 v[194:197], v236 offset:2048
	ds_read_b128 v[198:201], v236 offset:3072
	ds_read_b128 v[202:205], v236 offset:4096
	ds_read_b128 v[206:209], v236 offset:5120
	ds_read_b128 v[210:213], v236 offset:6144
	ds_read_b128 v[214:217], v236 offset:7168
	global_load_lds_dwordx4 v190, s[76:77]
	s_add_i32 m0, s9, 0xe000
	s_nop 0
	global_load_lds_dwordx4 v192, s[76:77]
	s_waitcnt vmcnt(8)
	s_waitcnt lgkmcnt(0)
	s_setprio 1
	s_barrier
	v_mfma_f32_16x16x32_bf16 v[124:127], v[128:131], v[160:163], 0
	v_mfma_f32_16x16x32_bf16 v[124:127], v[132:135], v[164:167], v[124:127]
	v_mfma_f32_16x16x32_bf16 v[108:111], v[128:131], v[194:197], 0
	v_mfma_f32_16x16x32_bf16 v[108:111], v[132:135], v[198:201], v[108:111]
	v_mfma_f32_16x16x32_bf16 v[100:103], v[128:131], v[202:205], 0
	v_mfma_f32_16x16x32_bf16 v[100:103], v[132:135], v[206:209], v[100:103]
	v_mfma_f32_16x16x32_bf16 v[84:87], v[128:131], v[210:213], 0
	v_mfma_f32_16x16x32_bf16 v[84:87], v[132:135], v[214:217], v[84:87]
	v_mfma_f32_16x16x32_bf16 v[120:123], v[136:139], v[160:163], 0
	v_mfma_f32_16x16x32_bf16 v[120:123], v[140:143], v[164:167], v[120:123]
	v_mfma_f32_16x16x32_bf16 v[104:107], v[136:139], v[194:197], 0
	v_mfma_f32_16x16x32_bf16 v[104:107], v[140:143], v[198:201], v[104:107]
	v_mfma_f32_16x16x32_bf16 v[92:95], v[136:139], v[202:205], 0
	v_mfma_f32_16x16x32_bf16 v[92:95], v[140:143], v[206:209], v[92:95]
	v_mfma_f32_16x16x32_bf16 v[76:79], v[136:139], v[210:213], 0
	v_mfma_f32_16x16x32_bf16 v[76:79], v[140:143], v[214:217], v[76:79]
	v_mfma_f32_16x16x32_bf16 v[116:119], v[144:147], v[160:163], 0
	v_mfma_f32_16x16x32_bf16 v[116:119], v[148:151], v[164:167], v[116:119]
	v_mfma_f32_16x16x32_bf16 v[96:99], v[144:147], v[194:197], 0
	v_mfma_f32_16x16x32_bf16 v[96:99], v[148:151], v[198:201], v[96:99]
	v_mfma_f32_16x16x32_bf16 v[80:83], v[144:147], v[202:205], 0
	v_mfma_f32_16x16x32_bf16 v[80:83], v[148:151], v[206:209], v[80:83]
	v_mfma_f32_16x16x32_bf16 v[68:71], v[144:147], v[210:213], 0
	v_mfma_f32_16x16x32_bf16 v[68:71], v[148:151], v[214:217], v[68:71]
	v_mfma_f32_16x16x32_bf16 v[112:115], v[152:155], v[160:163], 0
	v_mfma_f32_16x16x32_bf16 v[112:115], v[156:159], v[164:167], v[112:115]
	v_mfma_f32_16x16x32_bf16 v[88:91], v[152:155], v[194:197], 0
	v_mfma_f32_16x16x32_bf16 v[88:91], v[156:159], v[198:201], v[88:91]
	v_mfma_f32_16x16x32_bf16 v[72:75], v[152:155], v[202:205], 0
	v_mfma_f32_16x16x32_bf16 v[72:75], v[156:159], v[206:209], v[72:75]
	v_mfma_f32_16x16x32_bf16 v[64:67], v[152:155], v[210:213], 0
	v_mfma_f32_16x16x32_bf16 v[64:67], v[156:159], v[214:217], v[64:67]
	s_barrier
	s_setprio 0
	s_add_i32 s12, s12, s8
	s_mov_b32 m0, s12
	ds_read_b128 v[160:163], v236 offset:16384
	ds_read_b128 v[164:167], v236 offset:17408
	ds_read_b128 v[194:197], v236 offset:18432
	ds_read_b128 v[198:201], v236 offset:19456
	ds_read_b128 v[202:205], v236 offset:20480
	ds_read_b128 v[206:209], v236 offset:21504
	ds_read_b128 v[210:213], v236 offset:22528
	ds_read_b128 v[214:217], v236 offset:23552
	global_load_lds_dwordx4 v184, s[80:81]
	s_add_i32 m0, s12, 0x2000
	s_add_u32 s42, s80, 0x160000
	s_addc_u32 s43, s81, 0
	s_add_i32 s12, s13, s8
	global_load_lds_dwordx4 v188, s[80:81]
	s_mov_b32 m0, s12
	s_nop 0
	global_load_lds_dwordx4 v184, s[42:43]
	s_add_i32 m0, s12, 0x2000
	s_nop 0
	global_load_lds_dwordx4 v188, s[42:43]
	s_mov_b32 m0, s9
	s_nop 0
	global_load_lds_dwordx4 v182, s[82:83]
	s_mov_b32 m0, s10
	s_nop 0
	global_load_lds_dwordx4 v186, s[82:83]
	s_waitcnt vmcnt(8)
	s_waitcnt lgkmcnt(0)
	s_setprio 1
	s_barrier
	v_mfma_f32_16x16x32_bf16 v[60:63], v[128:131], v[160:163], 0
	v_mfma_f32_16x16x32_bf16 v[60:63], v[132:135], v[164:167], v[60:63]
	v_mfma_f32_16x16x32_bf16 v[52:55], v[128:131], v[194:197], 0
	v_mfma_f32_16x16x32_bf16 v[52:55], v[132:135], v[198:201], v[52:55]
	v_mfma_f32_16x16x32_bf16 v[36:39], v[128:131], v[202:205], 0
	v_mfma_f32_16x16x32_bf16 v[36:39], v[132:135], v[206:209], v[36:39]
	v_mfma_f32_16x16x32_bf16 v[20:23], v[128:131], v[210:213], 0
	v_mfma_f32_16x16x32_bf16 v[20:23], v[132:135], v[214:217], v[20:23]
	v_mfma_f32_16x16x32_bf16 v[56:59], v[136:139], v[160:163], 0
	v_mfma_f32_16x16x32_bf16 v[56:59], v[140:143], v[164:167], v[56:59]
	v_mfma_f32_16x16x32_bf16 v[44:47], v[136:139], v[194:197], 0
	v_mfma_f32_16x16x32_bf16 v[44:47], v[140:143], v[198:201], v[44:47]
	v_mfma_f32_16x16x32_bf16 v[28:31], v[136:139], v[202:205], 0
	v_mfma_f32_16x16x32_bf16 v[28:31], v[140:143], v[206:209], v[28:31]
	v_mfma_f32_16x16x32_bf16 v[12:15], v[136:139], v[210:213], 0
	v_mfma_f32_16x16x32_bf16 v[12:15], v[140:143], v[214:217], v[12:15]
	v_mfma_f32_16x16x32_bf16 v[48:51], v[144:147], v[160:163], 0
	v_mfma_f32_16x16x32_bf16 v[48:51], v[148:151], v[164:167], v[48:51]
	v_mfma_f32_16x16x32_bf16 v[32:35], v[144:147], v[194:197], 0
	v_mfma_f32_16x16x32_bf16 v[32:35], v[148:151], v[198:201], v[32:35]
	v_mfma_f32_16x16x32_bf16 v[16:19], v[144:147], v[202:205], 0
	v_mfma_f32_16x16x32_bf16 v[16:19], v[148:151], v[206:209], v[16:19]
	v_mfma_f32_16x16x32_bf16 v[4:7], v[144:147], v[210:213], 0
	v_mfma_f32_16x16x32_bf16 v[4:7], v[148:151], v[214:217], v[4:7]
	v_mfma_f32_16x16x32_bf16 v[40:43], v[152:155], v[160:163], 0
	v_mfma_f32_16x16x32_bf16 v[40:43], v[156:159], v[164:167], v[40:43]
	v_mfma_f32_16x16x32_bf16 v[24:27], v[152:155], v[194:197], 0
	v_mfma_f32_16x16x32_bf16 v[24:27], v[156:159], v[198:201], v[24:27]
	v_mfma_f32_16x16x32_bf16 v[8:11], v[152:155], v[202:205], 0
	v_mfma_f32_16x16x32_bf16 v[8:11], v[156:159], v[206:209], v[8:11]
	v_mfma_f32_16x16x32_bf16 v[0:3], v[152:155], v[210:213], 0
	v_mfma_f32_16x16x32_bf16 v[0:3], v[156:159], v[214:217], v[0:3]
	s_barrier
; #define PG8_STAGE(bufoff, gbase, voff) do { _Pragma("unroll") for (int _i = 0; _i < 2; ++_i) \
;         __builtin_amdgcn_global_load_lds((const unsigned*)((const char*)(gbase) + (voff)[_i]), (PG8_LAS unsigned*)(lds + (bufoff) + ldsw + _i * 8192), 16, 0, 0); } while (0)
; #define PG8_LDA(dst, b, h) do { _Pragma("unroll") for (int m = 0; m < 4; ++m) _Pragma("unroll") for (int k = 0; k < 2; ++k) dst[m][k] = *(const PG8_LAS bf16x8*)(lds + PG8_SA(b, h) + aoff + m * 2048 + k * 1024); } while (0)
; #define PG8_LDB(dst, b, h) do { _Pragma("unroll") for (int n = 0; n < 2; ++n) _Pragma("unroll") for (int k = 0; k < 2; ++k) dst[n][k] = *(const PG8_LAS bf16x8*)(lds + PG8_SB(b, h) + boff + n * 2048 + k * 1024); } while (0)
; #define PG8_MMA(ai, bj, At, Bt) do { __builtin_amdgcn_s_setprio(1); _Pragma("unroll") for (int m = 0; m < 4; ++m) _Pragma("unroll") for (int n = 0; n < 2; ++n) _Pragma("unroll") for (int k = 0; k < 2; ++k) \
;         acc[ai][bj][m][n] = __builtin_amdgcn_mfma_f32_16x16x32_bf16(Bt[n][k], At[m][k], acc[ai][bj][m][n], 0, 0, 0); __builtin_amdgcn_s_setprio(0); } while (0)
; #define PG8_WAIT_V(n) asm volatile("s_waitcnt vmcnt(" #n ")" ::: "memory")
; #define PG8_WAIT_L(n) asm volatile("s_waitcnt lgkmcnt(" #n ")" ::: "memory")
; #define PG8_BAR __builtin_amdgcn_s_barrier()
; #define PG8_SCHED __builtin_amdgcn_sched_barrier(0)
;     ...
;             PG8_LDB(B0, 1, 0); PG8_LDB(B1, 1, 1); PG8_SCHED; PG8_LDA(At, 1, 0); PG8_STAGE(PG8_SA(0, 1), a2 + hstep, voffA);
;             PG8_WAIT_V(8); PG8_WAIT_L(0); PG8_BAR; PG8_MMA(0, 0, At, B0); PG8_MMA(0, 1, At, B1); PG8_BAR; PG8_SCHED;
;             PG8_LDA(At, 1, 1); PG8_STAGE(PG8_SB(1, 0), b3, voffB); PG8_STAGE(PG8_SB(1, 1), b3 + hstep, voffB); PG8_STAGE(PG8_SA(1, 0), a3, voffA);
;             PG8_WAIT_V(8); PG8_WAIT_L(0); PG8_BAR; PG8_MMA(1, 0, At, B0); PG8_MMA(1, 1, At, B1); PG8_BAR; PG8_SCHED;
	s_setprio 0
	s_add_i32 s12, 0, 0x18000
	s_add_i32 s13, 0, 0x1c000
	v_add_u32_e32 v140, s12, v233
	v_add_u32_e32 v156, s13, v233
	ds_read_b128 v[128:131], v140
	ds_read_b128 v[132:135], v140 offset:1024
	ds_read_b128 v[136:139], v140 offset:2048
	ds_read_b128 v[140:143], v140 offset:3072
	ds_read_b128 v[144:147], v156
	ds_read_b128 v[148:151], v156 offset:1024
	ds_read_b128 v[152:155], v156 offset:2048
	ds_read_b128 v[156:159], v156 offset:3072
	s_add_u32 s42, s82, 0x160000
	s_addc_u32 s43, s83, 0
	s_mov_b32 m0, s18
	ds_read_b128 v[160:163], v236 offset:32768
	ds_read_b128 v[164:167], v236 offset:33792
	ds_read_b128 v[194:197], v236 offset:34816
	ds_read_b128 v[198:201], v236 offset:35840
	ds_read_b128 v[202:205], v236 offset:36864
	ds_read_b128 v[206:209], v236 offset:37888
	ds_read_b128 v[210:213], v236 offset:38912
	ds_read_b128 v[214:217], v236 offset:39936
	global_load_lds_dwordx4 v182, s[42:43]
	s_mov_b32 m0, s19
	s_nop 0
	global_load_lds_dwordx4 v186, s[42:43]
	s_waitcnt vmcnt(8)
	s_waitcnt lgkmcnt(0)
	s_setprio 1
	s_barrier
	v_mfma_f32_16x16x32_bf16 v[124:127], v[128:131], v[160:163], v[124:127]
	v_mfma_f32_16x16x32_bf16 v[124:127], v[132:135], v[164:167], v[124:127]
	v_mfma_f32_16x16x32_bf16 v[108:111], v[128:131], v[194:197], v[108:111]
	v_mfma_f32_16x16x32_bf16 v[108:111], v[132:135], v[198:201], v[108:111]
	v_mfma_f32_16x16x32_bf16 v[100:103], v[128:131], v[202:205], v[100:103]
	v_mfma_f32_16x16x32_bf16 v[100:103], v[132:135], v[206:209], v[100:103]
	v_mfma_f32_16x16x32_bf16 v[84:87], v[128:131], v[210:213], v[84:87]
	v_mfma_f32_16x16x32_bf16 v[84:87], v[132:135], v[214:217], v[84:87]
	v_mfma_f32_16x16x32_bf16 v[120:123], v[136:139], v[160:163], v[120:123]
	v_mfma_f32_16x16x32_bf16 v[120:123], v[140:143], v[164:167], v[120:123]
	v_mfma_f32_16x16x32_bf16 v[104:107], v[136:139], v[194:197], v[104:107]
	v_mfma_f32_16x16x32_bf16 v[104:107], v[140:143], v[198:201], v[104:107]
	v_mfma_f32_16x16x32_bf16 v[92:95], v[136:139], v[202:205], v[92:95]
	v_mfma_f32_16x16x32_bf16 v[92:95], v[140:143], v[206:209], v[92:95]
	v_mfma_f32_16x16x32_bf16 v[76:79], v[136:139], v[210:213], v[76:79]
	v_mfma_f32_16x16x32_bf16 v[76:79], v[140:143], v[214:217], v[76:79]
	v_mfma_f32_16x16x32_bf16 v[116:119], v[144:147], v[160:163], v[116:119]
	v_mfma_f32_16x16x32_bf16 v[116:119], v[148:151], v[164:167], v[116:119]
	v_mfma_f32_16x16x32_bf16 v[96:99], v[144:147], v[194:197], v[96:99]
	v_mfma_f32_16x16x32_bf16 v[96:99], v[148:151], v[198:201], v[96:99]
	v_mfma_f32_16x16x32_bf16 v[80:83], v[144:147], v[202:205], v[80:83]
	v_mfma_f32_16x16x32_bf16 v[80:83], v[148:151], v[206:209], v[80:83]
	v_mfma_f32_16x16x32_bf16 v[68:71], v[144:147], v[210:213], v[68:71]
	v_mfma_f32_16x16x32_bf16 v[68:71], v[148:151], v[214:217], v[68:71]
	v_mfma_f32_16x16x32_bf16 v[112:115], v[152:155], v[160:163], v[112:115]
	v_mfma_f32_16x16x32_bf16 v[112:115], v[156:159], v[164:167], v[112:115]
	v_mfma_f32_16x16x32_bf16 v[88:91], v[152:155], v[194:197], v[88:91]
	v_mfma_f32_16x16x32_bf16 v[88:91], v[156:159], v[198:201], v[88:91]
	v_mfma_f32_16x16x32_bf16 v[72:75], v[152:155], v[202:205], v[72:75]
	v_mfma_f32_16x16x32_bf16 v[72:75], v[156:159], v[206:209], v[72:75]
	v_mfma_f32_16x16x32_bf16 v[64:67], v[152:155], v[210:213], v[64:67]
	v_mfma_f32_16x16x32_bf16 v[64:67], v[156:159], v[214:217], v[64:67]
	s_barrier
	s_setprio 0
	s_add_i32 s12, s12, s8
	s_mov_b32 m0, s12
	ds_read_b128 v[160:163], v236 offset:49152
	ds_read_b128 v[164:167], v236 offset:50176
	ds_read_b128 v[194:197], v236 offset:51200
	ds_read_b128 v[198:201], v236 offset:52224
	ds_read_b128 v[202:205], v236 offset:53248
	ds_read_b128 v[206:209], v236 offset:54272
	ds_read_b128 v[210:213], v236 offset:55296
	ds_read_b128 v[214:217], v236 offset:56320
	s_add_u32 s100, s80, s38
	s_addc_u32 s101, s81, s39
	global_load_lds_dwordx4 v184, s[100:101]
	s_add_i32 m0, s12, 0x2000
	s_add_u32 s42, s80, 0x15ff80
	s_addc_u32 s43, s81, 0
	s_add_i32 s12, s13, s8
	global_load_lds_dwordx4 v188, s[100:101]
	s_mov_b32 m0, s12
	s_nop 0
	global_load_lds_dwordx4 v184, s[42:43]
	s_add_i32 m0, s12, 0x2000
	s_nop 0
	global_load_lds_dwordx4 v188, s[42:43]
	s_mov_b32 m0, s20
	s_nop 0
	s_add_u32 s100, s82, s38
	s_addc_u32 s101, s83, s39
	global_load_lds_dwordx4 v182, s[100:101]
	s_mov_b32 m0, s21
	s_nop 0
	global_load_lds_dwordx4 v186, s[100:101]
	s_waitcnt vmcnt(8)
	s_waitcnt lgkmcnt(0)
	s_setprio 1
	s_barrier
	v_mfma_f32_16x16x32_bf16 v[60:63], v[128:131], v[160:163], v[60:63]
	v_mfma_f32_16x16x32_bf16 v[60:63], v[132:135], v[164:167], v[60:63]
	v_mfma_f32_16x16x32_bf16 v[52:55], v[128:131], v[194:197], v[52:55]
	v_mfma_f32_16x16x32_bf16 v[52:55], v[132:135], v[198:201], v[52:55]
	v_mfma_f32_16x16x32_bf16 v[36:39], v[128:131], v[202:205], v[36:39]
	v_mfma_f32_16x16x32_bf16 v[36:39], v[132:135], v[206:209], v[36:39]
	v_mfma_f32_16x16x32_bf16 v[20:23], v[128:131], v[210:213], v[20:23]
	v_mfma_f32_16x16x32_bf16 v[20:23], v[132:135], v[214:217], v[20:23]
	v_mfma_f32_16x16x32_bf16 v[56:59], v[136:139], v[160:163], v[56:59]
	v_mfma_f32_16x16x32_bf16 v[56:59], v[140:143], v[164:167], v[56:59]
	v_mfma_f32_16x16x32_bf16 v[44:47], v[136:139], v[194:197], v[44:47]
	v_mfma_f32_16x16x32_bf16 v[44:47], v[140:143], v[198:201], v[44:47]
	v_mfma_f32_16x16x32_bf16 v[28:31], v[136:139], v[202:205], v[28:31]
	v_mfma_f32_16x16x32_bf16 v[28:31], v[140:143], v[206:209], v[28:31]
	v_mfma_f32_16x16x32_bf16 v[12:15], v[136:139], v[210:213], v[12:15]
	v_mfma_f32_16x16x32_bf16 v[12:15], v[140:143], v[214:217], v[12:15]
	v_mfma_f32_16x16x32_bf16 v[48:51], v[144:147], v[160:163], v[48:51]
	v_mfma_f32_16x16x32_bf16 v[48:51], v[148:151], v[164:167], v[48:51]
	v_mfma_f32_16x16x32_bf16 v[32:35], v[144:147], v[194:197], v[32:35]
	v_mfma_f32_16x16x32_bf16 v[32:35], v[148:151], v[198:201], v[32:35]
	v_mfma_f32_16x16x32_bf16 v[16:19], v[144:147], v[202:205], v[16:19]
	v_mfma_f32_16x16x32_bf16 v[16:19], v[148:151], v[206:209], v[16:19]
	v_mfma_f32_16x16x32_bf16 v[4:7], v[144:147], v[210:213], v[4:7]
	v_mfma_f32_16x16x32_bf16 v[4:7], v[148:151], v[214:217], v[4:7]
	v_mfma_f32_16x16x32_bf16 v[40:43], v[152:155], v[160:163], v[40:43]
	v_mfma_f32_16x16x32_bf16 v[40:43], v[156:159], v[164:167], v[40:43]
	v_mfma_f32_16x16x32_bf16 v[24:27], v[152:155], v[194:197], v[24:27]
	v_mfma_f32_16x16x32_bf16 v[24:27], v[156:159], v[198:201], v[24:27]
	v_mfma_f32_16x16x32_bf16 v[8:11], v[152:155], v[202:205], v[8:11]
	v_mfma_f32_16x16x32_bf16 v[8:11], v[156:159], v[206:209], v[8:11]
	v_mfma_f32_16x16x32_bf16 v[0:3], v[152:155], v[210:213], v[0:3]
	v_mfma_f32_16x16x32_bf16 v[0:3], v[156:159], v[214:217], v[0:3]
	s_barrier
	s_setprio 0
	s_add_i32 s3, s3, 2
	s_add_u32 s2, s2, 0xffffff00
	s_addc_u32 s30, s30, -1
	s_cmpk_gt_u32 s3, 0x55
	s_mov_b64 s[76:77], s[78:79]

; #define PG8_STAGE(bufoff, gbase, voff) do { _Pragma("unroll") for (int _i = 0; _i < 2; ++_i) \
;         __builtin_amdgcn_global_load_lds((const unsigned*)((const char*)(gbase) + (voff)[_i]), (PG8_LAS unsigned*)(lds + (bufoff) + ldsw + _i * 8192), 16, 0, 0); } while (0)
; #define PG8_LDA(dst, b, h) do { _Pragma("unroll") for (int m = 0; m < 4; ++m) _Pragma("unroll") for (int k = 0; k < 2; ++k) dst[m][k] = *(const PG8_LAS bf16x8*)(lds + PG8_SA(b, h) + aoff + m * 2048 + k * 1024); } while (0)
; #define PG8_LDB(dst, b, h) do { _Pragma("unroll") for (int n = 0; n < 2; ++n) _Pragma("unroll") for (int k = 0; k < 2; ++k) dst[n][k] = *(const PG8_LAS bf16x8*)(lds + PG8_SB(b, h) + boff + n * 2048 + k * 1024); } while (0)
; #define PG8_MMA(ai, bj, At, Bt) do { __builtin_amdgcn_s_setprio(1); _Pragma("unroll") for (int m = 0; m < 4; ++m) _Pragma("unroll") for (int n = 0; n < 2; ++n) _Pragma("unroll") for (int k = 0; k < 2; ++k) \
;         acc[ai][bj][m][n] = __builtin_amdgcn_mfma_f32_16x16x32_bf16(Bt[n][k], At[m][k], acc[ai][bj][m][n], 0, 0, 0); __builtin_amdgcn_s_setprio(0); } while (0)
; #define PG8_WAIT_V(n) asm volatile("s_waitcnt vmcnt(" #n ")" ::: "memory")
; #define PG8_WAIT_L(n) asm volatile("s_waitcnt lgkmcnt(" #n ")" ::: "memory")
;     ...
;         const char* nA = has_next ? (const char*)g.A + (size_t)nxt.pm * tstep : cA; const char* nB = has_next ? (const char*)g.Bt + (size_t)nxt.pn * tstep : cB;
;         for (int t = 0; t < nt; t += 2) {
;             if constexpr (Epi::MIDK) { if (t == nt / 2) E.midk(acc, cur, wr, wc, fr, fq); }
;             const bool last = (t == nt - 2);
;             const char* a1 = PG8_KADV(cA, (size_t)(t + 1) * kstep);
;             const char* a2 = last ? nA : PG8_KADV(cA, (size_t)(t + 2) * kstep); const char* b2 = last ? nB : PG8_KADV(cB, (size_t)(t + 2) * kstep);
;             const char* a3 = PG8_KADV(a2, kstep); const char* b3 = PG8_KADV(b2, kstep);
;             if (last && has_next) S.a_ready(nxt);
;             if constexpr (SP2) {
;             PG8_LDB(B0, 0, 0); PG8_LDB(B1, 0, 1); PG8_SCHED; PG8_LDA(At, 0, 0); PG8_STAGE(PG8_SA(1, 1), a1 + hstep, voffA);
;             PG8_WAIT_V(8); PG8_WAIT_L(0); PG8_BAR; PG8_MMA(0, 0, At, B0); PG8_MMA(0, 1, At, B1); PG8_BAR; PG8_SCHED;
;             PG8_LDA(At, 0, 1); PG8_STAGE(PG8_SB(0, 0), b2, voffB); PG8_STAGE(PG8_SB(0, 1), b2 + hstep, voffB); PG8_STAGE(PG8_SA(0, 0), a2, voffA);
.LBB0_489:
	s_ashr_i32 s81, s80, 31
	s_lshl_b64 s[2:3], s[80:81], 20
	s_add_u32 s82, s0, s2
	s_addc_u32 s83, s1, s3
	s_and_b64 s[2:3], s[4:5], exec
	s_cselect_b32 s23, s83, s87
	s_cselect_b32 s25, s82, s86
	s_ashr_i32 s79, s78, 31
	s_lshl_b64 s[2:3], s[78:79], 20
	s_add_u32 s84, s70, s2
	s_addc_u32 s85, s71, s3
	s_and_b64 s[2:3], s[4:5], exec
	s_cselect_b32 s28, s85, s89
	s_cselect_b32 s30, s84, s88
	s_add_u32 s86, s86, 0x80080
	s_addc_u32 s87, s87, 0
	s_add_u32 s33, s88, 0x100
	s_addc_u32 s40, s89, 0
	s_mov_b32 s2, -2
	s_add_u32 s3, s86, 0xfff80080
	s_addc_u32 s12, s87, -1
	s_add_i32 s13, 0, 0x10000
	s_cmp_eq_u32 s2, 28
	s_cselect_b32 s91, s23, s12
	s_cselect_b32 s90, s25, s3
	s_cselect_b32 s89, s28, s40
	s_cselect_b32 s88, s30, s33
	s_add_i32 s3, 0, 0x14000
	v_add_u32_e32 v156, s13, v141
	v_add_u32_e32 v168, s3, v141
	ds_read_b128 v[144:147], v156
	ds_read_b128 v[148:151], v156 offset:1024
	ds_read_b128 v[152:155], v156 offset:2048
	ds_read_b128 v[156:159], v156 offset:3072
	ds_read_b128 v[160:163], v168
	ds_read_b128 v[164:167], v168 offset:1024
	ds_read_b128 v[170:173], v168 offset:2048
	ds_read_b128 v[178:181], v168 offset:3072
	s_add_i32 m0, s9, 0xc000
	ds_read_b128 v[182:185], v143
	ds_read_b128 v[186:189], v143 offset:1024
	ds_read_b128 v[190:193], v143 offset:2048
	ds_read_b128 v[194:197], v143 offset:3072
	ds_read_b128 v[198:201], v143 offset:4096
	ds_read_b128 v[202:205], v143 offset:5120
	ds_read_b128 v[206:209], v143 offset:6144
	ds_read_b128 v[210:213], v143 offset:7168
	global_load_lds_dwordx4 v136, s[86:87]
	s_add_i32 m0, s9, 0xe000
	s_nop 0
	global_load_lds_dwordx4 v138, s[86:87]
	s_waitcnt vmcnt(8)
	s_waitcnt lgkmcnt(0)
	s_setprio 1
	s_barrier
	v_mfma_f32_16x16x32_bf16 v[124:127], v[144:147], v[182:185], 0
	v_mfma_f32_16x16x32_bf16 v[124:127], v[148:151], v[186:189], v[124:127]
	v_mfma_f32_16x16x32_bf16 v[116:119], v[144:147], v[190:193], 0
	v_mfma_f32_16x16x32_bf16 v[116:119], v[148:151], v[194:197], v[116:119]
	v_mfma_f32_16x16x32_bf16 v[100:103], v[144:147], v[198:201], 0
	v_mfma_f32_16x16x32_bf16 v[100:103], v[148:151], v[202:205], v[100:103]
	v_mfma_f32_16x16x32_bf16 v[84:87], v[144:147], v[206:209], 0
	v_mfma_f32_16x16x32_bf16 v[84:87], v[148:151], v[210:213], v[84:87]
	v_mfma_f32_16x16x32_bf16 v[120:123], v[152:155], v[182:185], 0
	v_mfma_f32_16x16x32_bf16 v[120:123], v[156:159], v[186:189], v[120:123]
	v_mfma_f32_16x16x32_bf16 v[112:115], v[152:155], v[190:193], 0
	v_mfma_f32_16x16x32_bf16 v[112:115], v[156:159], v[194:197], v[112:115]
	v_mfma_f32_16x16x32_bf16 v[96:99], v[152:155], v[198:201], 0
	v_mfma_f32_16x16x32_bf16 v[96:99], v[156:159], v[202:205], v[96:99]
	v_mfma_f32_16x16x32_bf16 v[80:83], v[152:155], v[206:209], 0
	v_mfma_f32_16x16x32_bf16 v[80:83], v[156:159], v[210:213], v[80:83]
	v_mfma_f32_16x16x32_bf16 v[108:111], v[160:163], v[182:185], 0
	v_mfma_f32_16x16x32_bf16 v[108:111], v[164:167], v[186:189], v[108:111]
	v_mfma_f32_16x16x32_bf16 v[92:95], v[160:163], v[190:193], 0
	v_mfma_f32_16x16x32_bf16 v[92:95], v[164:167], v[194:197], v[92:95]
	v_mfma_f32_16x16x32_bf16 v[76:79], v[160:163], v[198:201], 0
	v_mfma_f32_16x16x32_bf16 v[76:79], v[164:167], v[202:205], v[76:79]
	v_mfma_f32_16x16x32_bf16 v[68:71], v[160:163], v[206:209], 0
	v_mfma_f32_16x16x32_bf16 v[68:71], v[164:167], v[210:213], v[68:71]
	v_mfma_f32_16x16x32_bf16 v[104:107], v[170:173], v[182:185], 0
	v_mfma_f32_16x16x32_bf16 v[104:107], v[178:181], v[186:189], v[104:107]
	v_mfma_f32_16x16x32_bf16 v[88:91], v[170:173], v[190:193], 0
	v_mfma_f32_16x16x32_bf16 v[88:91], v[178:181], v[194:197], v[88:91]
	v_mfma_f32_16x16x32_bf16 v[72:75], v[170:173], v[198:201], 0
	v_mfma_f32_16x16x32_bf16 v[72:75], v[178:181], v[202:205], v[72:75]
	v_mfma_f32_16x16x32_bf16 v[64:67], v[170:173], v[206:209], 0
	v_mfma_f32_16x16x32_bf16 v[64:67], v[178:181], v[210:213], v[64:67]
	s_barrier
	s_setprio 0
	s_add_i32 s12, s13, s8
	s_mov_b32 m0, s12
	ds_read_b128 v[182:185], v143 offset:16384
	ds_read_b128 v[186:189], v143 offset:17408
	ds_read_b128 v[190:193], v143 offset:18432
	ds_read_b128 v[194:197], v143 offset:19456
	ds_read_b128 v[198:201], v143 offset:20480
	ds_read_b128 v[202:205], v143 offset:21504
	ds_read_b128 v[206:209], v143 offset:22528
	ds_read_b128 v[210:213], v143 offset:23552
	global_load_lds_dwordx4 v130, s[88:89]
	s_add_i32 m0, s12, 0x2000
	s_add_u32 s42, s88, 0x80000
	s_addc_u32 s43, s89, 0
	s_add_i32 s3, s3, s8
	global_load_lds_dwordx4 v134, s[88:89]
	s_mov_b32 m0, s3
	s_nop 0
	global_load_lds_dwordx4 v130, s[42:43]
	s_add_i32 m0, s3, 0x2000
	s_nop 0
	global_load_lds_dwordx4 v134, s[42:43]
	s_mov_b32 m0, s9
	s_nop 0
	global_load_lds_dwordx4 v128, s[90:91]
	s_mov_b32 m0, s10
	s_nop 0
	global_load_lds_dwordx4 v132, s[90:91]
	s_waitcnt vmcnt(8)
	s_waitcnt lgkmcnt(0)
	s_setprio 1
	s_barrier
; #define PG8_STAGE(bufoff, gbase, voff) do { _Pragma("unroll") for (int _i = 0; _i < 2; ++_i) \
;         __builtin_amdgcn_global_load_lds((const unsigned*)((const char*)(gbase) + (voff)[_i]), (PG8_LAS unsigned*)(lds + (bufoff) + ldsw + _i * 8192), 16, 0, 0); } while (0)
; #define PG8_LDA(dst, b, h) do { _Pragma("unroll") for (int m = 0; m < 4; ++m) _Pragma("unroll") for (int k = 0; k < 2; ++k) dst[m][k] = *(const PG8_LAS bf16x8*)(lds + PG8_SA(b, h) + aoff + m * 2048 + k * 1024); } while (0)
; #define PG8_LDB(dst, b, h) do { _Pragma("unroll") for (int n = 0; n < 2; ++n) _Pragma("unroll") for (int k = 0; k < 2; ++k) dst[n][k] = *(const PG8_LAS bf16x8*)(lds + PG8_SB(b, h) + boff + n * 2048 + k * 1024); } while (0)
; #define PG8_MMA(ai, bj, At, Bt) do { __builtin_amdgcn_s_setprio(1); _Pragma("unroll") for (int m = 0; m < 4; ++m) _Pragma("unroll") for (int n = 0; n < 2; ++n) _Pragma("unroll") for (int k = 0; k < 2; ++k) \
;         acc[ai][bj][m][n] = __builtin_amdgcn_mfma_f32_16x16x32_bf16(Bt[n][k], At[m][k], acc[ai][bj][m][n], 0, 0, 0); __builtin_amdgcn_s_setprio(0); } while (0)
; #define PG8_WAIT_V(n) asm volatile("s_waitcnt vmcnt(" #n ")" ::: "memory")
; #define PG8_WAIT_L(n) asm volatile("s_waitcnt lgkmcnt(" #n ")" ::: "memory")
; #define PG8_BAR __builtin_amdgcn_s_barrier()
; #define PG8_SCHED __builtin_amdgcn_sched_barrier(0)
;     ...
;             PG8_WAIT_V(8); PG8_WAIT_L(0); PG8_BAR; PG8_MMA(1, 0, At, B0); PG8_MMA(1, 1, At, B1); PG8_BAR; PG8_SCHED;
;             PG8_LDB(B0, 1, 0); PG8_LDB(B1, 1, 1); PG8_SCHED; PG8_LDA(At, 1, 0); PG8_STAGE(PG8_SA(0, 1), a2 + hstep, voffA);
;             PG8_WAIT_V(8); PG8_WAIT_L(0); PG8_BAR; PG8_MMA(0, 0, At, B0); PG8_MMA(0, 1, At, B1); PG8_BAR; PG8_SCHED;
	v_mfma_f32_16x16x32_bf16 v[60:63], v[144:147], v[182:185], 0
	v_mfma_f32_16x16x32_bf16 v[60:63], v[148:151], v[186:189], v[60:63]
	v_mfma_f32_16x16x32_bf16 v[52:55], v[144:147], v[190:193], 0
	v_mfma_f32_16x16x32_bf16 v[52:55], v[148:151], v[194:197], v[52:55]
	v_mfma_f32_16x16x32_bf16 v[36:39], v[144:147], v[198:201], 0
	v_mfma_f32_16x16x32_bf16 v[36:39], v[148:151], v[202:205], v[36:39]
	v_mfma_f32_16x16x32_bf16 v[20:23], v[144:147], v[206:209], 0
	v_mfma_f32_16x16x32_bf16 v[20:23], v[148:151], v[210:213], v[20:23]
	v_mfma_f32_16x16x32_bf16 v[56:59], v[152:155], v[182:185], 0
	v_mfma_f32_16x16x32_bf16 v[56:59], v[156:159], v[186:189], v[56:59]
	v_mfma_f32_16x16x32_bf16 v[48:51], v[152:155], v[190:193], 0
	v_mfma_f32_16x16x32_bf16 v[48:51], v[156:159], v[194:197], v[48:51]
	v_mfma_f32_16x16x32_bf16 v[32:35], v[152:155], v[198:201], 0
	v_mfma_f32_16x16x32_bf16 v[32:35], v[156:159], v[202:205], v[32:35]
	v_mfma_f32_16x16x32_bf16 v[16:19], v[152:155], v[206:209], 0
	v_mfma_f32_16x16x32_bf16 v[16:19], v[156:159], v[210:213], v[16:19]
	v_mfma_f32_16x16x32_bf16 v[44:47], v[160:163], v[182:185], 0
	v_mfma_f32_16x16x32_bf16 v[44:47], v[164:167], v[186:189], v[44:47]
	v_mfma_f32_16x16x32_bf16 v[28:31], v[160:163], v[190:193], 0
	v_mfma_f32_16x16x32_bf16 v[28:31], v[164:167], v[194:197], v[28:31]
	v_mfma_f32_16x16x32_bf16 v[12:15], v[160:163], v[198:201], 0
	v_mfma_f32_16x16x32_bf16 v[12:15], v[164:167], v[202:205], v[12:15]
	v_mfma_f32_16x16x32_bf16 v[4:7], v[160:163], v[206:209], 0
	v_mfma_f32_16x16x32_bf16 v[4:7], v[164:167], v[210:213], v[4:7]
	v_mfma_f32_16x16x32_bf16 v[40:43], v[170:173], v[182:185], 0
	v_mfma_f32_16x16x32_bf16 v[40:43], v[178:181], v[186:189], v[40:43]
	v_mfma_f32_16x16x32_bf16 v[24:27], v[170:173], v[190:193], 0
	v_mfma_f32_16x16x32_bf16 v[24:27], v[178:181], v[194:197], v[24:27]
	v_mfma_f32_16x16x32_bf16 v[8:11], v[170:173], v[198:201], 0
	v_mfma_f32_16x16x32_bf16 v[8:11], v[178:181], v[202:205], v[8:11]
	v_mfma_f32_16x16x32_bf16 v[0:3], v[170:173], v[206:209], 0
	v_mfma_f32_16x16x32_bf16 v[0:3], v[178:181], v[210:213], v[0:3]
	s_barrier
	s_setprio 0
	s_add_i32 s3, 0, 0x18000
	s_add_i32 s12, 0, 0x1c000
	v_add_u32_e32 v156, s3, v141
	v_add_u32_e32 v168, s12, v141
	ds_read_b128 v[144:147], v156
	ds_read_b128 v[148:151], v156 offset:1024
	ds_read_b128 v[152:155], v156 offset:2048
	ds_read_b128 v[156:159], v156 offset:3072
	ds_read_b128 v[160:163], v168
	ds_read_b128 v[164:167], v168 offset:1024
	ds_read_b128 v[170:173], v168 offset:2048
	ds_read_b128 v[178:181], v168 offset:3072
	s_add_u32 s42, s90, 0x80000
	s_addc_u32 s43, s91, 0
	s_mov_b32 m0, s18
	ds_read_b128 v[182:185], v143 offset:32768
	ds_read_b128 v[186:189], v143 offset:33792
	ds_read_b128 v[190:193], v143 offset:34816
	ds_read_b128 v[194:197], v143 offset:35840
	ds_read_b128 v[198:201], v143 offset:36864
	ds_read_b128 v[202:205], v143 offset:37888
	ds_read_b128 v[206:209], v143 offset:38912
	ds_read_b128 v[210:213], v143 offset:39936
	global_load_lds_dwordx4 v128, s[42:43]
	s_mov_b32 m0, s19
	s_nop 0
	global_load_lds_dwordx4 v132, s[42:43]
	s_waitcnt vmcnt(8)
	s_waitcnt lgkmcnt(0)
	s_setprio 1
	s_barrier
	v_mfma_f32_16x16x32_bf16 v[124:127], v[144:147], v[182:185], v[124:127]
	v_mfma_f32_16x16x32_bf16 v[124:127], v[148:151], v[186:189], v[124:127]
	v_mfma_f32_16x16x32_bf16 v[116:119], v[144:147], v[190:193], v[116:119]
	v_mfma_f32_16x16x32_bf16 v[116:119], v[148:151], v[194:197], v[116:119]
	v_mfma_f32_16x16x32_bf16 v[100:103], v[144:147], v[198:201], v[100:103]
	v_mfma_f32_16x16x32_bf16 v[100:103], v[148:151], v[202:205], v[100:103]
	v_mfma_f32_16x16x32_bf16 v[84:87], v[144:147], v[206:209], v[84:87]
	v_mfma_f32_16x16x32_bf16 v[84:87], v[148:151], v[210:213], v[84:87]
	v_mfma_f32_16x16x32_bf16 v[120:123], v[152:155], v[182:185], v[120:123]
	v_mfma_f32_16x16x32_bf16 v[120:123], v[156:159], v[186:189], v[120:123]
	v_mfma_f32_16x16x32_bf16 v[112:115], v[152:155], v[190:193], v[112:115]
	v_mfma_f32_16x16x32_bf16 v[112:115], v[156:159], v[194:197], v[112:115]
	v_mfma_f32_16x16x32_bf16 v[96:99], v[152:155], v[198:201], v[96:99]
	v_mfma_f32_16x16x32_bf16 v[96:99], v[156:159], v[202:205], v[96:99]
	v_mfma_f32_16x16x32_bf16 v[80:83], v[152:155], v[206:209], v[80:83]
	v_mfma_f32_16x16x32_bf16 v[80:83], v[156:159], v[210:213], v[80:83]
	v_mfma_f32_16x16x32_bf16 v[108:111], v[160:163], v[182:185], v[108:111]
	v_mfma_f32_16x16x32_bf16 v[108:111], v[164:167], v[186:189], v[108:111]
	v_mfma_f32_16x16x32_bf16 v[92:95], v[160:163], v[190:193], v[92:95]
	v_mfma_f32_16x16x32_bf16 v[92:95], v[164:167], v[194:197], v[92:95]
	v_mfma_f32_16x16x32_bf16 v[76:79], v[160:163], v[198:201], v[76:79]
	v_mfma_f32_16x16x32_bf16 v[76:79], v[164:167], v[202:205], v[76:79]
	v_mfma_f32_16x16x32_bf16 v[68:71], v[160:163], v[206:209], v[68:71]
	v_mfma_f32_16x16x32_bf16 v[68:71], v[164:167], v[210:213], v[68:71]
	v_mfma_f32_16x16x32_bf16 v[104:107], v[170:173], v[182:185], v[104:107]
	v_mfma_f32_16x16x32_bf16 v[104:107], v[178:181], v[186:189], v[104:107]
	v_mfma_f32_16x16x32_bf16 v[88:91], v[170:173], v[190:193], v[88:91]
	v_mfma_f32_16x16x32_bf16 v[88:91], v[178:181], v[194:197], v[88:91]
	v_mfma_f32_16x16x32_bf16 v[72:75], v[170:173], v[198:201], v[72:75]
	v_mfma_f32_16x16x32_bf16 v[72:75], v[178:181], v[202:205], v[72:75]
	v_mfma_f32_16x16x32_bf16 v[64:67], v[170:173], v[206:209], v[64:67]
	v_mfma_f32_16x16x32_bf16 v[64:67], v[178:181], v[210:213], v[64:67]
	s_barrier
; #define PG8_STAGE(bufoff, gbase, voff) do { _Pragma("unroll") for (int _i = 0; _i < 2; ++_i) \
;         __builtin_amdgcn_global_load_lds((const unsigned*)((const char*)(gbase) + (voff)[_i]), (PG8_LAS unsigned*)(lds + (bufoff) + ldsw + _i * 8192), 16, 0, 0); } while (0)
; #define PG8_LDA(dst, b, h) do { _Pragma("unroll") for (int m = 0; m < 4; ++m) _Pragma("unroll") for (int k = 0; k < 2; ++k) dst[m][k] = *(const PG8_LAS bf16x8*)(lds + PG8_SA(b, h) + aoff + m * 2048 + k * 1024); } while (0)
; #define PG8_MMA(ai, bj, At, Bt) do { __builtin_amdgcn_s_setprio(1); _Pragma("unroll") for (int m = 0; m < 4; ++m) _Pragma("unroll") for (int n = 0; n < 2; ++n) _Pragma("unroll") for (int k = 0; k < 2; ++k) \
;         acc[ai][bj][m][n] = __builtin_amdgcn_mfma_f32_16x16x32_bf16(Bt[n][k], At[m][k], acc[ai][bj][m][n], 0, 0, 0); __builtin_amdgcn_s_setprio(0); } while (0)
; #define PG8_WAIT_V(n) asm volatile("s_waitcnt vmcnt(" #n ")" ::: "memory")
; #define PG8_WAIT_L(n) asm volatile("s_waitcnt lgkmcnt(" #n ")" ::: "memory")
; #define PG8_BAR __builtin_amdgcn_s_barrier()
; #define PG8_SCHED __builtin_amdgcn_sched_barrier(0)
;     ...
;             PG8_WAIT_V(8); PG8_WAIT_L(0); PG8_BAR; PG8_MMA(0, 0, At, B0); PG8_MMA(0, 1, At, B1); PG8_BAR; PG8_SCHED;
;             PG8_LDA(At, 1, 1); PG8_STAGE(PG8_SB(1, 0), b3, voffB); PG8_STAGE(PG8_SB(1, 1), b3 + hstep, voffB); PG8_STAGE(PG8_SA(1, 0), a3, voffA);
;             PG8_WAIT_V(8); PG8_WAIT_L(0); PG8_BAR; PG8_MMA(1, 0, At, B0); PG8_MMA(1, 1, At, B1); PG8_BAR; PG8_SCHED;
	s_setprio 0
	s_add_i32 s3, s3, s8
	s_mov_b32 m0, s3
	ds_read_b128 v[182:185], v143 offset:49152
	ds_read_b128 v[186:189], v143 offset:50176
	ds_read_b128 v[190:193], v143 offset:51200
	ds_read_b128 v[194:197], v143 offset:52224
	ds_read_b128 v[198:201], v143 offset:53248
	ds_read_b128 v[202:205], v143 offset:54272
	ds_read_b128 v[206:209], v143 offset:55296
	ds_read_b128 v[210:213], v143 offset:56320
	s_add_u32 s100, s88, s16
	s_addc_u32 s101, s89, s17
	global_load_lds_dwordx4 v130, s[100:101]
	s_add_i32 m0, s3, 0x2000
	s_add_u32 s42, s88, 0x80080
	s_addc_u32 s43, s89, 0
	s_add_i32 s3, s12, s8
	global_load_lds_dwordx4 v134, s[100:101]
	s_mov_b32 m0, s3
	s_nop 0
	global_load_lds_dwordx4 v130, s[42:43]
	s_add_i32 m0, s3, 0x2000
	s_nop 0
	global_load_lds_dwordx4 v134, s[42:43]
	s_mov_b32 m0, s20
	s_nop 0
	s_add_u32 s100, s90, s16
	s_addc_u32 s101, s91, s17
	global_load_lds_dwordx4 v128, s[100:101]
	s_mov_b32 m0, s21
	s_nop 0
	global_load_lds_dwordx4 v132, s[100:101]
	s_waitcnt vmcnt(8)
	s_waitcnt lgkmcnt(0)
	s_setprio 1
	s_barrier
	v_mfma_f32_16x16x32_bf16 v[60:63], v[144:147], v[182:185], v[60:63]
	v_mfma_f32_16x16x32_bf16 v[60:63], v[148:151], v[186:189], v[60:63]
	v_mfma_f32_16x16x32_bf16 v[52:55], v[144:147], v[190:193], v[52:55]
	v_mfma_f32_16x16x32_bf16 v[52:55], v[148:151], v[194:197], v[52:55]
	v_mfma_f32_16x16x32_bf16 v[36:39], v[144:147], v[198:201], v[36:39]
	v_mfma_f32_16x16x32_bf16 v[36:39], v[148:151], v[202:205], v[36:39]
	v_mfma_f32_16x16x32_bf16 v[20:23], v[144:147], v[206:209], v[20:23]
	v_mfma_f32_16x16x32_bf16 v[20:23], v[148:151], v[210:213], v[20:23]
	v_mfma_f32_16x16x32_bf16 v[56:59], v[152:155], v[182:185], v[56:59]
	v_mfma_f32_16x16x32_bf16 v[56:59], v[156:159], v[186:189], v[56:59]
	v_mfma_f32_16x16x32_bf16 v[48:51], v[152:155], v[190:193], v[48:51]
	v_mfma_f32_16x16x32_bf16 v[48:51], v[156:159], v[194:197], v[48:51]
	v_mfma_f32_16x16x32_bf16 v[32:35], v[152:155], v[198:201], v[32:35]
	v_mfma_f32_16x16x32_bf16 v[32:35], v[156:159], v[202:205], v[32:35]
	v_mfma_f32_16x16x32_bf16 v[16:19], v[152:155], v[206:209], v[16:19]
	v_mfma_f32_16x16x32_bf16 v[16:19], v[156:159], v[210:213], v[16:19]
	v_mfma_f32_16x16x32_bf16 v[44:47], v[160:163], v[182:185], v[44:47]
	v_mfma_f32_16x16x32_bf16 v[44:47], v[164:167], v[186:189], v[44:47]
	v_mfma_f32_16x16x32_bf16 v[28:31], v[160:163], v[190:193], v[28:31]
	v_mfma_f32_16x16x32_bf16 v[28:31], v[164:167], v[194:197], v[28:31]
	v_mfma_f32_16x16x32_bf16 v[12:15], v[160:163], v[198:201], v[12:15]
	v_mfma_f32_16x16x32_bf16 v[12:15], v[164:167], v[202:205], v[12:15]
	v_mfma_f32_16x16x32_bf16 v[4:7], v[160:163], v[206:209], v[4:7]
	v_mfma_f32_16x16x32_bf16 v[4:7], v[164:167], v[210:213], v[4:7]
	v_mfma_f32_16x16x32_bf16 v[40:43], v[170:173], v[182:185], v[40:43]
	v_mfma_f32_16x16x32_bf16 v[40:43], v[178:181], v[186:189], v[40:43]
	v_mfma_f32_16x16x32_bf16 v[24:27], v[170:173], v[190:193], v[24:27]
	v_mfma_f32_16x16x32_bf16 v[24:27], v[178:181], v[194:197], v[24:27]
	v_mfma_f32_16x16x32_bf16 v[8:11], v[170:173], v[198:201], v[8:11]
	v_mfma_f32_16x16x32_bf16 v[8:11], v[178:181], v[202:205], v[8:11]
	v_mfma_f32_16x16x32_bf16 v[0:3], v[170:173], v[206:209], v[0:3]
	v_mfma_f32_16x16x32_bf16 v[0:3], v[178:181], v[210:213], v[0:3]
	s_barrier
	s_setprio 0
	s_add_i32 s2, s2, 2
	s_add_u32 s86, s86, 0x100
	s_addc_u32 s87, s87, 0
	s_add_u32 s33, s33, 0x100
	s_addc_u32 s40, s40, 0
	s_cmp_gt_u32 s2, 29

; #define PG8_STAGE(bufoff, gbase, voff) do { _Pragma("unroll") for (int _i = 0; _i < 2; ++_i) \
;         __builtin_amdgcn_global_load_lds((const unsigned*)((const char*)(gbase) + (voff)[_i]), (PG8_LAS unsigned*)(lds + (bufoff) + ldsw + _i * 8192), 16, 0, 0); } while (0)
; #define PG8_LDA(dst, b, h) do { _Pragma("unroll") for (int m = 0; m < 4; ++m) _Pragma("unroll") for (int k = 0; k < 2; ++k) dst[m][k] = *(const PG8_LAS bf16x8*)(lds + PG8_SA(b, h) + aoff + m * 2048 + k * 1024); } while (0)
; #define PG8_LDB(dst, b, h) do { _Pragma("unroll") for (int n = 0; n < 2; ++n) _Pragma("unroll") for (int k = 0; k < 2; ++k) dst[n][k] = *(const PG8_LAS bf16x8*)(lds + PG8_SB(b, h) + boff + n * 2048 + k * 1024); } while (0)
; #define PG8_MMA(ai, bj, At, Bt) do { __builtin_amdgcn_s_setprio(1); _Pragma("unroll") for (int m = 0; m < 4; ++m) _Pragma("unroll") for (int n = 0; n < 2; ++n) _Pragma("unroll") for (int k = 0; k < 2; ++k) \
;         acc[ai][bj][m][n] = __builtin_amdgcn_mfma_f32_16x16x32_bf16(Bt[n][k], At[m][k], acc[ai][bj][m][n], 0, 0, 0); __builtin_amdgcn_s_setprio(0); } while (0)
; #define PG8_WAIT_V(n) asm volatile("s_waitcnt vmcnt(" #n ")" ::: "memory")
; #define PG8_WAIT_L(n) asm volatile("s_waitcnt lgkmcnt(" #n ")" ::: "memory")
;     ...
;         const char* nA = has_next ? (const char*)g.A + (size_t)nxt.pm * tstep : cA; const char* nB = has_next ? (const char*)g.Bt + (size_t)nxt.pn * tstep : cB;
;         for (int t = 0; t < nt; t += 2) {
;             if constexpr (Epi::MIDK) { if (t == nt / 2) E.midk(acc, cur, wr, wc, fr, fq); }
;             const bool last = (t == nt - 2);
;             const char* a1 = PG8_KADV(cA, (size_t)(t + 1) * kstep);
;             const char* a2 = last ? nA : PG8_KADV(cA, (size_t)(t + 2) * kstep); const char* b2 = last ? nB : PG8_KADV(cB, (size_t)(t + 2) * kstep);
;             const char* a3 = PG8_KADV(a2, kstep); const char* b3 = PG8_KADV(b2, kstep);
;             if (last && has_next) S.a_ready(nxt);
;             if constexpr (SP2) {
;             PG8_LDB(B0, 0, 0); PG8_LDB(B1, 0, 1); PG8_SCHED; PG8_LDA(At, 0, 0); PG8_STAGE(PG8_SA(1, 1), a1 + hstep, voffA);
;             PG8_WAIT_V(8); PG8_WAIT_L(0); PG8_BAR; PG8_MMA(0, 0, At, B0); PG8_MMA(0, 1, At, B1); PG8_BAR; PG8_SCHED;
;             PG8_LDA(At, 0, 1); PG8_STAGE(PG8_SB(0, 0), b2, voffB); PG8_STAGE(PG8_SB(0, 1), b2 + hstep, voffB); PG8_STAGE(PG8_SA(0, 0), a2, voffA);
.LBB0_513:
	s_ashr_i32 s81, s80, 31
	s_lshl_b64 s[2:3], s[80:81], 20
	s_add_u32 s82, s8, s2
	s_addc_u32 s83, s9, s3
	s_and_b64 s[2:3], s[4:5], exec
	s_cselect_b32 s28, s83, s87
	s_cselect_b32 s30, s82, s86
	s_ashr_i32 s79, s78, 31
	s_lshl_b64 s[2:3], s[78:79], 20
	s_add_u32 s84, s68, s2
	s_addc_u32 s85, s69, s3
	s_and_b64 s[2:3], s[4:5], exec
	s_cselect_b32 s33, s85, s89
	s_cselect_b32 s40, s84, s88
	s_add_u32 s86, s86, 0x80080
	s_addc_u32 s87, s87, 0
	s_add_u32 s42, s88, 0x100
	s_addc_u32 s43, s89, 0
	s_mov_b32 s2, -2
	s_add_u32 s3, s86, 0xfff80080
	s_addc_u32 s12, s87, -1
	s_add_i32 s13, 0, 0x10000
	s_cmp_eq_u32 s2, 28
	s_cselect_b32 s91, s28, s12
	s_cselect_b32 s90, s30, s3
	s_cselect_b32 s89, s33, s43
	s_cselect_b32 s88, s40, s42
	s_add_i32 s3, 0, 0x14000
	v_add_u32_e32 v156, s13, v141
	v_add_u32_e32 v168, s3, v141
	ds_read_b128 v[144:147], v156
	ds_read_b128 v[148:151], v156 offset:1024
	ds_read_b128 v[152:155], v156 offset:2048
	ds_read_b128 v[156:159], v156 offset:3072
	ds_read_b128 v[160:163], v168
	ds_read_b128 v[164:167], v168 offset:1024
	ds_read_b128 v[170:173], v168 offset:2048
	ds_read_b128 v[178:181], v168 offset:3072
	s_add_i32 m0, s18, 0xc000
	ds_read_b128 v[182:185], v143
	ds_read_b128 v[186:189], v143 offset:1024
	ds_read_b128 v[190:193], v143 offset:2048
	ds_read_b128 v[194:197], v143 offset:3072
	ds_read_b128 v[198:201], v143 offset:4096
	ds_read_b128 v[202:205], v143 offset:5120
	ds_read_b128 v[206:209], v143 offset:6144
	ds_read_b128 v[210:213], v143 offset:7168
	global_load_lds_dwordx4 v136, s[86:87]
	s_add_i32 m0, s18, 0xe000
	s_nop 0
	global_load_lds_dwordx4 v138, s[86:87]
	s_waitcnt vmcnt(8)
	s_waitcnt lgkmcnt(0)
	s_setprio 1
	s_barrier
	v_mfma_f32_16x16x32_bf16 v[124:127], v[144:147], v[182:185], 0
	v_mfma_f32_16x16x32_bf16 v[124:127], v[148:151], v[186:189], v[124:127]
	v_mfma_f32_16x16x32_bf16 v[116:119], v[144:147], v[190:193], 0
	v_mfma_f32_16x16x32_bf16 v[116:119], v[148:151], v[194:197], v[116:119]
	v_mfma_f32_16x16x32_bf16 v[100:103], v[144:147], v[198:201], 0
	v_mfma_f32_16x16x32_bf16 v[100:103], v[148:151], v[202:205], v[100:103]
	v_mfma_f32_16x16x32_bf16 v[84:87], v[144:147], v[206:209], 0
	v_mfma_f32_16x16x32_bf16 v[84:87], v[148:151], v[210:213], v[84:87]
	v_mfma_f32_16x16x32_bf16 v[120:123], v[152:155], v[182:185], 0
	v_mfma_f32_16x16x32_bf16 v[120:123], v[156:159], v[186:189], v[120:123]
	v_mfma_f32_16x16x32_bf16 v[112:115], v[152:155], v[190:193], 0
	v_mfma_f32_16x16x32_bf16 v[112:115], v[156:159], v[194:197], v[112:115]
	v_mfma_f32_16x16x32_bf16 v[96:99], v[152:155], v[198:201], 0
	v_mfma_f32_16x16x32_bf16 v[96:99], v[156:159], v[202:205], v[96:99]
	v_mfma_f32_16x16x32_bf16 v[80:83], v[152:155], v[206:209], 0
	v_mfma_f32_16x16x32_bf16 v[80:83], v[156:159], v[210:213], v[80:83]
	v_mfma_f32_16x16x32_bf16 v[108:111], v[160:163], v[182:185], 0
	v_mfma_f32_16x16x32_bf16 v[108:111], v[164:167], v[186:189], v[108:111]
	v_mfma_f32_16x16x32_bf16 v[92:95], v[160:163], v[190:193], 0
	v_mfma_f32_16x16x32_bf16 v[92:95], v[164:167], v[194:197], v[92:95]
	v_mfma_f32_16x16x32_bf16 v[76:79], v[160:163], v[198:201], 0
	v_mfma_f32_16x16x32_bf16 v[76:79], v[164:167], v[202:205], v[76:79]
	v_mfma_f32_16x16x32_bf16 v[68:71], v[160:163], v[206:209], 0
	v_mfma_f32_16x16x32_bf16 v[68:71], v[164:167], v[210:213], v[68:71]
	v_mfma_f32_16x16x32_bf16 v[104:107], v[170:173], v[182:185], 0
	v_mfma_f32_16x16x32_bf16 v[104:107], v[178:181], v[186:189], v[104:107]
	v_mfma_f32_16x16x32_bf16 v[88:91], v[170:173], v[190:193], 0
	v_mfma_f32_16x16x32_bf16 v[88:91], v[178:181], v[194:197], v[88:91]
	v_mfma_f32_16x16x32_bf16 v[72:75], v[170:173], v[198:201], 0
	v_mfma_f32_16x16x32_bf16 v[72:75], v[178:181], v[202:205], v[72:75]
	v_mfma_f32_16x16x32_bf16 v[64:67], v[170:173], v[206:209], 0
	v_mfma_f32_16x16x32_bf16 v[64:67], v[178:181], v[210:213], v[64:67]
	s_barrier
	s_setprio 0
	s_add_i32 s12, s13, s10
	s_mov_b32 m0, s12
	ds_read_b128 v[182:185], v143 offset:16384
	ds_read_b128 v[186:189], v143 offset:17408
	ds_read_b128 v[190:193], v143 offset:18432
	ds_read_b128 v[194:197], v143 offset:19456
	ds_read_b128 v[198:201], v143 offset:20480
	ds_read_b128 v[202:205], v143 offset:21504
	ds_read_b128 v[206:209], v143 offset:22528
	ds_read_b128 v[210:213], v143 offset:23552
	global_load_lds_dwordx4 v130, s[88:89]
	s_add_i32 m0, s12, 0x2000
	s_add_u32 vcc_lo, s88, 0x80000
	v_lshl_add_u64 v[216:217], s[88:89], 0, v[134:135]
	s_addc_u32 vcc_hi, s89, 0
	s_add_i32 s3, s3, s10
	global_load_lds_dwordx4 v134, s[88:89]
	s_mov_b32 m0, s3
	v_lshl_add_u64 v[220:221], s[90:91], 0, v[132:133]
	global_load_lds_dwordx4 v130, vcc
	s_add_i32 m0, s3, 0x2000
	s_nop 0
	global_load_lds_dwordx4 v134, vcc
	v_lshl_add_u64 v[218:219], s[90:91], 0, v[128:129]
	s_mov_b32 m0, s18
	s_nop 0
	global_load_lds_dwordx4 v128, s[90:91]
	s_mov_b32 m0, s19
	s_nop 0
	global_load_lds_dwordx4 v132, s[90:91]
	s_waitcnt vmcnt(8)
	s_waitcnt lgkmcnt(0)
	s_setprio 1
	s_barrier
; #define PG8_STAGE(bufoff, gbase, voff) do { _Pragma("unroll") for (int _i = 0; _i < 2; ++_i) \
;         __builtin_amdgcn_global_load_lds((const unsigned*)((const char*)(gbase) + (voff)[_i]), (PG8_LAS unsigned*)(lds + (bufoff) + ldsw + _i * 8192), 16, 0, 0); } while (0)
; #define PG8_LDA(dst, b, h) do { _Pragma("unroll") for (int m = 0; m < 4; ++m) _Pragma("unroll") for (int k = 0; k < 2; ++k) dst[m][k] = *(const PG8_LAS bf16x8*)(lds + PG8_SA(b, h) + aoff + m * 2048 + k * 1024); } while (0)
; #define PG8_LDB(dst, b, h) do { _Pragma("unroll") for (int n = 0; n < 2; ++n) _Pragma("unroll") for (int k = 0; k < 2; ++k) dst[n][k] = *(const PG8_LAS bf16x8*)(lds + PG8_SB(b, h) + boff + n * 2048 + k * 1024); } while (0)
; #define PG8_MMA(ai, bj, At, Bt) do { __builtin_amdgcn_s_setprio(1); _Pragma("unroll") for (int m = 0; m < 4; ++m) _Pragma("unroll") for (int n = 0; n < 2; ++n) _Pragma("unroll") for (int k = 0; k < 2; ++k) \
;         acc[ai][bj][m][n] = __builtin_amdgcn_mfma_f32_16x16x32_bf16(Bt[n][k], At[m][k], acc[ai][bj][m][n], 0, 0, 0); __builtin_amdgcn_s_setprio(0); } while (0)
; #define PG8_WAIT_V(n) asm volatile("s_waitcnt vmcnt(" #n ")" ::: "memory")
; #define PG8_WAIT_L(n) asm volatile("s_waitcnt lgkmcnt(" #n ")" ::: "memory")
; #define PG8_BAR __builtin_amdgcn_s_barrier()
; #define PG8_SCHED __builtin_amdgcn_sched_barrier(0)
;     ...
;             PG8_WAIT_V(8); PG8_WAIT_L(0); PG8_BAR; PG8_MMA(1, 0, At, B0); PG8_MMA(1, 1, At, B1); PG8_BAR; PG8_SCHED;
;             PG8_LDB(B0, 1, 0); PG8_LDB(B1, 1, 1); PG8_SCHED; PG8_LDA(At, 1, 0); PG8_STAGE(PG8_SA(0, 1), a2 + hstep, voffA);
;             PG8_WAIT_V(8); PG8_WAIT_L(0); PG8_BAR; PG8_MMA(0, 0, At, B0); PG8_MMA(0, 1, At, B1); PG8_BAR; PG8_SCHED;
	v_mfma_f32_16x16x32_bf16 v[60:63], v[144:147], v[182:185], 0
	v_mfma_f32_16x16x32_bf16 v[60:63], v[148:151], v[186:189], v[60:63]
	v_mfma_f32_16x16x32_bf16 v[52:55], v[144:147], v[190:193], 0
	v_mfma_f32_16x16x32_bf16 v[52:55], v[148:151], v[194:197], v[52:55]
	v_mfma_f32_16x16x32_bf16 v[36:39], v[144:147], v[198:201], 0
	v_mfma_f32_16x16x32_bf16 v[36:39], v[148:151], v[202:205], v[36:39]
	v_mfma_f32_16x16x32_bf16 v[20:23], v[144:147], v[206:209], 0
	v_mfma_f32_16x16x32_bf16 v[20:23], v[148:151], v[210:213], v[20:23]
	v_mfma_f32_16x16x32_bf16 v[56:59], v[152:155], v[182:185], 0
	v_mfma_f32_16x16x32_bf16 v[56:59], v[156:159], v[186:189], v[56:59]
	v_mfma_f32_16x16x32_bf16 v[48:51], v[152:155], v[190:193], 0
	v_mfma_f32_16x16x32_bf16 v[48:51], v[156:159], v[194:197], v[48:51]
	v_mfma_f32_16x16x32_bf16 v[32:35], v[152:155], v[198:201], 0
	v_mfma_f32_16x16x32_bf16 v[32:35], v[156:159], v[202:205], v[32:35]
	v_mfma_f32_16x16x32_bf16 v[16:19], v[152:155], v[206:209], 0
	v_mfma_f32_16x16x32_bf16 v[16:19], v[156:159], v[210:213], v[16:19]
	v_mfma_f32_16x16x32_bf16 v[44:47], v[160:163], v[182:185], 0
	v_mfma_f32_16x16x32_bf16 v[44:47], v[164:167], v[186:189], v[44:47]
	v_mfma_f32_16x16x32_bf16 v[28:31], v[160:163], v[190:193], 0
	v_mfma_f32_16x16x32_bf16 v[28:31], v[164:167], v[194:197], v[28:31]
	v_mfma_f32_16x16x32_bf16 v[12:15], v[160:163], v[198:201], 0
	v_mfma_f32_16x16x32_bf16 v[12:15], v[164:167], v[202:205], v[12:15]
	v_mfma_f32_16x16x32_bf16 v[4:7], v[160:163], v[206:209], 0
	v_mfma_f32_16x16x32_bf16 v[4:7], v[164:167], v[210:213], v[4:7]
	v_mfma_f32_16x16x32_bf16 v[40:43], v[170:173], v[182:185], 0
	v_mfma_f32_16x16x32_bf16 v[40:43], v[178:181], v[186:189], v[40:43]
	v_mfma_f32_16x16x32_bf16 v[24:27], v[170:173], v[190:193], 0
	v_mfma_f32_16x16x32_bf16 v[24:27], v[178:181], v[194:197], v[24:27]
	v_mfma_f32_16x16x32_bf16 v[8:11], v[170:173], v[198:201], 0
	v_mfma_f32_16x16x32_bf16 v[8:11], v[178:181], v[202:205], v[8:11]
	v_mfma_f32_16x16x32_bf16 v[0:3], v[170:173], v[206:209], 0
	v_mfma_f32_16x16x32_bf16 v[0:3], v[178:181], v[210:213], v[0:3]
	s_barrier
	s_setprio 0
	s_add_i32 s3, 0, 0x18000
	s_add_i32 s12, 0, 0x1c000
	v_add_u32_e32 v156, s3, v141
	v_add_u32_e32 v168, s12, v141
	ds_read_b128 v[144:147], v156
	ds_read_b128 v[148:151], v156 offset:1024
	ds_read_b128 v[152:155], v156 offset:2048
	ds_read_b128 v[156:159], v156 offset:3072
	ds_read_b128 v[160:163], v168
	ds_read_b128 v[164:167], v168 offset:1024
	ds_read_b128 v[170:173], v168 offset:2048
	ds_read_b128 v[178:181], v168 offset:3072
	s_add_u32 s90, s90, 0x80000
	s_addc_u32 s91, s91, 0
	s_mov_b32 m0, s20
	ds_read_b128 v[182:185], v143 offset:32768
	ds_read_b128 v[186:189], v143 offset:33792
	ds_read_b128 v[190:193], v143 offset:34816
	ds_read_b128 v[194:197], v143 offset:35840
	ds_read_b128 v[198:201], v143 offset:36864
	ds_read_b128 v[202:205], v143 offset:37888
	ds_read_b128 v[206:209], v143 offset:38912
	ds_read_b128 v[210:213], v143 offset:39936
	global_load_lds_dwordx4 v128, s[90:91]
	s_mov_b32 m0, s21
	s_nop 0
	global_load_lds_dwordx4 v132, s[90:91]
	s_waitcnt vmcnt(8)
	s_waitcnt lgkmcnt(0)
	s_setprio 1
	s_barrier
	v_mfma_f32_16x16x32_bf16 v[124:127], v[144:147], v[182:185], v[124:127]
	v_mfma_f32_16x16x32_bf16 v[124:127], v[148:151], v[186:189], v[124:127]
	v_mfma_f32_16x16x32_bf16 v[116:119], v[144:147], v[190:193], v[116:119]
	v_mfma_f32_16x16x32_bf16 v[116:119], v[148:151], v[194:197], v[116:119]
	v_mfma_f32_16x16x32_bf16 v[100:103], v[144:147], v[198:201], v[100:103]
	v_mfma_f32_16x16x32_bf16 v[100:103], v[148:151], v[202:205], v[100:103]
	v_mfma_f32_16x16x32_bf16 v[84:87], v[144:147], v[206:209], v[84:87]
	v_mfma_f32_16x16x32_bf16 v[84:87], v[148:151], v[210:213], v[84:87]
	v_mfma_f32_16x16x32_bf16 v[120:123], v[152:155], v[182:185], v[120:123]
	v_mfma_f32_16x16x32_bf16 v[120:123], v[156:159], v[186:189], v[120:123]
	v_mfma_f32_16x16x32_bf16 v[112:115], v[152:155], v[190:193], v[112:115]
	v_mfma_f32_16x16x32_bf16 v[112:115], v[156:159], v[194:197], v[112:115]
	v_mfma_f32_16x16x32_bf16 v[96:99], v[152:155], v[198:201], v[96:99]
	v_mfma_f32_16x16x32_bf16 v[96:99], v[156:159], v[202:205], v[96:99]
	v_mfma_f32_16x16x32_bf16 v[80:83], v[152:155], v[206:209], v[80:83]
	v_mfma_f32_16x16x32_bf16 v[80:83], v[156:159], v[210:213], v[80:83]
	v_mfma_f32_16x16x32_bf16 v[108:111], v[160:163], v[182:185], v[108:111]
	v_mfma_f32_16x16x32_bf16 v[108:111], v[164:167], v[186:189], v[108:111]
	v_mfma_f32_16x16x32_bf16 v[92:95], v[160:163], v[190:193], v[92:95]
	v_mfma_f32_16x16x32_bf16 v[92:95], v[164:167], v[194:197], v[92:95]
	v_mfma_f32_16x16x32_bf16 v[76:79], v[160:163], v[198:201], v[76:79]
	v_mfma_f32_16x16x32_bf16 v[76:79], v[164:167], v[202:205], v[76:79]
	v_mfma_f32_16x16x32_bf16 v[68:71], v[160:163], v[206:209], v[68:71]
	v_mfma_f32_16x16x32_bf16 v[68:71], v[164:167], v[210:213], v[68:71]
	v_mfma_f32_16x16x32_bf16 v[104:107], v[170:173], v[182:185], v[104:107]
	v_mfma_f32_16x16x32_bf16 v[104:107], v[178:181], v[186:189], v[104:107]
	v_mfma_f32_16x16x32_bf16 v[88:91], v[170:173], v[190:193], v[88:91]
	v_mfma_f32_16x16x32_bf16 v[88:91], v[178:181], v[194:197], v[88:91]
	v_mfma_f32_16x16x32_bf16 v[72:75], v[170:173], v[198:201], v[72:75]
	v_mfma_f32_16x16x32_bf16 v[72:75], v[178:181], v[202:205], v[72:75]
	v_mfma_f32_16x16x32_bf16 v[64:67], v[170:173], v[206:209], v[64:67]
	v_mfma_f32_16x16x32_bf16 v[64:67], v[178:181], v[210:213], v[64:67]
	s_barrier
; #define PG8_STAGE(bufoff, gbase, voff) do { _Pragma("unroll") for (int _i = 0; _i < 2; ++_i) \
;         __builtin_amdgcn_global_load_lds((const unsigned*)((const char*)(gbase) + (voff)[_i]), (PG8_LAS unsigned*)(lds + (bufoff) + ldsw + _i * 8192), 16, 0, 0); } while (0)
; #define PG8_LDA(dst, b, h) do { _Pragma("unroll") for (int m = 0; m < 4; ++m) _Pragma("unroll") for (int k = 0; k < 2; ++k) dst[m][k] = *(const PG8_LAS bf16x8*)(lds + PG8_SA(b, h) + aoff + m * 2048 + k * 1024); } while (0)
; #define PG8_MMA(ai, bj, At, Bt) do { __builtin_amdgcn_s_setprio(1); _Pragma("unroll") for (int m = 0; m < 4; ++m) _Pragma("unroll") for (int n = 0; n < 2; ++n) _Pragma("unroll") for (int k = 0; k < 2; ++k) \
;         acc[ai][bj][m][n] = __builtin_amdgcn_mfma_f32_16x16x32_bf16(Bt[n][k], At[m][k], acc[ai][bj][m][n], 0, 0, 0); __builtin_amdgcn_s_setprio(0); } while (0)
; #define PG8_WAIT_V(n) asm volatile("s_waitcnt vmcnt(" #n ")" ::: "memory")
; #define PG8_WAIT_L(n) asm volatile("s_waitcnt lgkmcnt(" #n ")" ::: "memory")
; #define PG8_BAR __builtin_amdgcn_s_barrier()
; #define PG8_SCHED __builtin_amdgcn_sched_barrier(0)
;     ...
;             PG8_WAIT_V(8); PG8_WAIT_L(0); PG8_BAR; PG8_MMA(0, 0, At, B0); PG8_MMA(0, 1, At, B1); PG8_BAR; PG8_SCHED;
;             PG8_LDA(At, 1, 1); PG8_STAGE(PG8_SB(1, 0), b3, voffB); PG8_STAGE(PG8_SB(1, 1), b3 + hstep, voffB); PG8_STAGE(PG8_SA(1, 0), a3, voffA);
;             PG8_WAIT_V(8); PG8_WAIT_L(0); PG8_BAR; PG8_MMA(1, 0, At, B0); PG8_MMA(1, 1, At, B1); PG8_BAR; PG8_SCHED;
	s_setprio 0
	s_add_i32 s3, s3, s10
	s_mov_b32 m0, s3
	ds_read_b128 v[182:185], v143 offset:49152
	ds_read_b128 v[186:189], v143 offset:50176
	ds_read_b128 v[190:193], v143 offset:51200
	ds_read_b128 v[194:197], v143 offset:52224
	ds_read_b128 v[198:201], v143 offset:53248
	ds_read_b128 v[202:205], v143 offset:54272
	ds_read_b128 v[206:209], v143 offset:55296
	ds_read_b128 v[210:213], v143 offset:56320
	s_add_u32 s100, s88, s16
	s_addc_u32 s101, s89, s17
	global_load_lds_dwordx4 v130, s[100:101]
	s_add_i32 m0, s3, 0x2000
	s_add_u32 s88, s88, 0x80080
	v_lshl_add_u64 v[214:215], v[216:217], 0, s[16:17]
	s_addc_u32 s89, s89, 0
	s_add_i32 s3, s12, s10
	global_load_lds_dwordx4 v[214:215], off
	s_mov_b32 m0, s3
	s_nop 0
	global_load_lds_dwordx4 v130, s[88:89]
	s_add_i32 m0, s3, 0x2000
	s_nop 0
	global_load_lds_dwordx4 v134, s[88:89]
	v_lshl_add_u64 v[214:215], v[218:219], 0, s[16:17]
	s_mov_b32 m0, s22
	s_nop 0
	global_load_lds_dwordx4 v[214:215], off
	v_lshl_add_u64 v[214:215], v[220:221], 0, s[16:17]
	s_mov_b32 m0, s23
	s_nop 0
	global_load_lds_dwordx4 v[214:215], off
	s_waitcnt vmcnt(8)
	s_waitcnt lgkmcnt(0)
	s_setprio 1
	s_barrier
	v_mfma_f32_16x16x32_bf16 v[60:63], v[144:147], v[182:185], v[60:63]
	v_mfma_f32_16x16x32_bf16 v[60:63], v[148:151], v[186:189], v[60:63]
	v_mfma_f32_16x16x32_bf16 v[52:55], v[144:147], v[190:193], v[52:55]
	v_mfma_f32_16x16x32_bf16 v[52:55], v[148:151], v[194:197], v[52:55]
	v_mfma_f32_16x16x32_bf16 v[36:39], v[144:147], v[198:201], v[36:39]
	v_mfma_f32_16x16x32_bf16 v[36:39], v[148:151], v[202:205], v[36:39]
	v_mfma_f32_16x16x32_bf16 v[20:23], v[144:147], v[206:209], v[20:23]
	v_mfma_f32_16x16x32_bf16 v[20:23], v[148:151], v[210:213], v[20:23]
	v_mfma_f32_16x16x32_bf16 v[56:59], v[152:155], v[182:185], v[56:59]
	v_mfma_f32_16x16x32_bf16 v[56:59], v[156:159], v[186:189], v[56:59]
	v_mfma_f32_16x16x32_bf16 v[48:51], v[152:155], v[190:193], v[48:51]
	v_mfma_f32_16x16x32_bf16 v[48:51], v[156:159], v[194:197], v[48:51]
	v_mfma_f32_16x16x32_bf16 v[32:35], v[152:155], v[198:201], v[32:35]
	v_mfma_f32_16x16x32_bf16 v[32:35], v[156:159], v[202:205], v[32:35]
	v_mfma_f32_16x16x32_bf16 v[16:19], v[152:155], v[206:209], v[16:19]
	v_mfma_f32_16x16x32_bf16 v[16:19], v[156:159], v[210:213], v[16:19]
	v_mfma_f32_16x16x32_bf16 v[44:47], v[160:163], v[182:185], v[44:47]
	v_mfma_f32_16x16x32_bf16 v[44:47], v[164:167], v[186:189], v[44:47]
	v_mfma_f32_16x16x32_bf16 v[28:31], v[160:163], v[190:193], v[28:31]
	v_mfma_f32_16x16x32_bf16 v[28:31], v[164:167], v[194:197], v[28:31]
	v_mfma_f32_16x16x32_bf16 v[12:15], v[160:163], v[198:201], v[12:15]
	v_mfma_f32_16x16x32_bf16 v[12:15], v[164:167], v[202:205], v[12:15]
	v_mfma_f32_16x16x32_bf16 v[4:7], v[160:163], v[206:209], v[4:7]
	v_mfma_f32_16x16x32_bf16 v[4:7], v[164:167], v[210:213], v[4:7]
	v_mfma_f32_16x16x32_bf16 v[40:43], v[170:173], v[182:185], v[40:43]
	v_mfma_f32_16x16x32_bf16 v[40:43], v[178:181], v[186:189], v[40:43]
	v_mfma_f32_16x16x32_bf16 v[24:27], v[170:173], v[190:193], v[24:27]
	v_mfma_f32_16x16x32_bf16 v[24:27], v[178:181], v[194:197], v[24:27]
	v_mfma_f32_16x16x32_bf16 v[8:11], v[170:173], v[198:201], v[8:11]
	v_mfma_f32_16x16x32_bf16 v[8:11], v[178:181], v[202:205], v[8:11]
	v_mfma_f32_16x16x32_bf16 v[0:3], v[170:173], v[206:209], v[0:3]
	v_mfma_f32_16x16x32_bf16 v[0:3], v[178:181], v[210:213], v[0:3]
	s_barrier
	s_setprio 0
	s_add_i32 s2, s2, 2
	s_add_u32 s86, s86, 0x100
	s_addc_u32 s87, s87, 0
	s_add_u32 s42, s42, 0x100
	s_addc_u32 s43, s43, 0
	s_cmp_gt_u32 s2, 29

; #define PG8_STAGE(bufoff, gbase, voff) do { _Pragma("unroll") for (int _i = 0; _i < 2; ++_i) \
;         __builtin_amdgcn_global_load_lds((const unsigned*)((const char*)(gbase) + (voff)[_i]), (PG8_LAS unsigned*)(lds + (bufoff) + ldsw + _i * 8192), 16, 0, 0); } while (0)
; #define PG8_LDA(dst, b, h) do { _Pragma("unroll") for (int m = 0; m < 4; ++m) _Pragma("unroll") for (int k = 0; k < 2; ++k) dst[m][k] = *(const PG8_LAS bf16x8*)(lds + PG8_SA(b, h) + aoff + m * 2048 + k * 1024); } while (0)
; #define PG8_LDB(dst, b, h) do { _Pragma("unroll") for (int n = 0; n < 2; ++n) _Pragma("unroll") for (int k = 0; k < 2; ++k) dst[n][k] = *(const PG8_LAS bf16x8*)(lds + PG8_SB(b, h) + boff + n * 2048 + k * 1024); } while (0)
; #define PG8_MMA(ai, bj, At, Bt) do { __builtin_amdgcn_s_setprio(1); _Pragma("unroll") for (int m = 0; m < 4; ++m) _Pragma("unroll") for (int n = 0; n < 2; ++n) _Pragma("unroll") for (int k = 0; k < 2; ++k) \
;         acc[ai][bj][m][n] = __builtin_amdgcn_mfma_f32_16x16x32_bf16(Bt[n][k], At[m][k], acc[ai][bj][m][n], 0, 0, 0); __builtin_amdgcn_s_setprio(0); } while (0)
; #define PG8_WAIT_V(n) asm volatile("s_waitcnt vmcnt(" #n ")" ::: "memory")
; #define PG8_WAIT_L(n) asm volatile("s_waitcnt lgkmcnt(" #n ")" ::: "memory")
;     ...
;         const char* nA = has_next ? (const char*)g.A + (size_t)nxt.pm * tstep : cA; const char* nB = has_next ? (const char*)g.Bt + (size_t)nxt.pn * tstep : cB;
;         for (int t = 0; t < nt; t += 2) {
;             if constexpr (Epi::MIDK) { if (t == nt / 2) E.midk(acc, cur, wr, wc, fr, fq); }
;             const bool last = (t == nt - 2);
;             const char* a1 = PG8_KADV(cA, (size_t)(t + 1) * kstep);
;             const char* a2 = last ? nA : PG8_KADV(cA, (size_t)(t + 2) * kstep); const char* b2 = last ? nB : PG8_KADV(cB, (size_t)(t + 2) * kstep);
;             const char* a3 = PG8_KADV(a2, kstep); const char* b3 = PG8_KADV(b2, kstep);
;             if (last && has_next) S.a_ready(nxt);
;             if constexpr (SP2) {
;             PG8_LDB(B0, 0, 0); PG8_LDB(B1, 0, 1); PG8_SCHED; PG8_LDA(At, 0, 0); PG8_STAGE(PG8_SA(1, 1), a1 + hstep, voffA);
;             PG8_WAIT_V(8); PG8_WAIT_L(0); PG8_BAR; PG8_MMA(0, 0, At, B0); PG8_MMA(0, 1, At, B1); PG8_BAR; PG8_SCHED;
;             PG8_LDA(At, 0, 1); PG8_STAGE(PG8_SB(0, 0), b2, voffB); PG8_STAGE(PG8_SB(0, 1), b2 + hstep, voffB); PG8_STAGE(PG8_SA(0, 0), a2, voffA);
.LBB0_540:
	s_ashr_i32 s81, s80, 31
	s_lshl_b64 s[2:3], s[80:81], 20
	s_add_u32 s82, s54, s2
	s_addc_u32 s83, s55, s3
	s_and_b64 s[2:3], s[4:5], exec
	s_cselect_b32 s15, s83, s89
	s_cselect_b32 s30, s82, s88
	s_ashr_i32 s79, s78, 31
	s_lshl_b64 s[2:3], s[78:79], 20
	s_add_u32 s84, s10, s2
	s_addc_u32 s85, s19, s3
	s_and_b64 s[2:3], s[4:5], exec
	s_cselect_b32 s33, s85, s91
	s_cselect_b32 s40, s84, s90
	s_add_u32 s88, s88, 0x80080
	s_addc_u32 s89, s89, 0
	s_add_u32 s42, s90, 0x100
	s_addc_u32 s43, s91, 0
	s_mov_b32 s2, -2
	s_add_u32 s3, s88, 0xfff80080
	s_addc_u32 s12, s89, -1
	s_add_i32 s13, 0, 0x10000
	s_cmp_eq_u32 s2, 28
	s_cselect_b32 s93, s15, s12
	s_cselect_b32 s92, s30, s3
	v_add_u32_e32 v140, s13, v142
	s_cselect_b32 s91, s33, s43
	s_cselect_b32 s90, s40, s42
	s_add_i32 s3, 0, 0x14000
	ds_read_b128 v[146:149], v140
	ds_read_b128 v[150:153], v140 offset:1024
	ds_read_b128 v[154:157], v140 offset:2048
	ds_read_b128 v[158:161], v140 offset:3072
	v_add_u32_e32 v140, s3, v142
	ds_read_b128 v[162:165], v140
	ds_read_b128 v[170:173], v140 offset:1024
	ds_read_b128 v[178:181], v140 offset:2048
	ds_read_b128 v[182:185], v140 offset:3072
	s_add_i32 m0, s21, 0xc000
	ds_read_b128 v[186:189], v145
	ds_read_b128 v[190:193], v145 offset:1024
	ds_read_b128 v[194:197], v145 offset:2048
	ds_read_b128 v[198:201], v145 offset:3072
	ds_read_b128 v[202:205], v145 offset:4096
	ds_read_b128 v[206:209], v145 offset:5120
	ds_read_b128 v[210:213], v145 offset:6144
	ds_read_b128 v[214:217], v145 offset:7168
	global_load_lds_dwordx4 v136, s[88:89]
	s_add_i32 m0, s21, 0xe000
	s_nop 0
	global_load_lds_dwordx4 v138, s[88:89]
	s_waitcnt vmcnt(8)
	s_waitcnt lgkmcnt(0)
	s_setprio 1
	s_barrier
	v_mfma_f32_16x16x32_bf16 v[124:127], v[146:149], v[186:189], 0
	v_mfma_f32_16x16x32_bf16 v[124:127], v[150:153], v[190:193], v[124:127]
	v_mfma_f32_16x16x32_bf16 v[116:119], v[146:149], v[194:197], 0
	v_mfma_f32_16x16x32_bf16 v[116:119], v[150:153], v[198:201], v[116:119]
	v_mfma_f32_16x16x32_bf16 v[100:103], v[146:149], v[202:205], 0
	v_mfma_f32_16x16x32_bf16 v[100:103], v[150:153], v[206:209], v[100:103]
	v_mfma_f32_16x16x32_bf16 v[84:87], v[146:149], v[210:213], 0
	v_mfma_f32_16x16x32_bf16 v[84:87], v[150:153], v[214:217], v[84:87]
	v_mfma_f32_16x16x32_bf16 v[120:123], v[154:157], v[186:189], 0
	v_mfma_f32_16x16x32_bf16 v[120:123], v[158:161], v[190:193], v[120:123]
	v_mfma_f32_16x16x32_bf16 v[112:115], v[154:157], v[194:197], 0
	v_mfma_f32_16x16x32_bf16 v[112:115], v[158:161], v[198:201], v[112:115]
	v_mfma_f32_16x16x32_bf16 v[96:99], v[154:157], v[202:205], 0
	v_mfma_f32_16x16x32_bf16 v[96:99], v[158:161], v[206:209], v[96:99]
	v_mfma_f32_16x16x32_bf16 v[80:83], v[154:157], v[210:213], 0
	v_mfma_f32_16x16x32_bf16 v[80:83], v[158:161], v[214:217], v[80:83]
	v_mfma_f32_16x16x32_bf16 v[108:111], v[162:165], v[186:189], 0
	v_mfma_f32_16x16x32_bf16 v[108:111], v[170:173], v[190:193], v[108:111]
	v_mfma_f32_16x16x32_bf16 v[92:95], v[162:165], v[194:197], 0
	v_mfma_f32_16x16x32_bf16 v[92:95], v[170:173], v[198:201], v[92:95]
	v_mfma_f32_16x16x32_bf16 v[76:79], v[162:165], v[202:205], 0
	v_mfma_f32_16x16x32_bf16 v[76:79], v[170:173], v[206:209], v[76:79]
	v_mfma_f32_16x16x32_bf16 v[68:71], v[162:165], v[210:213], 0
	v_mfma_f32_16x16x32_bf16 v[68:71], v[170:173], v[214:217], v[68:71]
	v_mfma_f32_16x16x32_bf16 v[104:107], v[178:181], v[186:189], 0
	v_mfma_f32_16x16x32_bf16 v[104:107], v[182:185], v[190:193], v[104:107]
	v_mfma_f32_16x16x32_bf16 v[88:91], v[178:181], v[194:197], 0
	v_mfma_f32_16x16x32_bf16 v[88:91], v[182:185], v[198:201], v[88:91]
	v_mfma_f32_16x16x32_bf16 v[72:75], v[178:181], v[202:205], 0
	v_mfma_f32_16x16x32_bf16 v[72:75], v[182:185], v[206:209], v[72:75]
	v_mfma_f32_16x16x32_bf16 v[64:67], v[178:181], v[210:213], 0
	v_mfma_f32_16x16x32_bf16 v[64:67], v[182:185], v[214:217], v[64:67]
	s_barrier
	s_setprio 0
	s_add_i32 s12, s13, s20
	s_mov_b32 m0, s12
	ds_read_b128 v[186:189], v145 offset:16384
	ds_read_b128 v[190:193], v145 offset:17408
	ds_read_b128 v[194:197], v145 offset:18432
	ds_read_b128 v[198:201], v145 offset:19456
	ds_read_b128 v[202:205], v145 offset:20480
	ds_read_b128 v[206:209], v145 offset:21504
	ds_read_b128 v[210:213], v145 offset:22528
	ds_read_b128 v[214:217], v145 offset:23552
	global_load_lds_dwordx4 v132, s[90:91]
	s_add_i32 m0, s12, 0x2000
	s_add_u32 vcc_lo, s90, 0x80000
	v_lshl_add_u64 v[218:219], s[90:91], 0, v[128:129]
	s_addc_u32 vcc_hi, s91, 0
	s_add_i32 s3, s3, s20
	global_load_lds_dwordx4 v128, s[90:91]
	s_mov_b32 m0, s3
	v_lshl_add_u64 v[222:223], s[92:93], 0, v[130:131]
	global_load_lds_dwordx4 v132, vcc
	s_add_i32 m0, s3, 0x2000
	s_nop 0
	global_load_lds_dwordx4 v128, vcc
	v_lshl_add_u64 v[220:221], s[92:93], 0, v[134:135]
	s_mov_b32 m0, s21
	s_nop 0
	global_load_lds_dwordx4 v134, s[92:93]
	s_mov_b32 m0, s22
	s_nop 0
	global_load_lds_dwordx4 v130, s[92:93]
	s_waitcnt vmcnt(8)
	s_waitcnt lgkmcnt(0)
	s_setprio 1
	s_barrier
; #define PG8_STAGE(bufoff, gbase, voff) do { _Pragma("unroll") for (int _i = 0; _i < 2; ++_i) \
;         __builtin_amdgcn_global_load_lds((const unsigned*)((const char*)(gbase) + (voff)[_i]), (PG8_LAS unsigned*)(lds + (bufoff) + ldsw + _i * 8192), 16, 0, 0); } while (0)
; #define PG8_LDA(dst, b, h) do { _Pragma("unroll") for (int m = 0; m < 4; ++m) _Pragma("unroll") for (int k = 0; k < 2; ++k) dst[m][k] = *(const PG8_LAS bf16x8*)(lds + PG8_SA(b, h) + aoff + m * 2048 + k * 1024); } while (0)
; #define PG8_LDB(dst, b, h) do { _Pragma("unroll") for (int n = 0; n < 2; ++n) _Pragma("unroll") for (int k = 0; k < 2; ++k) dst[n][k] = *(const PG8_LAS bf16x8*)(lds + PG8_SB(b, h) + boff + n * 2048 + k * 1024); } while (0)
; #define PG8_MMA(ai, bj, At, Bt) do { __builtin_amdgcn_s_setprio(1); _Pragma("unroll") for (int m = 0; m < 4; ++m) _Pragma("unroll") for (int n = 0; n < 2; ++n) _Pragma("unroll") for (int k = 0; k < 2; ++k) \
;         acc[ai][bj][m][n] = __builtin_amdgcn_mfma_f32_16x16x32_bf16(Bt[n][k], At[m][k], acc[ai][bj][m][n], 0, 0, 0); __builtin_amdgcn_s_setprio(0); } while (0)
; #define PG8_WAIT_V(n) asm volatile("s_waitcnt vmcnt(" #n ")" ::: "memory")
; #define PG8_WAIT_L(n) asm volatile("s_waitcnt lgkmcnt(" #n ")" ::: "memory")
; #define PG8_BAR __builtin_amdgcn_s_barrier()
; #define PG8_SCHED __builtin_amdgcn_sched_barrier(0)
;     ...
;             PG8_WAIT_V(8); PG8_WAIT_L(0); PG8_BAR; PG8_MMA(1, 0, At, B0); PG8_MMA(1, 1, At, B1); PG8_BAR; PG8_SCHED;
;             PG8_LDB(B0, 1, 0); PG8_LDB(B1, 1, 1); PG8_SCHED; PG8_LDA(At, 1, 0); PG8_STAGE(PG8_SA(0, 1), a2 + hstep, voffA);
;             PG8_WAIT_V(8); PG8_WAIT_L(0); PG8_BAR; PG8_MMA(0, 0, At, B0); PG8_MMA(0, 1, At, B1); PG8_BAR; PG8_SCHED;
	v_mfma_f32_16x16x32_bf16 v[60:63], v[146:149], v[186:189], 0
	v_mfma_f32_16x16x32_bf16 v[60:63], v[150:153], v[190:193], v[60:63]
	v_mfma_f32_16x16x32_bf16 v[52:55], v[146:149], v[194:197], 0
	v_mfma_f32_16x16x32_bf16 v[52:55], v[150:153], v[198:201], v[52:55]
	v_mfma_f32_16x16x32_bf16 v[36:39], v[146:149], v[202:205], 0
	v_mfma_f32_16x16x32_bf16 v[36:39], v[150:153], v[206:209], v[36:39]
	v_mfma_f32_16x16x32_bf16 v[20:23], v[146:149], v[210:213], 0
	v_mfma_f32_16x16x32_bf16 v[20:23], v[150:153], v[214:217], v[20:23]
	v_mfma_f32_16x16x32_bf16 v[56:59], v[154:157], v[186:189], 0
	v_mfma_f32_16x16x32_bf16 v[56:59], v[158:161], v[190:193], v[56:59]
	v_mfma_f32_16x16x32_bf16 v[48:51], v[154:157], v[194:197], 0
	v_mfma_f32_16x16x32_bf16 v[48:51], v[158:161], v[198:201], v[48:51]
	v_mfma_f32_16x16x32_bf16 v[32:35], v[154:157], v[202:205], 0
	v_mfma_f32_16x16x32_bf16 v[32:35], v[158:161], v[206:209], v[32:35]
	v_mfma_f32_16x16x32_bf16 v[16:19], v[154:157], v[210:213], 0
	v_mfma_f32_16x16x32_bf16 v[16:19], v[158:161], v[214:217], v[16:19]
	v_mfma_f32_16x16x32_bf16 v[44:47], v[162:165], v[186:189], 0
	v_mfma_f32_16x16x32_bf16 v[44:47], v[170:173], v[190:193], v[44:47]
	v_mfma_f32_16x16x32_bf16 v[28:31], v[162:165], v[194:197], 0
	v_mfma_f32_16x16x32_bf16 v[28:31], v[170:173], v[198:201], v[28:31]
	v_mfma_f32_16x16x32_bf16 v[12:15], v[162:165], v[202:205], 0
	v_mfma_f32_16x16x32_bf16 v[12:15], v[170:173], v[206:209], v[12:15]
	v_mfma_f32_16x16x32_bf16 v[4:7], v[162:165], v[210:213], 0
	v_mfma_f32_16x16x32_bf16 v[4:7], v[170:173], v[214:217], v[4:7]
	v_mfma_f32_16x16x32_bf16 v[40:43], v[178:181], v[186:189], 0
	v_mfma_f32_16x16x32_bf16 v[40:43], v[182:185], v[190:193], v[40:43]
	v_mfma_f32_16x16x32_bf16 v[24:27], v[178:181], v[194:197], 0
	v_mfma_f32_16x16x32_bf16 v[24:27], v[182:185], v[198:201], v[24:27]
	v_mfma_f32_16x16x32_bf16 v[8:11], v[178:181], v[202:205], 0
	v_mfma_f32_16x16x32_bf16 v[8:11], v[182:185], v[206:209], v[8:11]
	v_mfma_f32_16x16x32_bf16 v[0:3], v[178:181], v[210:213], 0
	v_mfma_f32_16x16x32_bf16 v[0:3], v[182:185], v[214:217], v[0:3]
	s_barrier
	s_setprio 0
	s_add_i32 s3, 0, 0x18000
	v_add_u32_e32 v140, s3, v142
	s_add_i32 s12, 0, 0x1c000
	ds_read_b128 v[146:149], v140
	ds_read_b128 v[150:153], v140 offset:1024
	ds_read_b128 v[154:157], v140 offset:2048
	ds_read_b128 v[158:161], v140 offset:3072
	v_add_u32_e32 v140, s12, v142
	ds_read_b128 v[162:165], v140
	ds_read_b128 v[170:173], v140 offset:1024
	ds_read_b128 v[178:181], v140 offset:2048
	ds_read_b128 v[182:185], v140 offset:3072
	s_add_u32 s92, s92, 0x80000
	s_addc_u32 s93, s93, 0
	s_mov_b32 m0, s23
	ds_read_b128 v[186:189], v145 offset:32768
	ds_read_b128 v[190:193], v145 offset:33792
	ds_read_b128 v[194:197], v145 offset:34816
	ds_read_b128 v[198:201], v145 offset:35840
	ds_read_b128 v[202:205], v145 offset:36864
	ds_read_b128 v[206:209], v145 offset:37888
	ds_read_b128 v[210:213], v145 offset:38912
	ds_read_b128 v[214:217], v145 offset:39936
	global_load_lds_dwordx4 v134, s[92:93]
	s_mov_b32 m0, s57
	s_nop 0
	global_load_lds_dwordx4 v130, s[92:93]
	s_waitcnt vmcnt(8)
	s_waitcnt lgkmcnt(0)
	s_setprio 1
	s_barrier
	v_mfma_f32_16x16x32_bf16 v[124:127], v[146:149], v[186:189], v[124:127]
	v_mfma_f32_16x16x32_bf16 v[124:127], v[150:153], v[190:193], v[124:127]
	v_mfma_f32_16x16x32_bf16 v[116:119], v[146:149], v[194:197], v[116:119]
	v_mfma_f32_16x16x32_bf16 v[116:119], v[150:153], v[198:201], v[116:119]
	v_mfma_f32_16x16x32_bf16 v[100:103], v[146:149], v[202:205], v[100:103]
	v_mfma_f32_16x16x32_bf16 v[100:103], v[150:153], v[206:209], v[100:103]
	v_mfma_f32_16x16x32_bf16 v[84:87], v[146:149], v[210:213], v[84:87]
	v_mfma_f32_16x16x32_bf16 v[84:87], v[150:153], v[214:217], v[84:87]
	v_mfma_f32_16x16x32_bf16 v[120:123], v[154:157], v[186:189], v[120:123]
	v_mfma_f32_16x16x32_bf16 v[120:123], v[158:161], v[190:193], v[120:123]
	v_mfma_f32_16x16x32_bf16 v[112:115], v[154:157], v[194:197], v[112:115]
	v_mfma_f32_16x16x32_bf16 v[112:115], v[158:161], v[198:201], v[112:115]
	v_mfma_f32_16x16x32_bf16 v[96:99], v[154:157], v[202:205], v[96:99]
	v_mfma_f32_16x16x32_bf16 v[96:99], v[158:161], v[206:209], v[96:99]
	v_mfma_f32_16x16x32_bf16 v[80:83], v[154:157], v[210:213], v[80:83]
	v_mfma_f32_16x16x32_bf16 v[80:83], v[158:161], v[214:217], v[80:83]
	v_mfma_f32_16x16x32_bf16 v[108:111], v[162:165], v[186:189], v[108:111]
	v_mfma_f32_16x16x32_bf16 v[108:111], v[170:173], v[190:193], v[108:111]
	v_mfma_f32_16x16x32_bf16 v[92:95], v[162:165], v[194:197], v[92:95]
	v_mfma_f32_16x16x32_bf16 v[92:95], v[170:173], v[198:201], v[92:95]
	v_mfma_f32_16x16x32_bf16 v[76:79], v[162:165], v[202:205], v[76:79]
	v_mfma_f32_16x16x32_bf16 v[76:79], v[170:173], v[206:209], v[76:79]
	v_mfma_f32_16x16x32_bf16 v[68:71], v[162:165], v[210:213], v[68:71]
	v_mfma_f32_16x16x32_bf16 v[68:71], v[170:173], v[214:217], v[68:71]
	v_mfma_f32_16x16x32_bf16 v[104:107], v[178:181], v[186:189], v[104:107]
	v_mfma_f32_16x16x32_bf16 v[104:107], v[182:185], v[190:193], v[104:107]
	v_mfma_f32_16x16x32_bf16 v[88:91], v[178:181], v[194:197], v[88:91]
	v_mfma_f32_16x16x32_bf16 v[88:91], v[182:185], v[198:201], v[88:91]
	v_mfma_f32_16x16x32_bf16 v[72:75], v[178:181], v[202:205], v[72:75]
	v_mfma_f32_16x16x32_bf16 v[72:75], v[182:185], v[206:209], v[72:75]
	v_mfma_f32_16x16x32_bf16 v[64:67], v[178:181], v[210:213], v[64:67]
	v_mfma_f32_16x16x32_bf16 v[64:67], v[182:185], v[214:217], v[64:67]
	s_barrier
; #define PG8_STAGE(bufoff, gbase, voff) do { _Pragma("unroll") for (int _i = 0; _i < 2; ++_i) \
;         __builtin_amdgcn_global_load_lds((const unsigned*)((const char*)(gbase) + (voff)[_i]), (PG8_LAS unsigned*)(lds + (bufoff) + ldsw + _i * 8192), 16, 0, 0); } while (0)
; #define PG8_LDA(dst, b, h) do { _Pragma("unroll") for (int m = 0; m < 4; ++m) _Pragma("unroll") for (int k = 0; k < 2; ++k) dst[m][k] = *(const PG8_LAS bf16x8*)(lds + PG8_SA(b, h) + aoff + m * 2048 + k * 1024); } while (0)
; #define PG8_MMA(ai, bj, At, Bt) do { __builtin_amdgcn_s_setprio(1); _Pragma("unroll") for (int m = 0; m < 4; ++m) _Pragma("unroll") for (int n = 0; n < 2; ++n) _Pragma("unroll") for (int k = 0; k < 2; ++k) \
;         acc[ai][bj][m][n] = __builtin_amdgcn_mfma_f32_16x16x32_bf16(Bt[n][k], At[m][k], acc[ai][bj][m][n], 0, 0, 0); __builtin_amdgcn_s_setprio(0); } while (0)
; #define PG8_WAIT_V(n) asm volatile("s_waitcnt vmcnt(" #n ")" ::: "memory")
; #define PG8_WAIT_L(n) asm volatile("s_waitcnt lgkmcnt(" #n ")" ::: "memory")
; #define PG8_BAR __builtin_amdgcn_s_barrier()
; #define PG8_SCHED __builtin_amdgcn_sched_barrier(0)
;     ...
;             PG8_LDA(At, 1, 1); PG8_STAGE(PG8_SB(1, 0), b3, voffB); PG8_STAGE(PG8_SB(1, 1), b3 + hstep, voffB); PG8_STAGE(PG8_SA(1, 0), a3, voffA);
;             PG8_WAIT_V(8); PG8_WAIT_L(0); PG8_BAR; PG8_MMA(1, 0, At, B0); PG8_MMA(1, 1, At, B1); PG8_BAR; PG8_SCHED;
	s_setprio 0
	s_add_i32 s3, s3, s20
	s_mov_b32 m0, s3
	ds_read_b128 v[186:189], v145 offset:49152
	ds_read_b128 v[190:193], v145 offset:50176
	ds_read_b128 v[194:197], v145 offset:51200
	ds_read_b128 v[198:201], v145 offset:52224
	ds_read_b128 v[202:205], v145 offset:53248
	ds_read_b128 v[206:209], v145 offset:54272
	ds_read_b128 v[210:213], v145 offset:55296
	ds_read_b128 v[214:217], v145 offset:56320
	s_add_u32 s100, s90, s16
	s_addc_u32 s101, s91, s17
	global_load_lds_dwordx4 v132, s[100:101]
	s_add_i32 m0, s3, 0x2000
	s_add_u32 s90, s90, 0x80080
	v_lshl_add_u64 v[166:167], v[218:219], 0, s[16:17]
	s_addc_u32 s91, s91, 0
	s_add_i32 s3, s12, s20
	global_load_lds_dwordx4 v[166:167], off
	s_mov_b32 m0, s3
	s_nop 0
	global_load_lds_dwordx4 v132, s[90:91]
	s_add_i32 m0, s3, 0x2000
	s_nop 0
	global_load_lds_dwordx4 v128, s[90:91]
	v_lshl_add_u64 v[166:167], v[220:221], 0, s[16:17]
	s_mov_b32 m0, s59
	s_nop 0
	global_load_lds_dwordx4 v[166:167], off
	v_lshl_add_u64 v[166:167], v[222:223], 0, s[16:17]
	s_mov_b32 m0, s8
	s_nop 0
	global_load_lds_dwordx4 v[166:167], off
	s_waitcnt vmcnt(8)
	s_waitcnt lgkmcnt(0)
	s_setprio 1
	s_barrier
	v_mfma_f32_16x16x32_bf16 v[60:63], v[146:149], v[186:189], v[60:63]
	v_mfma_f32_16x16x32_bf16 v[60:63], v[150:153], v[190:193], v[60:63]
	v_mfma_f32_16x16x32_bf16 v[52:55], v[146:149], v[194:197], v[52:55]
	v_mfma_f32_16x16x32_bf16 v[52:55], v[150:153], v[198:201], v[52:55]
	v_mfma_f32_16x16x32_bf16 v[36:39], v[146:149], v[202:205], v[36:39]
	v_mfma_f32_16x16x32_bf16 v[36:39], v[150:153], v[206:209], v[36:39]
	v_mfma_f32_16x16x32_bf16 v[20:23], v[146:149], v[210:213], v[20:23]
	v_mfma_f32_16x16x32_bf16 v[20:23], v[150:153], v[214:217], v[20:23]
	v_mfma_f32_16x16x32_bf16 v[56:59], v[154:157], v[186:189], v[56:59]
	v_mfma_f32_16x16x32_bf16 v[56:59], v[158:161], v[190:193], v[56:59]
	v_mfma_f32_16x16x32_bf16 v[48:51], v[154:157], v[194:197], v[48:51]
	v_mfma_f32_16x16x32_bf16 v[48:51], v[158:161], v[198:201], v[48:51]
	v_mfma_f32_16x16x32_bf16 v[32:35], v[154:157], v[202:205], v[32:35]
	v_mfma_f32_16x16x32_bf16 v[32:35], v[158:161], v[206:209], v[32:35]
	v_mfma_f32_16x16x32_bf16 v[16:19], v[154:157], v[210:213], v[16:19]
	v_mfma_f32_16x16x32_bf16 v[16:19], v[158:161], v[214:217], v[16:19]
	v_mfma_f32_16x16x32_bf16 v[44:47], v[162:165], v[186:189], v[44:47]
	v_mfma_f32_16x16x32_bf16 v[44:47], v[170:173], v[190:193], v[44:47]
	v_mfma_f32_16x16x32_bf16 v[28:31], v[162:165], v[194:197], v[28:31]
	v_mfma_f32_16x16x32_bf16 v[28:31], v[170:173], v[198:201], v[28:31]
	v_mfma_f32_16x16x32_bf16 v[12:15], v[162:165], v[202:205], v[12:15]
	v_mfma_f32_16x16x32_bf16 v[12:15], v[170:173], v[206:209], v[12:15]
	v_mfma_f32_16x16x32_bf16 v[4:7], v[162:165], v[210:213], v[4:7]
	v_mfma_f32_16x16x32_bf16 v[4:7], v[170:173], v[214:217], v[4:7]
	v_mfma_f32_16x16x32_bf16 v[40:43], v[178:181], v[186:189], v[40:43]
	v_mfma_f32_16x16x32_bf16 v[40:43], v[182:185], v[190:193], v[40:43]
	v_mfma_f32_16x16x32_bf16 v[24:27], v[178:181], v[194:197], v[24:27]
	v_mfma_f32_16x16x32_bf16 v[24:27], v[182:185], v[198:201], v[24:27]
	v_mfma_f32_16x16x32_bf16 v[8:11], v[178:181], v[202:205], v[8:11]
	v_mfma_f32_16x16x32_bf16 v[8:11], v[182:185], v[206:209], v[8:11]
	v_mfma_f32_16x16x32_bf16 v[0:3], v[178:181], v[210:213], v[0:3]
	v_mfma_f32_16x16x32_bf16 v[0:3], v[182:185], v[214:217], v[0:3]
	s_barrier
	s_setprio 0
	s_add_i32 s2, s2, 2
	s_add_u32 s88, s88, 0x100
	s_addc_u32 s89, s89, 0
	s_add_u32 s42, s42, 0x100
	s_addc_u32 s43, s43, 0
	s_cmp_gt_u32 s2, 29

; #define PG8_STAGE(bufoff, gbase, voff) do { _Pragma("unroll") for (int _i = 0; _i < 2; ++_i) \
;         __builtin_amdgcn_global_load_lds((const unsigned*)((const char*)(gbase) + (voff)[_i]), (PG8_LAS unsigned*)(lds + (bufoff) + ldsw + _i * 8192), 16, 0, 0); } while (0)
; #define PG8_LDA(dst, b, h) do { _Pragma("unroll") for (int m = 0; m < 4; ++m) _Pragma("unroll") for (int k = 0; k < 2; ++k) dst[m][k] = *(const PG8_LAS bf16x8*)(lds + PG8_SA(b, h) + aoff + m * 2048 + k * 1024); } while (0)
; #define PG8_LDB(dst, b, h) do { _Pragma("unroll") for (int n = 0; n < 2; ++n) _Pragma("unroll") for (int k = 0; k < 2; ++k) dst[n][k] = *(const PG8_LAS bf16x8*)(lds + PG8_SB(b, h) + boff + n * 2048 + k * 1024); } while (0)
; #define PG8_MMA(ai, bj, At, Bt) do { __builtin_amdgcn_s_setprio(1); _Pragma("unroll") for (int m = 0; m < 4; ++m) _Pragma("unroll") for (int n = 0; n < 2; ++n) _Pragma("unroll") for (int k = 0; k < 2; ++k) \
;         acc[ai][bj][m][n] = __builtin_amdgcn_mfma_f32_16x16x32_bf16(Bt[n][k], At[m][k], acc[ai][bj][m][n], 0, 0, 0); __builtin_amdgcn_s_setprio(0); } while (0)
; #define PG8_BAR __builtin_amdgcn_s_barrier()
;     ...
;         const char* nA = has_next ? (const char*)g.A + (size_t)nxt.pm * tstep : cA; const char* nB = has_next ? (const char*)g.Bt + (size_t)nxt.pn * tstep : cB;
;         for (int t = 0; t < nt; t += 2) {
;             if constexpr (Epi::MIDK) { if (t == nt / 2) E.midk(acc, cur, wr, wc, fr, fq); }
;             const bool last = (t == nt - 2);
;             const char* a1 = PG8_KADV(cA, (size_t)(t + 1) * kstep);
;             const char* a2 = last ? nA : PG8_KADV(cA, (size_t)(t + 2) * kstep); const char* b2 = last ? nB : PG8_KADV(cB, (size_t)(t + 2) * kstep);
;             const char* a3 = PG8_KADV(a2, kstep); const char* b3 = PG8_KADV(b2, kstep);
;             if (last && has_next) S.a_ready(nxt);
;             if constexpr (SP2) {
;             PG8_LDB(B0, 0, 0); PG8_LDB(B1, 0, 1); PG8_SCHED; PG8_LDA(At, 0, 0); PG8_STAGE(PG8_SA(1, 1), a1 + hstep, voffA);
;             PG8_WAIT_V(8); PG8_WAIT_L(0); PG8_BAR; PG8_MMA(0, 0, At, B0); PG8_MMA(0, 1, At, B1); PG8_BAR; PG8_SCHED;
;             PG8_LDA(At, 0, 1); PG8_STAGE(PG8_SB(0, 0), b2, voffB); PG8_STAGE(PG8_SB(0, 1), b2 + hstep, voffB); PG8_STAGE(PG8_SA(0, 0), a2, voffA);
;             PG8_WAIT_V(8); PG8_WAIT_L(0); PG8_BAR; PG8_MMA(1, 0, At, B0); PG8_MMA(1, 1, At, B1); PG8_BAR; PG8_SCHED;
.LBB0_625:
	s_ashr_i32 s81, s80, 31
	s_lshl_b64 s[2:3], s[80:81], 19
	s_add_u32 s82, s23, s2
	s_addc_u32 s83, s28, s3
	s_and_b64 s[2:3], s[76:77], exec
	s_cselect_b32 s75, s83, s87
	s_cselect_b32 s81, s82, s86
	s_ashr_i32 s79, s78, 31
	s_lshl_b64 s[2:3], s[78:79], 19
	s_add_u32 s84, s57, s2
	s_addc_u32 s85, s59, s3
	s_and_b64 s[2:3], s[76:77], exec
	s_cselect_b32 s79, s85, s89
	s_cselect_b32 vcc_lo, s84, s88
	s_add_u32 s86, s86, 0x40080
	s_addc_u32 s87, s87, 0
	s_add_u32 vcc_hi, s88, 0x100
	s_addc_u32 s2, s89, 0
	s_mov_b32 s3, -2
	s_add_u32 s12, s86, 0xfffc0080
	s_addc_u32 s13, s87, -1
	s_add_i32 s96, 0, 0x10000
	s_cmp_eq_u32 s3, 12
	s_cselect_b32 s91, s75, s13
	s_cselect_b32 s90, s81, s12
	v_add_u32_e32 v143, s96, v140
	s_cselect_b32 s89, s79, s2
	s_cselect_b32 s88, vcc_lo, vcc_hi
	s_add_i32 s31, 0, 0x14000
	ds_read_b128 v[144:147], v143
	ds_read_b128 v[148:151], v143 offset:1024
	ds_read_b128 v[152:155], v143 offset:2048
	ds_read_b128 v[156:159], v143 offset:3072
	v_add_u32_e32 v143, s31, v140
	ds_read_b128 v[160:163], v143
	ds_read_b128 v[164:167], v143 offset:1024
	ds_read_b128 v[170:173], v143 offset:2048
	ds_read_b128 v[178:181], v143 offset:3072
	s_add_i32 m0, s97, 0xc000
	ds_read_b128 v[182:185], v142
	ds_read_b128 v[186:189], v142 offset:1024
	ds_read_b128 v[190:193], v142 offset:2048
	ds_read_b128 v[194:197], v142 offset:3072
	ds_read_b128 v[198:201], v142 offset:4096
	ds_read_b128 v[202:205], v142 offset:5120
	ds_read_b128 v[206:209], v142 offset:6144
	ds_read_b128 v[210:213], v142 offset:7168
	global_load_lds_dwordx4 v136, s[86:87]
	s_add_i32 m0, s97, 0xe000
	s_nop 0
	global_load_lds_dwordx4 v138, s[86:87]
	s_waitcnt vmcnt(8)
	s_waitcnt lgkmcnt(0)
	s_setprio 1
	s_barrier
	v_mfma_f32_16x16x32_bf16 v[124:127], v[144:147], v[182:185], 0
	v_mfma_f32_16x16x32_bf16 v[124:127], v[148:151], v[186:189], v[124:127]
	v_mfma_f32_16x16x32_bf16 v[116:119], v[144:147], v[190:193], 0
	v_mfma_f32_16x16x32_bf16 v[116:119], v[148:151], v[194:197], v[116:119]
	v_mfma_f32_16x16x32_bf16 v[100:103], v[144:147], v[198:201], 0
	v_mfma_f32_16x16x32_bf16 v[100:103], v[148:151], v[202:205], v[100:103]
	v_mfma_f32_16x16x32_bf16 v[84:87], v[144:147], v[206:209], 0
	v_mfma_f32_16x16x32_bf16 v[84:87], v[148:151], v[210:213], v[84:87]
	v_mfma_f32_16x16x32_bf16 v[120:123], v[152:155], v[182:185], 0
	v_mfma_f32_16x16x32_bf16 v[120:123], v[156:159], v[186:189], v[120:123]
	v_mfma_f32_16x16x32_bf16 v[112:115], v[152:155], v[190:193], 0
	v_mfma_f32_16x16x32_bf16 v[112:115], v[156:159], v[194:197], v[112:115]
	v_mfma_f32_16x16x32_bf16 v[96:99], v[152:155], v[198:201], 0
	v_mfma_f32_16x16x32_bf16 v[96:99], v[156:159], v[202:205], v[96:99]
	v_mfma_f32_16x16x32_bf16 v[80:83], v[152:155], v[206:209], 0
	v_mfma_f32_16x16x32_bf16 v[80:83], v[156:159], v[210:213], v[80:83]
	v_mfma_f32_16x16x32_bf16 v[108:111], v[160:163], v[182:185], 0
	v_mfma_f32_16x16x32_bf16 v[108:111], v[164:167], v[186:189], v[108:111]
	v_mfma_f32_16x16x32_bf16 v[92:95], v[160:163], v[190:193], 0
	v_mfma_f32_16x16x32_bf16 v[92:95], v[164:167], v[194:197], v[92:95]
	v_mfma_f32_16x16x32_bf16 v[76:79], v[160:163], v[198:201], 0
	v_mfma_f32_16x16x32_bf16 v[76:79], v[164:167], v[202:205], v[76:79]
	v_mfma_f32_16x16x32_bf16 v[68:71], v[160:163], v[206:209], 0
	v_mfma_f32_16x16x32_bf16 v[68:71], v[164:167], v[210:213], v[68:71]
	v_mfma_f32_16x16x32_bf16 v[104:107], v[170:173], v[182:185], 0
	v_mfma_f32_16x16x32_bf16 v[104:107], v[178:181], v[186:189], v[104:107]
	v_mfma_f32_16x16x32_bf16 v[88:91], v[170:173], v[190:193], 0
	v_mfma_f32_16x16x32_bf16 v[88:91], v[178:181], v[194:197], v[88:91]
	v_mfma_f32_16x16x32_bf16 v[72:75], v[170:173], v[198:201], 0
	v_mfma_f32_16x16x32_bf16 v[72:75], v[178:181], v[202:205], v[72:75]
	v_mfma_f32_16x16x32_bf16 v[64:67], v[170:173], v[206:209], 0
	v_mfma_f32_16x16x32_bf16 v[64:67], v[178:181], v[210:213], v[64:67]
	s_barrier
	s_setprio 0
	s_add_i32 s12, s96, s93
	s_mov_b32 m0, s12
	ds_read_b128 v[182:185], v142 offset:16384
	ds_read_b128 v[186:189], v142 offset:17408
	ds_read_b128 v[190:193], v142 offset:18432
	ds_read_b128 v[194:197], v142 offset:19456
	ds_read_b128 v[198:201], v142 offset:20480
	ds_read_b128 v[202:205], v142 offset:21504
	ds_read_b128 v[206:209], v142 offset:22528
	ds_read_b128 v[210:213], v142 offset:23552
	global_load_lds_dwordx4 v130, s[88:89]
	s_add_i32 m0, s12, 0x2000
	s_add_u32 s12, s88, 0x40000
	s_addc_u32 s13, s89, 0
	s_add_i32 s31, s31, s93
	global_load_lds_dwordx4 v134, s[88:89]
	s_mov_b32 m0, s31
	s_nop 0
	global_load_lds_dwordx4 v130, s[12:13]
	s_add_i32 m0, s31, 0x2000
	s_nop 0
	global_load_lds_dwordx4 v134, s[12:13]
	s_mov_b32 m0, s97
	s_nop 0
	global_load_lds_dwordx4 v128, s[90:91]
	s_mov_b32 m0, s40
	s_nop 0
	global_load_lds_dwordx4 v132, s[90:91]
	s_waitcnt vmcnt(8)
	s_waitcnt lgkmcnt(0)
	s_setprio 1
	s_barrier
; #define PG8_STAGE(bufoff, gbase, voff) do { _Pragma("unroll") for (int _i = 0; _i < 2; ++_i) \
;         __builtin_amdgcn_global_load_lds((const unsigned*)((const char*)(gbase) + (voff)[_i]), (PG8_LAS unsigned*)(lds + (bufoff) + ldsw + _i * 8192), 16, 0, 0); } while (0)
; #define PG8_LDA(dst, b, h) do { _Pragma("unroll") for (int m = 0; m < 4; ++m) _Pragma("unroll") for (int k = 0; k < 2; ++k) dst[m][k] = *(const PG8_LAS bf16x8*)(lds + PG8_SA(b, h) + aoff + m * 2048 + k * 1024); } while (0)
; #define PG8_LDB(dst, b, h) do { _Pragma("unroll") for (int n = 0; n < 2; ++n) _Pragma("unroll") for (int k = 0; k < 2; ++k) dst[n][k] = *(const PG8_LAS bf16x8*)(lds + PG8_SB(b, h) + boff + n * 2048 + k * 1024); } while (0)
; #define PG8_MMA(ai, bj, At, Bt) do { __builtin_amdgcn_s_setprio(1); _Pragma("unroll") for (int m = 0; m < 4; ++m) _Pragma("unroll") for (int n = 0; n < 2; ++n) _Pragma("unroll") for (int k = 0; k < 2; ++k) \
;         acc[ai][bj][m][n] = __builtin_amdgcn_mfma_f32_16x16x32_bf16(Bt[n][k], At[m][k], acc[ai][bj][m][n], 0, 0, 0); __builtin_amdgcn_s_setprio(0); } while (0)
; #define PG8_WAIT_V(n) asm volatile("s_waitcnt vmcnt(" #n ")" ::: "memory")
; #define PG8_WAIT_L(n) asm volatile("s_waitcnt lgkmcnt(" #n ")" ::: "memory")
; #define PG8_BAR __builtin_amdgcn_s_barrier()
; #define PG8_SCHED __builtin_amdgcn_sched_barrier(0)
;     ...
;             PG8_WAIT_V(8); PG8_WAIT_L(0); PG8_BAR; PG8_MMA(1, 0, At, B0); PG8_MMA(1, 1, At, B1); PG8_BAR; PG8_SCHED;
;             PG8_LDB(B0, 1, 0); PG8_LDB(B1, 1, 1); PG8_SCHED; PG8_LDA(At, 1, 0); PG8_STAGE(PG8_SA(0, 1), a2 + hstep, voffA);
;             PG8_WAIT_V(8); PG8_WAIT_L(0); PG8_BAR; PG8_MMA(0, 0, At, B0); PG8_MMA(0, 1, At, B1); PG8_BAR; PG8_SCHED;
	v_mfma_f32_16x16x32_bf16 v[60:63], v[144:147], v[182:185], 0
	v_mfma_f32_16x16x32_bf16 v[60:63], v[148:151], v[186:189], v[60:63]
	v_mfma_f32_16x16x32_bf16 v[52:55], v[144:147], v[190:193], 0
	v_mfma_f32_16x16x32_bf16 v[52:55], v[148:151], v[194:197], v[52:55]
	v_mfma_f32_16x16x32_bf16 v[36:39], v[144:147], v[198:201], 0
	v_mfma_f32_16x16x32_bf16 v[36:39], v[148:151], v[202:205], v[36:39]
	v_mfma_f32_16x16x32_bf16 v[20:23], v[144:147], v[206:209], 0
	v_mfma_f32_16x16x32_bf16 v[20:23], v[148:151], v[210:213], v[20:23]
	v_mfma_f32_16x16x32_bf16 v[56:59], v[152:155], v[182:185], 0
	v_mfma_f32_16x16x32_bf16 v[56:59], v[156:159], v[186:189], v[56:59]
	v_mfma_f32_16x16x32_bf16 v[48:51], v[152:155], v[190:193], 0
	v_mfma_f32_16x16x32_bf16 v[48:51], v[156:159], v[194:197], v[48:51]
	v_mfma_f32_16x16x32_bf16 v[32:35], v[152:155], v[198:201], 0
	v_mfma_f32_16x16x32_bf16 v[32:35], v[156:159], v[202:205], v[32:35]
	v_mfma_f32_16x16x32_bf16 v[16:19], v[152:155], v[206:209], 0
	v_mfma_f32_16x16x32_bf16 v[16:19], v[156:159], v[210:213], v[16:19]
	v_mfma_f32_16x16x32_bf16 v[44:47], v[160:163], v[182:185], 0
	v_mfma_f32_16x16x32_bf16 v[44:47], v[164:167], v[186:189], v[44:47]
	v_mfma_f32_16x16x32_bf16 v[28:31], v[160:163], v[190:193], 0
	v_mfma_f32_16x16x32_bf16 v[28:31], v[164:167], v[194:197], v[28:31]
	v_mfma_f32_16x16x32_bf16 v[12:15], v[160:163], v[198:201], 0
	v_mfma_f32_16x16x32_bf16 v[12:15], v[164:167], v[202:205], v[12:15]
	v_mfma_f32_16x16x32_bf16 v[4:7], v[160:163], v[206:209], 0
	v_mfma_f32_16x16x32_bf16 v[4:7], v[164:167], v[210:213], v[4:7]
	v_mfma_f32_16x16x32_bf16 v[40:43], v[170:173], v[182:185], 0
	v_mfma_f32_16x16x32_bf16 v[40:43], v[178:181], v[186:189], v[40:43]
	v_mfma_f32_16x16x32_bf16 v[24:27], v[170:173], v[190:193], 0
	v_mfma_f32_16x16x32_bf16 v[24:27], v[178:181], v[194:197], v[24:27]
	v_mfma_f32_16x16x32_bf16 v[8:11], v[170:173], v[198:201], 0
	v_mfma_f32_16x16x32_bf16 v[8:11], v[178:181], v[202:205], v[8:11]
	v_mfma_f32_16x16x32_bf16 v[0:3], v[170:173], v[206:209], 0
	v_mfma_f32_16x16x32_bf16 v[0:3], v[178:181], v[210:213], v[0:3]
	s_barrier
	s_setprio 0
	s_add_i32 s31, 0, 0x18000
	v_add_u32_e32 v143, s31, v140
	s_add_i32 s96, 0, 0x1c000
	ds_read_b128 v[144:147], v143
	ds_read_b128 v[148:151], v143 offset:1024
	ds_read_b128 v[152:155], v143 offset:2048
	ds_read_b128 v[156:159], v143 offset:3072
	v_add_u32_e32 v143, s96, v140
	ds_read_b128 v[160:163], v143
	ds_read_b128 v[164:167], v143 offset:1024
	ds_read_b128 v[170:173], v143 offset:2048
	ds_read_b128 v[178:181], v143 offset:3072
	s_add_u32 s12, s90, 0x40000
	s_addc_u32 s13, s91, 0
	s_mov_b32 m0, s33
	ds_read_b128 v[182:185], v142 offset:32768
	ds_read_b128 v[186:189], v142 offset:33792
	ds_read_b128 v[190:193], v142 offset:34816
	ds_read_b128 v[194:197], v142 offset:35840
	ds_read_b128 v[198:201], v142 offset:36864
	ds_read_b128 v[202:205], v142 offset:37888
	ds_read_b128 v[206:209], v142 offset:38912
	ds_read_b128 v[210:213], v142 offset:39936
	global_load_lds_dwordx4 v128, s[12:13]
	s_mov_b32 m0, s30
	s_nop 0
	global_load_lds_dwordx4 v132, s[12:13]
	s_waitcnt vmcnt(8)
	s_waitcnt lgkmcnt(0)
	s_setprio 1
	s_barrier
	v_mfma_f32_16x16x32_bf16 v[124:127], v[144:147], v[182:185], v[124:127]
	v_mfma_f32_16x16x32_bf16 v[124:127], v[148:151], v[186:189], v[124:127]
	v_mfma_f32_16x16x32_bf16 v[116:119], v[144:147], v[190:193], v[116:119]
	v_mfma_f32_16x16x32_bf16 v[116:119], v[148:151], v[194:197], v[116:119]
	v_mfma_f32_16x16x32_bf16 v[100:103], v[144:147], v[198:201], v[100:103]
	v_mfma_f32_16x16x32_bf16 v[100:103], v[148:151], v[202:205], v[100:103]
	v_mfma_f32_16x16x32_bf16 v[84:87], v[144:147], v[206:209], v[84:87]
	v_mfma_f32_16x16x32_bf16 v[84:87], v[148:151], v[210:213], v[84:87]
	v_mfma_f32_16x16x32_bf16 v[120:123], v[152:155], v[182:185], v[120:123]
	v_mfma_f32_16x16x32_bf16 v[120:123], v[156:159], v[186:189], v[120:123]
	v_mfma_f32_16x16x32_bf16 v[112:115], v[152:155], v[190:193], v[112:115]
	v_mfma_f32_16x16x32_bf16 v[112:115], v[156:159], v[194:197], v[112:115]
	v_mfma_f32_16x16x32_bf16 v[96:99], v[152:155], v[198:201], v[96:99]
	v_mfma_f32_16x16x32_bf16 v[96:99], v[156:159], v[202:205], v[96:99]
	v_mfma_f32_16x16x32_bf16 v[80:83], v[152:155], v[206:209], v[80:83]
	v_mfma_f32_16x16x32_bf16 v[80:83], v[156:159], v[210:213], v[80:83]
	v_mfma_f32_16x16x32_bf16 v[108:111], v[160:163], v[182:185], v[108:111]
	v_mfma_f32_16x16x32_bf16 v[108:111], v[164:167], v[186:189], v[108:111]
	v_mfma_f32_16x16x32_bf16 v[92:95], v[160:163], v[190:193], v[92:95]
	v_mfma_f32_16x16x32_bf16 v[92:95], v[164:167], v[194:197], v[92:95]
	v_mfma_f32_16x16x32_bf16 v[76:79], v[160:163], v[198:201], v[76:79]
	v_mfma_f32_16x16x32_bf16 v[76:79], v[164:167], v[202:205], v[76:79]
	v_mfma_f32_16x16x32_bf16 v[68:71], v[160:163], v[206:209], v[68:71]
	v_mfma_f32_16x16x32_bf16 v[68:71], v[164:167], v[210:213], v[68:71]
	v_mfma_f32_16x16x32_bf16 v[104:107], v[170:173], v[182:185], v[104:107]
	v_mfma_f32_16x16x32_bf16 v[104:107], v[178:181], v[186:189], v[104:107]
	v_mfma_f32_16x16x32_bf16 v[88:91], v[170:173], v[190:193], v[88:91]
	v_mfma_f32_16x16x32_bf16 v[88:91], v[178:181], v[194:197], v[88:91]
	v_mfma_f32_16x16x32_bf16 v[72:75], v[170:173], v[198:201], v[72:75]
	v_mfma_f32_16x16x32_bf16 v[72:75], v[178:181], v[202:205], v[72:75]
	v_mfma_f32_16x16x32_bf16 v[64:67], v[170:173], v[206:209], v[64:67]
	v_mfma_f32_16x16x32_bf16 v[64:67], v[178:181], v[210:213], v[64:67]
	s_barrier
; #define PG8_STAGE(bufoff, gbase, voff) do { _Pragma("unroll") for (int _i = 0; _i < 2; ++_i) \
;         __builtin_amdgcn_global_load_lds((const unsigned*)((const char*)(gbase) + (voff)[_i]), (PG8_LAS unsigned*)(lds + (bufoff) + ldsw + _i * 8192), 16, 0, 0); } while (0)
; #define PG8_LDA(dst, b, h) do { _Pragma("unroll") for (int m = 0; m < 4; ++m) _Pragma("unroll") for (int k = 0; k < 2; ++k) dst[m][k] = *(const PG8_LAS bf16x8*)(lds + PG8_SA(b, h) + aoff + m * 2048 + k * 1024); } while (0)
; #define PG8_MMA(ai, bj, At, Bt) do { __builtin_amdgcn_s_setprio(1); _Pragma("unroll") for (int m = 0; m < 4; ++m) _Pragma("unroll") for (int n = 0; n < 2; ++n) _Pragma("unroll") for (int k = 0; k < 2; ++k) \
;         acc[ai][bj][m][n] = __builtin_amdgcn_mfma_f32_16x16x32_bf16(Bt[n][k], At[m][k], acc[ai][bj][m][n], 0, 0, 0); __builtin_amdgcn_s_setprio(0); } while (0)
; #define PG8_WAIT_V(n) asm volatile("s_waitcnt vmcnt(" #n ")" ::: "memory")
; #define PG8_WAIT_L(n) asm volatile("s_waitcnt lgkmcnt(" #n ")" ::: "memory")
; #define PG8_BAR __builtin_amdgcn_s_barrier()
; #define PG8_SCHED __builtin_amdgcn_sched_barrier(0)
;     ...
;             PG8_LDA(At, 1, 1); PG8_STAGE(PG8_SB(1, 0), b3, voffB); PG8_STAGE(PG8_SB(1, 1), b3 + hstep, voffB); PG8_STAGE(PG8_SA(1, 0), a3, voffA);
;             PG8_WAIT_V(8); PG8_WAIT_L(0); PG8_BAR; PG8_MMA(1, 0, At, B0); PG8_MMA(1, 1, At, B1); PG8_BAR; PG8_SCHED;
	s_setprio 0
	s_add_i32 s12, s31, s93
	s_mov_b32 m0, s12
	ds_read_b128 v[182:185], v142 offset:49152
	ds_read_b128 v[186:189], v142 offset:50176
	ds_read_b128 v[190:193], v142 offset:51200
	ds_read_b128 v[194:197], v142 offset:52224
	ds_read_b128 v[198:201], v142 offset:53248
	ds_read_b128 v[202:205], v142 offset:54272
	ds_read_b128 v[206:209], v142 offset:55296
	ds_read_b128 v[210:213], v142 offset:56320
	s_add_u32 s100, s88, s16
	s_addc_u32 s101, s89, s17
	global_load_lds_dwordx4 v130, s[100:101]
	s_add_i32 m0, s12, 0x2000
	s_add_u32 s12, s88, 0x40080
	s_addc_u32 s13, s89, 0
	s_add_i32 s31, s96, s93
	global_load_lds_dwordx4 v134, s[100:101]
	s_mov_b32 m0, s31
	s_nop 0
	global_load_lds_dwordx4 v130, s[12:13]
	s_add_i32 m0, s31, 0x2000
	s_nop 0
	global_load_lds_dwordx4 v134, s[12:13]
	s_mov_b32 m0, s14
	s_nop 0
	s_add_u32 s100, s90, s16
	s_addc_u32 s101, s91, s17
	global_load_lds_dwordx4 v128, s[100:101]
	s_mov_b32 m0, s15
	s_nop 0
	global_load_lds_dwordx4 v132, s[100:101]
	s_waitcnt vmcnt(8)
	s_waitcnt lgkmcnt(0)
	s_setprio 1
	s_barrier
	v_mfma_f32_16x16x32_bf16 v[60:63], v[144:147], v[182:185], v[60:63]
	v_mfma_f32_16x16x32_bf16 v[60:63], v[148:151], v[186:189], v[60:63]
	v_mfma_f32_16x16x32_bf16 v[52:55], v[144:147], v[190:193], v[52:55]
	v_mfma_f32_16x16x32_bf16 v[52:55], v[148:151], v[194:197], v[52:55]
	v_mfma_f32_16x16x32_bf16 v[36:39], v[144:147], v[198:201], v[36:39]
	v_mfma_f32_16x16x32_bf16 v[36:39], v[148:151], v[202:205], v[36:39]
	v_mfma_f32_16x16x32_bf16 v[20:23], v[144:147], v[206:209], v[20:23]
	v_mfma_f32_16x16x32_bf16 v[20:23], v[148:151], v[210:213], v[20:23]
	v_mfma_f32_16x16x32_bf16 v[56:59], v[152:155], v[182:185], v[56:59]
	v_mfma_f32_16x16x32_bf16 v[56:59], v[156:159], v[186:189], v[56:59]
	v_mfma_f32_16x16x32_bf16 v[48:51], v[152:155], v[190:193], v[48:51]
	v_mfma_f32_16x16x32_bf16 v[48:51], v[156:159], v[194:197], v[48:51]
	v_mfma_f32_16x16x32_bf16 v[32:35], v[152:155], v[198:201], v[32:35]
	v_mfma_f32_16x16x32_bf16 v[32:35], v[156:159], v[202:205], v[32:35]
	v_mfma_f32_16x16x32_bf16 v[16:19], v[152:155], v[206:209], v[16:19]
	v_mfma_f32_16x16x32_bf16 v[16:19], v[156:159], v[210:213], v[16:19]
	v_mfma_f32_16x16x32_bf16 v[44:47], v[160:163], v[182:185], v[44:47]
	v_mfma_f32_16x16x32_bf16 v[44:47], v[164:167], v[186:189], v[44:47]
	v_mfma_f32_16x16x32_bf16 v[28:31], v[160:163], v[190:193], v[28:31]
	v_mfma_f32_16x16x32_bf16 v[28:31], v[164:167], v[194:197], v[28:31]
	v_mfma_f32_16x16x32_bf16 v[12:15], v[160:163], v[198:201], v[12:15]
	v_mfma_f32_16x16x32_bf16 v[12:15], v[164:167], v[202:205], v[12:15]
	v_mfma_f32_16x16x32_bf16 v[4:7], v[160:163], v[206:209], v[4:7]
	v_mfma_f32_16x16x32_bf16 v[4:7], v[164:167], v[210:213], v[4:7]
	v_mfma_f32_16x16x32_bf16 v[40:43], v[170:173], v[182:185], v[40:43]
	v_mfma_f32_16x16x32_bf16 v[40:43], v[178:181], v[186:189], v[40:43]
	v_mfma_f32_16x16x32_bf16 v[24:27], v[170:173], v[190:193], v[24:27]
	v_mfma_f32_16x16x32_bf16 v[24:27], v[178:181], v[194:197], v[24:27]
	v_mfma_f32_16x16x32_bf16 v[8:11], v[170:173], v[198:201], v[8:11]
	v_mfma_f32_16x16x32_bf16 v[8:11], v[178:181], v[202:205], v[8:11]
	v_mfma_f32_16x16x32_bf16 v[0:3], v[170:173], v[206:209], v[0:3]
	v_mfma_f32_16x16x32_bf16 v[0:3], v[178:181], v[210:213], v[0:3]
	s_barrier
	s_setprio 0
	s_add_i32 s3, s3, 2
	s_add_u32 s86, s86, 0x100
	s_addc_u32 s87, s87, 0
	s_add_u32 vcc_hi, vcc_hi, 0x100
	s_addc_u32 s2, s2, 0
	s_cmp_gt_u32 s3, 13

; #define PG8_STAGE(bufoff, gbase, voff) do { _Pragma("unroll") for (int _i = 0; _i < 2; ++_i) \
;         __builtin_amdgcn_global_load_lds((const unsigned*)((const char*)(gbase) + (voff)[_i]), (PG8_LAS unsigned*)(lds + (bufoff) + ldsw + _i * 8192), 16, 0, 0); } while (0)
; #define PG8_LDA(dst, b, h) do { _Pragma("unroll") for (int m = 0; m < 4; ++m) _Pragma("unroll") for (int k = 0; k < 2; ++k) dst[m][k] = *(const PG8_LAS bf16x8*)(lds + PG8_SA(b, h) + aoff + m * 2048 + k * 1024); } while (0)
; #define PG8_LDB(dst, b, h) do { _Pragma("unroll") for (int n = 0; n < 2; ++n) _Pragma("unroll") for (int k = 0; k < 2; ++k) dst[n][k] = *(const PG8_LAS bf16x8*)(lds + PG8_SB(b, h) + boff + n * 2048 + k * 1024); } while (0)
; #define PG8_MMA(ai, bj, At, Bt) do { __builtin_amdgcn_s_setprio(1); _Pragma("unroll") for (int m = 0; m < 4; ++m) _Pragma("unroll") for (int n = 0; n < 2; ++n) _Pragma("unroll") for (int k = 0; k < 2; ++k) \
;         acc[ai][bj][m][n] = __builtin_amdgcn_mfma_f32_16x16x32_bf16(Bt[n][k], At[m][k], acc[ai][bj][m][n], 0, 0, 0); __builtin_amdgcn_s_setprio(0); } while (0)
; #define PG8_BAR __builtin_amdgcn_s_barrier()
;     ...
;         const char* nA = has_next ? (const char*)g.A + (size_t)nxt.pm * tstep : cA; const char* nB = has_next ? (const char*)g.Bt + (size_t)nxt.pn * tstep : cB;
;         for (int t = 0; t < nt; t += 2) {
;             if constexpr (Epi::MIDK) { if (t == nt / 2) E.midk(acc, cur, wr, wc, fr, fq); }
;             const bool last = (t == nt - 2);
;             const char* a1 = PG8_KADV(cA, (size_t)(t + 1) * kstep);
;             const char* a2 = last ? nA : PG8_KADV(cA, (size_t)(t + 2) * kstep); const char* b2 = last ? nB : PG8_KADV(cB, (size_t)(t + 2) * kstep);
;             const char* a3 = PG8_KADV(a2, kstep); const char* b3 = PG8_KADV(b2, kstep);
;             if (last && has_next) S.a_ready(nxt);
;             if constexpr (SP2) {
;             PG8_LDB(B0, 0, 0); PG8_LDB(B1, 0, 1); PG8_SCHED; PG8_LDA(At, 0, 0); PG8_STAGE(PG8_SA(1, 1), a1 + hstep, voffA);
;             PG8_WAIT_V(8); PG8_WAIT_L(0); PG8_BAR; PG8_MMA(0, 0, At, B0); PG8_MMA(0, 1, At, B1); PG8_BAR; PG8_SCHED;
;             PG8_LDA(At, 0, 1); PG8_STAGE(PG8_SB(0, 0), b2, voffB); PG8_STAGE(PG8_SB(0, 1), b2 + hstep, voffB); PG8_STAGE(PG8_SA(0, 0), a2, voffA);
;             PG8_WAIT_V(8); PG8_WAIT_L(0); PG8_BAR; PG8_MMA(1, 0, At, B0); PG8_MMA(1, 1, At, B1); PG8_BAR; PG8_SCHED;
.LBB0_855:
	s_ashr_i32 s75, s74, 31
	s_lshl_b64 s[2:3], s[74:75], 20
	s_add_u32 s76, s68, s2
	s_addc_u32 s77, s69, s3
	s_and_b64 s[2:3], s[4:5], exec
	s_cselect_b32 s15, s77, s83
	s_cselect_b32 s23, s76, s82
	s_ashr_i32 s73, s72, 31
	s_lshl_b64 s[2:3], s[72:73], 20
	s_add_u32 s78, s0, s2
	s_addc_u32 s79, s1, s3
	s_and_b64 s[2:3], s[4:5], exec
	s_cselect_b32 s25, s79, s85
	s_cselect_b32 s28, s78, s84
	s_add_u32 s82, s82, 0x80080
	s_addc_u32 s83, s83, 0
	s_add_u32 s30, s84, 0x100
	s_addc_u32 s2, s85, 0
	s_mov_b32 s3, -2
	s_add_u32 s12, s82, 0xfff80080
	s_addc_u32 s13, s83, -1
	s_add_i32 s31, 0, 0x10000
	s_cmp_eq_u32 s3, 28
	s_cselect_b32 s87, s15, s13
	s_cselect_b32 s86, s23, s12
	s_cselect_b32 s85, s25, s2
	s_cselect_b32 s84, s28, s30
	s_add_i32 s33, 0, 0x14000
	v_add_u32_e32 v140, s31, v166
	v_add_u32_e32 v164, s33, v166
	ds_read_b128 v[128:131], v140
	ds_read_b128 v[132:135], v140 offset:1024
	ds_read_b128 v[136:139], v140 offset:2048
	ds_read_b128 v[140:143], v140 offset:3072
	ds_read_b128 v[144:147], v164
	ds_read_b128 v[148:151], v164 offset:1024
	ds_read_b128 v[170:173], v164 offset:2048
	ds_read_b128 v[178:181], v164 offset:3072
	s_add_i32 m0, s9, 0xc000
	ds_read_b128 v[184:187], v183
	ds_read_b128 v[188:191], v183 offset:1024
	ds_read_b128 v[192:195], v183 offset:2048
	ds_read_b128 v[196:199], v183 offset:3072
	ds_read_b128 v[200:203], v183 offset:4096
	ds_read_b128 v[204:207], v183 offset:5120
	ds_read_b128 v[208:211], v183 offset:6144
	ds_read_b128 v[212:215], v183 offset:7168
	global_load_lds_dwordx4 v160, s[82:83]
	s_add_i32 m0, s9, 0xe000
	s_nop 0
	global_load_lds_dwordx4 v162, s[82:83]
	s_waitcnt vmcnt(8)
	s_waitcnt lgkmcnt(0)
	s_setprio 1
	s_barrier
	v_mfma_f32_16x16x32_bf16 v[124:127], v[128:131], v[184:187], 0
	v_mfma_f32_16x16x32_bf16 v[124:127], v[132:135], v[188:191], v[124:127]
	v_mfma_f32_16x16x32_bf16 v[112:115], v[128:131], v[192:195], 0
	v_mfma_f32_16x16x32_bf16 v[112:115], v[132:135], v[196:199], v[112:115]
	v_mfma_f32_16x16x32_bf16 v[92:95], v[128:131], v[200:203], 0
	v_mfma_f32_16x16x32_bf16 v[92:95], v[132:135], v[204:207], v[92:95]
	v_mfma_f32_16x16x32_bf16 v[80:83], v[128:131], v[208:211], 0
	v_mfma_f32_16x16x32_bf16 v[80:83], v[132:135], v[212:215], v[80:83]
	v_mfma_f32_16x16x32_bf16 v[120:123], v[136:139], v[184:187], 0
	v_mfma_f32_16x16x32_bf16 v[120:123], v[140:143], v[188:191], v[120:123]
	v_mfma_f32_16x16x32_bf16 v[104:107], v[136:139], v[192:195], 0
	v_mfma_f32_16x16x32_bf16 v[104:107], v[140:143], v[196:199], v[104:107]
	v_mfma_f32_16x16x32_bf16 v[88:91], v[136:139], v[200:203], 0
	v_mfma_f32_16x16x32_bf16 v[88:91], v[140:143], v[204:207], v[88:91]
	v_mfma_f32_16x16x32_bf16 v[72:75], v[136:139], v[208:211], 0
	v_mfma_f32_16x16x32_bf16 v[72:75], v[140:143], v[212:215], v[72:75]
	v_mfma_f32_16x16x32_bf16 v[116:119], v[144:147], v[184:187], 0
	v_mfma_f32_16x16x32_bf16 v[116:119], v[148:151], v[188:191], v[116:119]
	v_mfma_f32_16x16x32_bf16 v[100:103], v[144:147], v[192:195], 0
	v_mfma_f32_16x16x32_bf16 v[100:103], v[148:151], v[196:199], v[100:103]
	v_mfma_f32_16x16x32_bf16 v[84:87], v[144:147], v[200:203], 0
	v_mfma_f32_16x16x32_bf16 v[84:87], v[148:151], v[204:207], v[84:87]
	v_mfma_f32_16x16x32_bf16 v[68:71], v[144:147], v[208:211], 0
	v_mfma_f32_16x16x32_bf16 v[68:71], v[148:151], v[212:215], v[68:71]
	v_mfma_f32_16x16x32_bf16 v[108:111], v[170:173], v[184:187], 0
	v_mfma_f32_16x16x32_bf16 v[108:111], v[178:181], v[188:191], v[108:111]
	v_mfma_f32_16x16x32_bf16 v[96:99], v[170:173], v[192:195], 0
	v_mfma_f32_16x16x32_bf16 v[96:99], v[178:181], v[196:199], v[96:99]
	v_mfma_f32_16x16x32_bf16 v[76:79], v[170:173], v[200:203], 0
	v_mfma_f32_16x16x32_bf16 v[76:79], v[178:181], v[204:207], v[76:79]
	v_mfma_f32_16x16x32_bf16 v[64:67], v[170:173], v[208:211], 0
	v_mfma_f32_16x16x32_bf16 v[64:67], v[178:181], v[212:215], v[64:67]
	s_barrier
	s_setprio 0
	s_add_i32 s12, s31, s8
	s_mov_b32 m0, s12
	ds_read_b128 v[184:187], v183 offset:16384
	ds_read_b128 v[188:191], v183 offset:17408
	ds_read_b128 v[192:195], v183 offset:18432
	ds_read_b128 v[196:199], v183 offset:19456
	ds_read_b128 v[200:203], v183 offset:20480
	ds_read_b128 v[204:207], v183 offset:21504
	ds_read_b128 v[208:211], v183 offset:22528
	ds_read_b128 v[212:215], v183 offset:23552
	global_load_lds_dwordx4 v154, s[84:85]
	s_add_i32 m0, s12, 0x2000
	s_add_u32 s12, s84, 0x80000
	s_addc_u32 s13, s85, 0
	s_add_i32 s31, s33, s8
	global_load_lds_dwordx4 v158, s[84:85]
	s_mov_b32 m0, s31
	s_nop 0
	global_load_lds_dwordx4 v154, s[12:13]
	s_add_i32 m0, s31, 0x2000
	s_nop 0
	global_load_lds_dwordx4 v158, s[12:13]
	s_mov_b32 m0, s9
	s_nop 0
	global_load_lds_dwordx4 v152, s[86:87]
	s_mov_b32 m0, s10
	s_nop 0
	global_load_lds_dwordx4 v156, s[86:87]
	s_waitcnt vmcnt(8)
	s_waitcnt lgkmcnt(0)
	s_setprio 1
	s_barrier
; #define PG8_STAGE(bufoff, gbase, voff) do { _Pragma("unroll") for (int _i = 0; _i < 2; ++_i) \
;         __builtin_amdgcn_global_load_lds((const unsigned*)((const char*)(gbase) + (voff)[_i]), (PG8_LAS unsigned*)(lds + (bufoff) + ldsw + _i * 8192), 16, 0, 0); } while (0)
; #define PG8_LDA(dst, b, h) do { _Pragma("unroll") for (int m = 0; m < 4; ++m) _Pragma("unroll") for (int k = 0; k < 2; ++k) dst[m][k] = *(const PG8_LAS bf16x8*)(lds + PG8_SA(b, h) + aoff + m * 2048 + k * 1024); } while (0)
; #define PG8_LDB(dst, b, h) do { _Pragma("unroll") for (int n = 0; n < 2; ++n) _Pragma("unroll") for (int k = 0; k < 2; ++k) dst[n][k] = *(const PG8_LAS bf16x8*)(lds + PG8_SB(b, h) + boff + n * 2048 + k * 1024); } while (0)
; #define PG8_MMA(ai, bj, At, Bt) do { __builtin_amdgcn_s_setprio(1); _Pragma("unroll") for (int m = 0; m < 4; ++m) _Pragma("unroll") for (int n = 0; n < 2; ++n) _Pragma("unroll") for (int k = 0; k < 2; ++k) \
;         acc[ai][bj][m][n] = __builtin_amdgcn_mfma_f32_16x16x32_bf16(Bt[n][k], At[m][k], acc[ai][bj][m][n], 0, 0, 0); __builtin_amdgcn_s_setprio(0); } while (0)
; #define PG8_WAIT_V(n) asm volatile("s_waitcnt vmcnt(" #n ")" ::: "memory")
; #define PG8_WAIT_L(n) asm volatile("s_waitcnt lgkmcnt(" #n ")" ::: "memory")
; #define PG8_BAR __builtin_amdgcn_s_barrier()
; #define PG8_SCHED __builtin_amdgcn_sched_barrier(0)
;     ...
;             PG8_WAIT_V(8); PG8_WAIT_L(0); PG8_BAR; PG8_MMA(1, 0, At, B0); PG8_MMA(1, 1, At, B1); PG8_BAR; PG8_SCHED;
;             PG8_LDB(B0, 1, 0); PG8_LDB(B1, 1, 1); PG8_SCHED; PG8_LDA(At, 1, 0); PG8_STAGE(PG8_SA(0, 1), a2 + hstep, voffA);
;             PG8_WAIT_V(8); PG8_WAIT_L(0); PG8_BAR; PG8_MMA(0, 0, At, B0); PG8_MMA(0, 1, At, B1); PG8_BAR; PG8_SCHED;
	v_mfma_f32_16x16x32_bf16 v[60:63], v[128:131], v[184:187], 0
	v_mfma_f32_16x16x32_bf16 v[60:63], v[132:135], v[188:191], v[60:63]
	v_mfma_f32_16x16x32_bf16 v[48:51], v[128:131], v[192:195], 0
	v_mfma_f32_16x16x32_bf16 v[48:51], v[132:135], v[196:199], v[48:51]
	v_mfma_f32_16x16x32_bf16 v[28:31], v[128:131], v[200:203], 0
	v_mfma_f32_16x16x32_bf16 v[28:31], v[132:135], v[204:207], v[28:31]
	v_mfma_f32_16x16x32_bf16 v[16:19], v[128:131], v[208:211], 0
	v_mfma_f32_16x16x32_bf16 v[16:19], v[132:135], v[212:215], v[16:19]
	v_mfma_f32_16x16x32_bf16 v[56:59], v[136:139], v[184:187], 0
	v_mfma_f32_16x16x32_bf16 v[56:59], v[140:143], v[188:191], v[56:59]
	v_mfma_f32_16x16x32_bf16 v[40:43], v[136:139], v[192:195], 0
	v_mfma_f32_16x16x32_bf16 v[40:43], v[140:143], v[196:199], v[40:43]
	v_mfma_f32_16x16x32_bf16 v[24:27], v[136:139], v[200:203], 0
	v_mfma_f32_16x16x32_bf16 v[24:27], v[140:143], v[204:207], v[24:27]
	v_mfma_f32_16x16x32_bf16 v[8:11], v[136:139], v[208:211], 0
	v_mfma_f32_16x16x32_bf16 v[8:11], v[140:143], v[212:215], v[8:11]
	v_mfma_f32_16x16x32_bf16 v[52:55], v[144:147], v[184:187], 0
	v_mfma_f32_16x16x32_bf16 v[52:55], v[148:151], v[188:191], v[52:55]
	v_mfma_f32_16x16x32_bf16 v[36:39], v[144:147], v[192:195], 0
	v_mfma_f32_16x16x32_bf16 v[36:39], v[148:151], v[196:199], v[36:39]
	v_mfma_f32_16x16x32_bf16 v[20:23], v[144:147], v[200:203], 0
	v_mfma_f32_16x16x32_bf16 v[20:23], v[148:151], v[204:207], v[20:23]
	v_mfma_f32_16x16x32_bf16 v[4:7], v[144:147], v[208:211], 0
	v_mfma_f32_16x16x32_bf16 v[4:7], v[148:151], v[212:215], v[4:7]
	v_mfma_f32_16x16x32_bf16 v[44:47], v[170:173], v[184:187], 0
	v_mfma_f32_16x16x32_bf16 v[44:47], v[178:181], v[188:191], v[44:47]
	v_mfma_f32_16x16x32_bf16 v[32:35], v[170:173], v[192:195], 0
	v_mfma_f32_16x16x32_bf16 v[32:35], v[178:181], v[196:199], v[32:35]
	v_mfma_f32_16x16x32_bf16 v[12:15], v[170:173], v[200:203], 0
	v_mfma_f32_16x16x32_bf16 v[12:15], v[178:181], v[204:207], v[12:15]
	v_mfma_f32_16x16x32_bf16 v[0:3], v[170:173], v[208:211], 0
	v_mfma_f32_16x16x32_bf16 v[0:3], v[178:181], v[212:215], v[0:3]
	s_barrier
	s_setprio 0
	s_add_i32 s31, 0, 0x18000
	s_add_i32 s33, 0, 0x1c000
	v_add_u32_e32 v140, s31, v166
	v_add_u32_e32 v168, s33, v166
	ds_read_b128 v[128:131], v140
	ds_read_b128 v[132:135], v140 offset:1024
	ds_read_b128 v[136:139], v140 offset:2048
	ds_read_b128 v[140:143], v140 offset:3072
	ds_read_b128 v[144:147], v168
	ds_read_b128 v[148:151], v168 offset:1024
	ds_read_b128 v[170:173], v168 offset:2048
	ds_read_b128 v[178:181], v168 offset:3072
	s_add_u32 s12, s86, 0x80000
	s_addc_u32 s13, s87, 0
	s_mov_b32 m0, s18
	ds_read_b128 v[184:187], v183 offset:32768
	ds_read_b128 v[188:191], v183 offset:33792
	ds_read_b128 v[192:195], v183 offset:34816
	ds_read_b128 v[196:199], v183 offset:35840
	ds_read_b128 v[200:203], v183 offset:36864
	ds_read_b128 v[204:207], v183 offset:37888
	ds_read_b128 v[208:211], v183 offset:38912
	ds_read_b128 v[212:215], v183 offset:39936
	global_load_lds_dwordx4 v152, s[12:13]
	s_mov_b32 m0, s19
	s_nop 0
	global_load_lds_dwordx4 v156, s[12:13]
	s_waitcnt vmcnt(8)
	s_waitcnt lgkmcnt(0)
	s_setprio 1
	s_barrier
	v_mfma_f32_16x16x32_bf16 v[124:127], v[128:131], v[184:187], v[124:127]
	v_mfma_f32_16x16x32_bf16 v[124:127], v[132:135], v[188:191], v[124:127]
	v_mfma_f32_16x16x32_bf16 v[112:115], v[128:131], v[192:195], v[112:115]
	v_mfma_f32_16x16x32_bf16 v[112:115], v[132:135], v[196:199], v[112:115]
	v_mfma_f32_16x16x32_bf16 v[92:95], v[128:131], v[200:203], v[92:95]
	v_mfma_f32_16x16x32_bf16 v[92:95], v[132:135], v[204:207], v[92:95]
	v_mfma_f32_16x16x32_bf16 v[80:83], v[128:131], v[208:211], v[80:83]
	v_mfma_f32_16x16x32_bf16 v[80:83], v[132:135], v[212:215], v[80:83]
	v_mfma_f32_16x16x32_bf16 v[120:123], v[136:139], v[184:187], v[120:123]
	v_mfma_f32_16x16x32_bf16 v[120:123], v[140:143], v[188:191], v[120:123]
	v_mfma_f32_16x16x32_bf16 v[104:107], v[136:139], v[192:195], v[104:107]
	v_mfma_f32_16x16x32_bf16 v[104:107], v[140:143], v[196:199], v[104:107]
	v_mfma_f32_16x16x32_bf16 v[88:91], v[136:139], v[200:203], v[88:91]
	v_mfma_f32_16x16x32_bf16 v[88:91], v[140:143], v[204:207], v[88:91]
	v_mfma_f32_16x16x32_bf16 v[72:75], v[136:139], v[208:211], v[72:75]
	v_mfma_f32_16x16x32_bf16 v[72:75], v[140:143], v[212:215], v[72:75]
	v_mfma_f32_16x16x32_bf16 v[116:119], v[144:147], v[184:187], v[116:119]
	v_mfma_f32_16x16x32_bf16 v[116:119], v[148:151], v[188:191], v[116:119]
	v_mfma_f32_16x16x32_bf16 v[100:103], v[144:147], v[192:195], v[100:103]
	v_mfma_f32_16x16x32_bf16 v[100:103], v[148:151], v[196:199], v[100:103]
	v_mfma_f32_16x16x32_bf16 v[84:87], v[144:147], v[200:203], v[84:87]
	v_mfma_f32_16x16x32_bf16 v[84:87], v[148:151], v[204:207], v[84:87]
	v_mfma_f32_16x16x32_bf16 v[68:71], v[144:147], v[208:211], v[68:71]
	v_mfma_f32_16x16x32_bf16 v[68:71], v[148:151], v[212:215], v[68:71]
	v_mfma_f32_16x16x32_bf16 v[108:111], v[170:173], v[184:187], v[108:111]
	v_mfma_f32_16x16x32_bf16 v[108:111], v[178:181], v[188:191], v[108:111]
	v_mfma_f32_16x16x32_bf16 v[96:99], v[170:173], v[192:195], v[96:99]
	v_mfma_f32_16x16x32_bf16 v[96:99], v[178:181], v[196:199], v[96:99]
	v_mfma_f32_16x16x32_bf16 v[76:79], v[170:173], v[200:203], v[76:79]
	v_mfma_f32_16x16x32_bf16 v[76:79], v[178:181], v[204:207], v[76:79]
	v_mfma_f32_16x16x32_bf16 v[64:67], v[170:173], v[208:211], v[64:67]
	v_mfma_f32_16x16x32_bf16 v[64:67], v[178:181], v[212:215], v[64:67]
	s_barrier
; #define PG8_STAGE(bufoff, gbase, voff) do { _Pragma("unroll") for (int _i = 0; _i < 2; ++_i) \
;         __builtin_amdgcn_global_load_lds((const unsigned*)((const char*)(gbase) + (voff)[_i]), (PG8_LAS unsigned*)(lds + (bufoff) + ldsw + _i * 8192), 16, 0, 0); } while (0)
; #define PG8_LDA(dst, b, h) do { _Pragma("unroll") for (int m = 0; m < 4; ++m) _Pragma("unroll") for (int k = 0; k < 2; ++k) dst[m][k] = *(const PG8_LAS bf16x8*)(lds + PG8_SA(b, h) + aoff + m * 2048 + k * 1024); } while (0)
; #define PG8_MMA(ai, bj, At, Bt) do { __builtin_amdgcn_s_setprio(1); _Pragma("unroll") for (int m = 0; m < 4; ++m) _Pragma("unroll") for (int n = 0; n < 2; ++n) _Pragma("unroll") for (int k = 0; k < 2; ++k) \
;         acc[ai][bj][m][n] = __builtin_amdgcn_mfma_f32_16x16x32_bf16(Bt[n][k], At[m][k], acc[ai][bj][m][n], 0, 0, 0); __builtin_amdgcn_s_setprio(0); } while (0)
; #define PG8_WAIT_V(n) asm volatile("s_waitcnt vmcnt(" #n ")" ::: "memory")
; #define PG8_WAIT_L(n) asm volatile("s_waitcnt lgkmcnt(" #n ")" ::: "memory")
; #define PG8_BAR __builtin_amdgcn_s_barrier()
; #define PG8_SCHED __builtin_amdgcn_sched_barrier(0)
;     ...
;             PG8_LDA(At, 1, 1); PG8_STAGE(PG8_SB(1, 0), b3, voffB); PG8_STAGE(PG8_SB(1, 1), b3 + hstep, voffB); PG8_STAGE(PG8_SA(1, 0), a3, voffA);
;             PG8_WAIT_V(8); PG8_WAIT_L(0); PG8_BAR; PG8_MMA(1, 0, At, B0); PG8_MMA(1, 1, At, B1); PG8_BAR; PG8_SCHED;
	s_setprio 0
	s_add_i32 s12, s31, s8
	s_mov_b32 m0, s12
	ds_read_b128 v[184:187], v183 offset:49152
	ds_read_b128 v[188:191], v183 offset:50176
	ds_read_b128 v[192:195], v183 offset:51200
	ds_read_b128 v[196:199], v183 offset:52224
	ds_read_b128 v[200:203], v183 offset:53248
	ds_read_b128 v[204:207], v183 offset:54272
	ds_read_b128 v[208:211], v183 offset:55296
	ds_read_b128 v[212:215], v183 offset:56320
	s_add_u32 s100, s84, s16
	s_addc_u32 s101, s85, s17
	global_load_lds_dwordx4 v154, s[100:101]
	s_add_i32 m0, s12, 0x2000
	s_add_u32 s12, s84, 0x80080
	s_addc_u32 s13, s85, 0
	s_add_i32 s31, s33, s8
	global_load_lds_dwordx4 v158, s[100:101]
	s_mov_b32 m0, s31
	s_nop 0
	global_load_lds_dwordx4 v154, s[12:13]
	s_add_i32 m0, s31, 0x2000
	s_nop 0
	global_load_lds_dwordx4 v158, s[12:13]
	s_mov_b32 m0, s20
	s_nop 0
	s_add_u32 s100, s86, s16
	s_addc_u32 s101, s87, s17
	global_load_lds_dwordx4 v152, s[100:101]
	s_mov_b32 m0, s21
	s_nop 0
	global_load_lds_dwordx4 v156, s[100:101]
	s_waitcnt vmcnt(8)
	s_waitcnt lgkmcnt(0)
	s_setprio 1
	s_barrier
	v_mfma_f32_16x16x32_bf16 v[60:63], v[128:131], v[184:187], v[60:63]
	v_mfma_f32_16x16x32_bf16 v[60:63], v[132:135], v[188:191], v[60:63]
	v_mfma_f32_16x16x32_bf16 v[48:51], v[128:131], v[192:195], v[48:51]
	v_mfma_f32_16x16x32_bf16 v[48:51], v[132:135], v[196:199], v[48:51]
	v_mfma_f32_16x16x32_bf16 v[28:31], v[128:131], v[200:203], v[28:31]
	v_mfma_f32_16x16x32_bf16 v[28:31], v[132:135], v[204:207], v[28:31]
	v_mfma_f32_16x16x32_bf16 v[16:19], v[128:131], v[208:211], v[16:19]
	v_mfma_f32_16x16x32_bf16 v[16:19], v[132:135], v[212:215], v[16:19]
	v_mfma_f32_16x16x32_bf16 v[56:59], v[136:139], v[184:187], v[56:59]
	v_mfma_f32_16x16x32_bf16 v[56:59], v[140:143], v[188:191], v[56:59]
	v_mfma_f32_16x16x32_bf16 v[40:43], v[136:139], v[192:195], v[40:43]
	v_mfma_f32_16x16x32_bf16 v[40:43], v[140:143], v[196:199], v[40:43]
	v_mfma_f32_16x16x32_bf16 v[24:27], v[136:139], v[200:203], v[24:27]
	v_mfma_f32_16x16x32_bf16 v[24:27], v[140:143], v[204:207], v[24:27]
	v_mfma_f32_16x16x32_bf16 v[8:11], v[136:139], v[208:211], v[8:11]
	v_mfma_f32_16x16x32_bf16 v[8:11], v[140:143], v[212:215], v[8:11]
	v_mfma_f32_16x16x32_bf16 v[52:55], v[144:147], v[184:187], v[52:55]
	v_mfma_f32_16x16x32_bf16 v[52:55], v[148:151], v[188:191], v[52:55]
	v_mfma_f32_16x16x32_bf16 v[36:39], v[144:147], v[192:195], v[36:39]
	v_mfma_f32_16x16x32_bf16 v[36:39], v[148:151], v[196:199], v[36:39]
	v_mfma_f32_16x16x32_bf16 v[20:23], v[144:147], v[200:203], v[20:23]
	v_mfma_f32_16x16x32_bf16 v[20:23], v[148:151], v[204:207], v[20:23]
	v_mfma_f32_16x16x32_bf16 v[4:7], v[144:147], v[208:211], v[4:7]
	v_mfma_f32_16x16x32_bf16 v[4:7], v[148:151], v[212:215], v[4:7]
	v_mfma_f32_16x16x32_bf16 v[44:47], v[170:173], v[184:187], v[44:47]
	v_mfma_f32_16x16x32_bf16 v[44:47], v[178:181], v[188:191], v[44:47]
	v_mfma_f32_16x16x32_bf16 v[32:35], v[170:173], v[192:195], v[32:35]
	v_mfma_f32_16x16x32_bf16 v[32:35], v[178:181], v[196:199], v[32:35]
	v_mfma_f32_16x16x32_bf16 v[12:15], v[170:173], v[200:203], v[12:15]
	v_mfma_f32_16x16x32_bf16 v[12:15], v[178:181], v[204:207], v[12:15]
	v_mfma_f32_16x16x32_bf16 v[0:3], v[170:173], v[208:211], v[0:3]
	v_mfma_f32_16x16x32_bf16 v[0:3], v[178:181], v[212:215], v[0:3]
	s_barrier
	s_setprio 0
	s_add_i32 s3, s3, 2
	s_add_u32 s82, s82, 0x100
	s_addc_u32 s83, s83, 0
	s_add_u32 s30, s30, 0x100
	s_addc_u32 s2, s2, 0
	s_cmp_gt_u32 s3, 29

; #define PG8_STAGE(bufoff, gbase, voff) do { _Pragma("unroll") for (int _i = 0; _i < 2; ++_i) \
;         __builtin_amdgcn_global_load_lds((const unsigned*)((const char*)(gbase) + (voff)[_i]), (PG8_LAS unsigned*)(lds + (bufoff) + ldsw + _i * 8192), 16, 0, 0); } while (0)
; #define PG8_LDA(dst, b, h) do { _Pragma("unroll") for (int m = 0; m < 4; ++m) _Pragma("unroll") for (int k = 0; k < 2; ++k) dst[m][k] = *(const PG8_LAS bf16x8*)(lds + PG8_SA(b, h) + aoff + m * 2048 + k * 1024); } while (0)
; #define PG8_LDB(dst, b, h) do { _Pragma("unroll") for (int n = 0; n < 2; ++n) _Pragma("unroll") for (int k = 0; k < 2; ++k) dst[n][k] = *(const PG8_LAS bf16x8*)(lds + PG8_SB(b, h) + boff + n * 2048 + k * 1024); } while (0)
; #define PG8_MMA(ai, bj, At, Bt) do { __builtin_amdgcn_s_setprio(1); _Pragma("unroll") for (int m = 0; m < 4; ++m) _Pragma("unroll") for (int n = 0; n < 2; ++n) _Pragma("unroll") for (int k = 0; k < 2; ++k) \
;         acc[ai][bj][m][n] = __builtin_amdgcn_mfma_f32_16x16x32_bf16(Bt[n][k], At[m][k], acc[ai][bj][m][n], 0, 0, 0); __builtin_amdgcn_s_setprio(0); } while (0)
; #define PG8_BAR __builtin_amdgcn_s_barrier()
;     ...
;         const char* nA = has_next ? (const char*)g.A + (size_t)nxt.pm * tstep : cA; const char* nB = has_next ? (const char*)g.Bt + (size_t)nxt.pn * tstep : cB;
;         for (int t = 0; t < nt; t += 2) {
;             if constexpr (Epi::MIDK) { if (t == nt / 2) E.midk(acc, cur, wr, wc, fr, fq); }
;             const bool last = (t == nt - 2);
;             const char* a1 = PG8_KADV(cA, (size_t)(t + 1) * kstep);
;             const char* a2 = last ? nA : PG8_KADV(cA, (size_t)(t + 2) * kstep); const char* b2 = last ? nB : PG8_KADV(cB, (size_t)(t + 2) * kstep);
;             const char* a3 = PG8_KADV(a2, kstep); const char* b3 = PG8_KADV(b2, kstep);
;             if (last && has_next) S.a_ready(nxt);
;             if constexpr (SP2) {
;             PG8_LDB(B0, 0, 0); PG8_LDB(B1, 0, 1); PG8_SCHED; PG8_LDA(At, 0, 0); PG8_STAGE(PG8_SA(1, 1), a1 + hstep, voffA);
;             PG8_WAIT_V(8); PG8_WAIT_L(0); PG8_BAR; PG8_MMA(0, 0, At, B0); PG8_MMA(0, 1, At, B1); PG8_BAR; PG8_SCHED;
;             PG8_LDA(At, 0, 1); PG8_STAGE(PG8_SB(0, 0), b2, voffB); PG8_STAGE(PG8_SB(0, 1), b2 + hstep, voffB); PG8_STAGE(PG8_SA(0, 0), a2, voffA);
;             PG8_WAIT_V(8); PG8_WAIT_L(0); PG8_BAR; PG8_MMA(1, 0, At, B0); PG8_MMA(1, 1, At, B1); PG8_BAR; PG8_SCHED;
.LBB0_982:
	s_ashr_i32 s61, s60, 31
	s_lshl_b64 s[2:3], s[60:61], 20
	s_add_u32 s62, s54, s2
	s_addc_u32 s63, s55, s3
	s_and_b64 s[2:3], s[0:1], exec
	s_cselect_b32 s15, s63, s71
	s_cselect_b32 s28, s62, s70
	s_ashr_i32 s59, s58, 31
	s_lshl_b64 s[2:3], s[58:59], 20
	s_add_u32 s66, s8, s2
	s_addc_u32 s67, s9, s3
	s_and_b64 s[2:3], s[0:1], exec
	s_cselect_b32 s30, s67, s73
	s_cselect_b32 s33, s66, s72
	s_add_u32 s70, s70, 0x80080
	s_addc_u32 s71, s71, 0
	s_add_u32 s40, s72, 0x100
	s_addc_u32 s2, s73, 0
	s_mov_b32 s3, -2
	s_add_u32 s12, s70, 0xfff80080
	s_addc_u32 s13, s71, -1
	s_add_i32 s31, 0, 0x10000
	s_cmp_eq_u32 s3, 28
	s_cselect_b32 s75, s15, s13
	s_cselect_b32 s74, s28, s12
	s_cselect_b32 s73, s30, s2
	s_cselect_b32 s72, s33, s40
	s_add_i32 s42, 0, 0x14000
	v_add_u32_e32 v156, s31, v141
	v_add_u32_e32 v168, s42, v141
	ds_read_b128 v[144:147], v156
	ds_read_b128 v[148:151], v156 offset:1024
	ds_read_b128 v[152:155], v156 offset:2048
	ds_read_b128 v[156:159], v156 offset:3072
	ds_read_b128 v[160:163], v168
	ds_read_b128 v[164:167], v168 offset:1024
	ds_read_b128 v[170:173], v168 offset:2048
	ds_read_b128 v[178:181], v168 offset:3072
	s_add_i32 m0, s18, 0xc000
	ds_read_b128 v[182:185], v143
	ds_read_b128 v[186:189], v143 offset:1024
	ds_read_b128 v[190:193], v143 offset:2048
	ds_read_b128 v[194:197], v143 offset:3072
	ds_read_b128 v[198:201], v143 offset:4096
	ds_read_b128 v[202:205], v143 offset:5120
	ds_read_b128 v[206:209], v143 offset:6144
	ds_read_b128 v[210:213], v143 offset:7168
	global_load_lds_dwordx4 v136, s[70:71]
	s_add_i32 m0, s18, 0xe000
	s_nop 0
	global_load_lds_dwordx4 v138, s[70:71]
	s_waitcnt vmcnt(8)
	s_waitcnt lgkmcnt(0)
	s_setprio 1
	s_barrier
	v_mfma_f32_16x16x32_bf16 v[124:127], v[144:147], v[182:185], 0
	v_mfma_f32_16x16x32_bf16 v[124:127], v[148:151], v[186:189], v[124:127]
	v_mfma_f32_16x16x32_bf16 v[108:111], v[144:147], v[190:193], 0
	v_mfma_f32_16x16x32_bf16 v[108:111], v[148:151], v[194:197], v[108:111]
	v_mfma_f32_16x16x32_bf16 v[92:95], v[144:147], v[198:201], 0
	v_mfma_f32_16x16x32_bf16 v[92:95], v[148:151], v[202:205], v[92:95]
	v_mfma_f32_16x16x32_bf16 v[76:79], v[144:147], v[206:209], 0
	v_mfma_f32_16x16x32_bf16 v[76:79], v[148:151], v[210:213], v[76:79]
	v_mfma_f32_16x16x32_bf16 v[120:123], v[152:155], v[182:185], 0
	v_mfma_f32_16x16x32_bf16 v[120:123], v[156:159], v[186:189], v[120:123]
	v_mfma_f32_16x16x32_bf16 v[104:107], v[152:155], v[190:193], 0
	v_mfma_f32_16x16x32_bf16 v[104:107], v[156:159], v[194:197], v[104:107]
	v_mfma_f32_16x16x32_bf16 v[88:91], v[152:155], v[198:201], 0
	v_mfma_f32_16x16x32_bf16 v[88:91], v[156:159], v[202:205], v[88:91]
	v_mfma_f32_16x16x32_bf16 v[72:75], v[152:155], v[206:209], 0
	v_mfma_f32_16x16x32_bf16 v[72:75], v[156:159], v[210:213], v[72:75]
	v_mfma_f32_16x16x32_bf16 v[116:119], v[160:163], v[182:185], 0
	v_mfma_f32_16x16x32_bf16 v[116:119], v[164:167], v[186:189], v[116:119]
	v_mfma_f32_16x16x32_bf16 v[100:103], v[160:163], v[190:193], 0
	v_mfma_f32_16x16x32_bf16 v[100:103], v[164:167], v[194:197], v[100:103]
	v_mfma_f32_16x16x32_bf16 v[84:87], v[160:163], v[198:201], 0
	v_mfma_f32_16x16x32_bf16 v[84:87], v[164:167], v[202:205], v[84:87]
	v_mfma_f32_16x16x32_bf16 v[68:71], v[160:163], v[206:209], 0
	v_mfma_f32_16x16x32_bf16 v[68:71], v[164:167], v[210:213], v[68:71]
	v_mfma_f32_16x16x32_bf16 v[112:115], v[170:173], v[182:185], 0
	v_mfma_f32_16x16x32_bf16 v[112:115], v[178:181], v[186:189], v[112:115]
	v_mfma_f32_16x16x32_bf16 v[96:99], v[170:173], v[190:193], 0
	v_mfma_f32_16x16x32_bf16 v[96:99], v[178:181], v[194:197], v[96:99]
	v_mfma_f32_16x16x32_bf16 v[80:83], v[170:173], v[198:201], 0
	v_mfma_f32_16x16x32_bf16 v[80:83], v[178:181], v[202:205], v[80:83]
	v_mfma_f32_16x16x32_bf16 v[64:67], v[170:173], v[206:209], 0
	v_mfma_f32_16x16x32_bf16 v[64:67], v[178:181], v[210:213], v[64:67]
	s_barrier
	s_setprio 0
	s_add_i32 s12, s31, s10
	s_mov_b32 m0, s12
	ds_read_b128 v[182:185], v143 offset:16384
	ds_read_b128 v[186:189], v143 offset:17408
	ds_read_b128 v[190:193], v143 offset:18432
	ds_read_b128 v[194:197], v143 offset:19456
	ds_read_b128 v[198:201], v143 offset:20480
	ds_read_b128 v[202:205], v143 offset:21504
	ds_read_b128 v[206:209], v143 offset:22528
	ds_read_b128 v[210:213], v143 offset:23552
	global_load_lds_dwordx4 v132, s[72:73]
	s_add_i32 m0, s12, 0x2000
	s_add_u32 s12, s72, 0x80000
	s_addc_u32 s13, s73, 0
	s_add_i32 s31, s42, s10
	global_load_lds_dwordx4 v128, s[72:73]
	s_mov_b32 m0, s31
	s_nop 0
	global_load_lds_dwordx4 v132, s[12:13]
	s_add_i32 m0, s31, 0x2000
	s_nop 0
	global_load_lds_dwordx4 v128, s[12:13]
	s_mov_b32 m0, s18
	s_nop 0
	global_load_lds_dwordx4 v134, s[74:75]
	s_mov_b32 m0, s19
	s_nop 0
	global_load_lds_dwordx4 v130, s[74:75]
	s_waitcnt vmcnt(8)
	s_waitcnt lgkmcnt(0)
	s_setprio 1
	s_barrier
; #define PG8_STAGE(bufoff, gbase, voff) do { _Pragma("unroll") for (int _i = 0; _i < 2; ++_i) \
;         __builtin_amdgcn_global_load_lds((const unsigned*)((const char*)(gbase) + (voff)[_i]), (PG8_LAS unsigned*)(lds + (bufoff) + ldsw + _i * 8192), 16, 0, 0); } while (0)
; #define PG8_LDA(dst, b, h) do { _Pragma("unroll") for (int m = 0; m < 4; ++m) _Pragma("unroll") for (int k = 0; k < 2; ++k) dst[m][k] = *(const PG8_LAS bf16x8*)(lds + PG8_SA(b, h) + aoff + m * 2048 + k * 1024); } while (0)
; #define PG8_LDB(dst, b, h) do { _Pragma("unroll") for (int n = 0; n < 2; ++n) _Pragma("unroll") for (int k = 0; k < 2; ++k) dst[n][k] = *(const PG8_LAS bf16x8*)(lds + PG8_SB(b, h) + boff + n * 2048 + k * 1024); } while (0)
; #define PG8_MMA(ai, bj, At, Bt) do { __builtin_amdgcn_s_setprio(1); _Pragma("unroll") for (int m = 0; m < 4; ++m) _Pragma("unroll") for (int n = 0; n < 2; ++n) _Pragma("unroll") for (int k = 0; k < 2; ++k) \
;         acc[ai][bj][m][n] = __builtin_amdgcn_mfma_f32_16x16x32_bf16(Bt[n][k], At[m][k], acc[ai][bj][m][n], 0, 0, 0); __builtin_amdgcn_s_setprio(0); } while (0)
; #define PG8_WAIT_V(n) asm volatile("s_waitcnt vmcnt(" #n ")" ::: "memory")
; #define PG8_WAIT_L(n) asm volatile("s_waitcnt lgkmcnt(" #n ")" ::: "memory")
; #define PG8_BAR __builtin_amdgcn_s_barrier()
; #define PG8_SCHED __builtin_amdgcn_sched_barrier(0)
;     ...
;             PG8_WAIT_V(8); PG8_WAIT_L(0); PG8_BAR; PG8_MMA(1, 0, At, B0); PG8_MMA(1, 1, At, B1); PG8_BAR; PG8_SCHED;
;             PG8_LDB(B0, 1, 0); PG8_LDB(B1, 1, 1); PG8_SCHED; PG8_LDA(At, 1, 0); PG8_STAGE(PG8_SA(0, 1), a2 + hstep, voffA);
;             PG8_WAIT_V(8); PG8_WAIT_L(0); PG8_BAR; PG8_MMA(0, 0, At, B0); PG8_MMA(0, 1, At, B1); PG8_BAR; PG8_SCHED;
	v_mfma_f32_16x16x32_bf16 v[60:63], v[144:147], v[182:185], 0
	v_mfma_f32_16x16x32_bf16 v[60:63], v[148:151], v[186:189], v[60:63]
	v_mfma_f32_16x16x32_bf16 v[44:47], v[144:147], v[190:193], 0
	v_mfma_f32_16x16x32_bf16 v[44:47], v[148:151], v[194:197], v[44:47]
	v_mfma_f32_16x16x32_bf16 v[28:31], v[144:147], v[198:201], 0
	v_mfma_f32_16x16x32_bf16 v[28:31], v[148:151], v[202:205], v[28:31]
	v_mfma_f32_16x16x32_bf16 v[12:15], v[144:147], v[206:209], 0
	v_mfma_f32_16x16x32_bf16 v[12:15], v[148:151], v[210:213], v[12:15]
	v_mfma_f32_16x16x32_bf16 v[56:59], v[152:155], v[182:185], 0
	v_mfma_f32_16x16x32_bf16 v[56:59], v[156:159], v[186:189], v[56:59]
	v_mfma_f32_16x16x32_bf16 v[40:43], v[152:155], v[190:193], 0
	v_mfma_f32_16x16x32_bf16 v[40:43], v[156:159], v[194:197], v[40:43]
	v_mfma_f32_16x16x32_bf16 v[24:27], v[152:155], v[198:201], 0
	v_mfma_f32_16x16x32_bf16 v[24:27], v[156:159], v[202:205], v[24:27]
	v_mfma_f32_16x16x32_bf16 v[8:11], v[152:155], v[206:209], 0
	v_mfma_f32_16x16x32_bf16 v[8:11], v[156:159], v[210:213], v[8:11]
	v_mfma_f32_16x16x32_bf16 v[52:55], v[160:163], v[182:185], 0
	v_mfma_f32_16x16x32_bf16 v[52:55], v[164:167], v[186:189], v[52:55]
	v_mfma_f32_16x16x32_bf16 v[36:39], v[160:163], v[190:193], 0
	v_mfma_f32_16x16x32_bf16 v[36:39], v[164:167], v[194:197], v[36:39]
	v_mfma_f32_16x16x32_bf16 v[20:23], v[160:163], v[198:201], 0
	v_mfma_f32_16x16x32_bf16 v[20:23], v[164:167], v[202:205], v[20:23]
	v_mfma_f32_16x16x32_bf16 v[4:7], v[160:163], v[206:209], 0
	v_mfma_f32_16x16x32_bf16 v[4:7], v[164:167], v[210:213], v[4:7]
	v_mfma_f32_16x16x32_bf16 v[48:51], v[170:173], v[182:185], 0
	v_mfma_f32_16x16x32_bf16 v[48:51], v[178:181], v[186:189], v[48:51]
	v_mfma_f32_16x16x32_bf16 v[32:35], v[170:173], v[190:193], 0
	v_mfma_f32_16x16x32_bf16 v[32:35], v[178:181], v[194:197], v[32:35]
	v_mfma_f32_16x16x32_bf16 v[16:19], v[170:173], v[198:201], 0
	v_mfma_f32_16x16x32_bf16 v[16:19], v[178:181], v[202:205], v[16:19]
	v_mfma_f32_16x16x32_bf16 v[0:3], v[170:173], v[206:209], 0
	v_mfma_f32_16x16x32_bf16 v[0:3], v[178:181], v[210:213], v[0:3]
	s_barrier
	s_setprio 0
	s_add_i32 s31, 0, 0x18000
	s_add_i32 s42, 0, 0x1c000
	v_add_u32_e32 v156, s31, v141
	v_add_u32_e32 v168, s42, v141
	ds_read_b128 v[144:147], v156
	ds_read_b128 v[148:151], v156 offset:1024
	ds_read_b128 v[152:155], v156 offset:2048
	ds_read_b128 v[156:159], v156 offset:3072
	ds_read_b128 v[160:163], v168
	ds_read_b128 v[164:167], v168 offset:1024
	ds_read_b128 v[170:173], v168 offset:2048
	ds_read_b128 v[178:181], v168 offset:3072
	s_add_u32 s12, s74, 0x80000
	s_addc_u32 s13, s75, 0
	s_mov_b32 m0, s20
	ds_read_b128 v[182:185], v143 offset:32768
	ds_read_b128 v[186:189], v143 offset:33792
	ds_read_b128 v[190:193], v143 offset:34816
	ds_read_b128 v[194:197], v143 offset:35840
	ds_read_b128 v[198:201], v143 offset:36864
	ds_read_b128 v[202:205], v143 offset:37888
	ds_read_b128 v[206:209], v143 offset:38912
	ds_read_b128 v[210:213], v143 offset:39936
	global_load_lds_dwordx4 v134, s[12:13]
	s_mov_b32 m0, s21
	s_nop 0
	global_load_lds_dwordx4 v130, s[12:13]
	s_waitcnt vmcnt(8)
	s_waitcnt lgkmcnt(0)
	s_setprio 1
	s_barrier
	v_mfma_f32_16x16x32_bf16 v[124:127], v[144:147], v[182:185], v[124:127]
	v_mfma_f32_16x16x32_bf16 v[124:127], v[148:151], v[186:189], v[124:127]
	v_mfma_f32_16x16x32_bf16 v[108:111], v[144:147], v[190:193], v[108:111]
	v_mfma_f32_16x16x32_bf16 v[108:111], v[148:151], v[194:197], v[108:111]
	v_mfma_f32_16x16x32_bf16 v[92:95], v[144:147], v[198:201], v[92:95]
	v_mfma_f32_16x16x32_bf16 v[92:95], v[148:151], v[202:205], v[92:95]
	v_mfma_f32_16x16x32_bf16 v[76:79], v[144:147], v[206:209], v[76:79]
	v_mfma_f32_16x16x32_bf16 v[76:79], v[148:151], v[210:213], v[76:79]
	v_mfma_f32_16x16x32_bf16 v[120:123], v[152:155], v[182:185], v[120:123]
	v_mfma_f32_16x16x32_bf16 v[120:123], v[156:159], v[186:189], v[120:123]
	v_mfma_f32_16x16x32_bf16 v[104:107], v[152:155], v[190:193], v[104:107]
	v_mfma_f32_16x16x32_bf16 v[104:107], v[156:159], v[194:197], v[104:107]
	v_mfma_f32_16x16x32_bf16 v[88:91], v[152:155], v[198:201], v[88:91]
	v_mfma_f32_16x16x32_bf16 v[88:91], v[156:159], v[202:205], v[88:91]
	v_mfma_f32_16x16x32_bf16 v[72:75], v[152:155], v[206:209], v[72:75]
	v_mfma_f32_16x16x32_bf16 v[72:75], v[156:159], v[210:213], v[72:75]
	v_mfma_f32_16x16x32_bf16 v[116:119], v[160:163], v[182:185], v[116:119]
	v_mfma_f32_16x16x32_bf16 v[116:119], v[164:167], v[186:189], v[116:119]
	v_mfma_f32_16x16x32_bf16 v[100:103], v[160:163], v[190:193], v[100:103]
	v_mfma_f32_16x16x32_bf16 v[100:103], v[164:167], v[194:197], v[100:103]
	v_mfma_f32_16x16x32_bf16 v[84:87], v[160:163], v[198:201], v[84:87]
	v_mfma_f32_16x16x32_bf16 v[84:87], v[164:167], v[202:205], v[84:87]
	v_mfma_f32_16x16x32_bf16 v[68:71], v[160:163], v[206:209], v[68:71]
	v_mfma_f32_16x16x32_bf16 v[68:71], v[164:167], v[210:213], v[68:71]
	v_mfma_f32_16x16x32_bf16 v[112:115], v[170:173], v[182:185], v[112:115]
	v_mfma_f32_16x16x32_bf16 v[112:115], v[178:181], v[186:189], v[112:115]
	v_mfma_f32_16x16x32_bf16 v[96:99], v[170:173], v[190:193], v[96:99]
	v_mfma_f32_16x16x32_bf16 v[96:99], v[178:181], v[194:197], v[96:99]
	v_mfma_f32_16x16x32_bf16 v[80:83], v[170:173], v[198:201], v[80:83]
	v_mfma_f32_16x16x32_bf16 v[80:83], v[178:181], v[202:205], v[80:83]
	v_mfma_f32_16x16x32_bf16 v[64:67], v[170:173], v[206:209], v[64:67]
	v_mfma_f32_16x16x32_bf16 v[64:67], v[178:181], v[210:213], v[64:67]
	s_barrier
; #define PG8_STAGE(bufoff, gbase, voff) do { _Pragma("unroll") for (int _i = 0; _i < 2; ++_i) \
;         __builtin_amdgcn_global_load_lds((const unsigned*)((const char*)(gbase) + (voff)[_i]), (PG8_LAS unsigned*)(lds + (bufoff) + ldsw + _i * 8192), 16, 0, 0); } while (0)
; #define PG8_LDA(dst, b, h) do { _Pragma("unroll") for (int m = 0; m < 4; ++m) _Pragma("unroll") for (int k = 0; k < 2; ++k) dst[m][k] = *(const PG8_LAS bf16x8*)(lds + PG8_SA(b, h) + aoff + m * 2048 + k * 1024); } while (0)
; #define PG8_MMA(ai, bj, At, Bt) do { __builtin_amdgcn_s_setprio(1); _Pragma("unroll") for (int m = 0; m < 4; ++m) _Pragma("unroll") for (int n = 0; n < 2; ++n) _Pragma("unroll") for (int k = 0; k < 2; ++k) \
;         acc[ai][bj][m][n] = __builtin_amdgcn_mfma_f32_16x16x32_bf16(Bt[n][k], At[m][k], acc[ai][bj][m][n], 0, 0, 0); __builtin_amdgcn_s_setprio(0); } while (0)
; #define PG8_WAIT_V(n) asm volatile("s_waitcnt vmcnt(" #n ")" ::: "memory")
; #define PG8_WAIT_L(n) asm volatile("s_waitcnt lgkmcnt(" #n ")" ::: "memory")
; #define PG8_BAR __builtin_amdgcn_s_barrier()
; #define PG8_SCHED __builtin_amdgcn_sched_barrier(0)
;     ...
;             PG8_LDA(At, 1, 1); PG8_STAGE(PG8_SB(1, 0), b3, voffB); PG8_STAGE(PG8_SB(1, 1), b3 + hstep, voffB); PG8_STAGE(PG8_SA(1, 0), a3, voffA);
;             PG8_WAIT_V(8); PG8_WAIT_L(0); PG8_BAR; PG8_MMA(1, 0, At, B0); PG8_MMA(1, 1, At, B1); PG8_BAR; PG8_SCHED;
	s_setprio 0
	s_add_i32 s12, s31, s10
	s_mov_b32 m0, s12
	ds_read_b128 v[182:185], v143 offset:49152
	ds_read_b128 v[186:189], v143 offset:50176
	ds_read_b128 v[190:193], v143 offset:51200
	ds_read_b128 v[194:197], v143 offset:52224
	ds_read_b128 v[198:201], v143 offset:53248
	ds_read_b128 v[202:205], v143 offset:54272
	ds_read_b128 v[206:209], v143 offset:55296
	ds_read_b128 v[210:213], v143 offset:56320
	s_add_u32 s100, s72, s16
	s_addc_u32 s101, s73, s17
	global_load_lds_dwordx4 v132, s[100:101]
	s_add_i32 m0, s12, 0x2000
	s_add_u32 s12, s72, 0x80080
	s_addc_u32 s13, s73, 0
	s_add_i32 s31, s42, s10
	global_load_lds_dwordx4 v128, s[100:101]
	s_mov_b32 m0, s31
	s_nop 0
	global_load_lds_dwordx4 v132, s[12:13]
	s_add_i32 m0, s31, 0x2000
	s_nop 0
	global_load_lds_dwordx4 v128, s[12:13]
	s_mov_b32 m0, s22
	s_nop 0
	s_add_u32 s100, s74, s16
	s_addc_u32 s101, s75, s17
	global_load_lds_dwordx4 v134, s[100:101]
	s_mov_b32 m0, s23
	s_nop 0
	global_load_lds_dwordx4 v130, s[100:101]
	s_waitcnt vmcnt(8)
	s_waitcnt lgkmcnt(0)
	s_setprio 1
	s_barrier
	v_mfma_f32_16x16x32_bf16 v[60:63], v[144:147], v[182:185], v[60:63]
	v_mfma_f32_16x16x32_bf16 v[60:63], v[148:151], v[186:189], v[60:63]
	v_mfma_f32_16x16x32_bf16 v[44:47], v[144:147], v[190:193], v[44:47]
	v_mfma_f32_16x16x32_bf16 v[44:47], v[148:151], v[194:197], v[44:47]
	v_mfma_f32_16x16x32_bf16 v[28:31], v[144:147], v[198:201], v[28:31]
	v_mfma_f32_16x16x32_bf16 v[28:31], v[148:151], v[202:205], v[28:31]
	v_mfma_f32_16x16x32_bf16 v[12:15], v[144:147], v[206:209], v[12:15]
	v_mfma_f32_16x16x32_bf16 v[12:15], v[148:151], v[210:213], v[12:15]
	v_mfma_f32_16x16x32_bf16 v[56:59], v[152:155], v[182:185], v[56:59]
	v_mfma_f32_16x16x32_bf16 v[56:59], v[156:159], v[186:189], v[56:59]
	v_mfma_f32_16x16x32_bf16 v[40:43], v[152:155], v[190:193], v[40:43]
	v_mfma_f32_16x16x32_bf16 v[40:43], v[156:159], v[194:197], v[40:43]
	v_mfma_f32_16x16x32_bf16 v[24:27], v[152:155], v[198:201], v[24:27]
	v_mfma_f32_16x16x32_bf16 v[24:27], v[156:159], v[202:205], v[24:27]
	v_mfma_f32_16x16x32_bf16 v[8:11], v[152:155], v[206:209], v[8:11]
	v_mfma_f32_16x16x32_bf16 v[8:11], v[156:159], v[210:213], v[8:11]
	v_mfma_f32_16x16x32_bf16 v[52:55], v[160:163], v[182:185], v[52:55]
	v_mfma_f32_16x16x32_bf16 v[52:55], v[164:167], v[186:189], v[52:55]
	v_mfma_f32_16x16x32_bf16 v[36:39], v[160:163], v[190:193], v[36:39]
	v_mfma_f32_16x16x32_bf16 v[36:39], v[164:167], v[194:197], v[36:39]
	v_mfma_f32_16x16x32_bf16 v[20:23], v[160:163], v[198:201], v[20:23]
	v_mfma_f32_16x16x32_bf16 v[20:23], v[164:167], v[202:205], v[20:23]
	v_mfma_f32_16x16x32_bf16 v[4:7], v[160:163], v[206:209], v[4:7]
	v_mfma_f32_16x16x32_bf16 v[4:7], v[164:167], v[210:213], v[4:7]
	v_mfma_f32_16x16x32_bf16 v[48:51], v[170:173], v[182:185], v[48:51]
	v_mfma_f32_16x16x32_bf16 v[48:51], v[178:181], v[186:189], v[48:51]
	v_mfma_f32_16x16x32_bf16 v[32:35], v[170:173], v[190:193], v[32:35]
	v_mfma_f32_16x16x32_bf16 v[32:35], v[178:181], v[194:197], v[32:35]
	v_mfma_f32_16x16x32_bf16 v[16:19], v[170:173], v[198:201], v[16:19]
	v_mfma_f32_16x16x32_bf16 v[16:19], v[178:181], v[202:205], v[16:19]
	v_mfma_f32_16x16x32_bf16 v[0:3], v[170:173], v[206:209], v[0:3]
	v_mfma_f32_16x16x32_bf16 v[0:3], v[178:181], v[210:213], v[0:3]
	s_barrier
	s_setprio 0
	s_add_i32 s3, s3, 2
	s_add_u32 s70, s70, 0x100
	s_addc_u32 s71, s71, 0
	s_add_u32 s40, s40, 0x100
	s_addc_u32 s2, s2, 0
	s_cmp_gt_u32 s3, 29

; #define PG8_STAGE(bufoff, gbase, voff) do { _Pragma("unroll") for (int _i = 0; _i < 2; ++_i) \
;         __builtin_amdgcn_global_load_lds((const unsigned*)((const char*)(gbase) + (voff)[_i]), (PG8_LAS unsigned*)(lds + (bufoff) + ldsw + _i * 8192), 16, 0, 0); } while (0)
; #define PG8_LDA(dst, b, h) do { _Pragma("unroll") for (int m = 0; m < 4; ++m) _Pragma("unroll") for (int k = 0; k < 2; ++k) dst[m][k] = *(const PG8_LAS bf16x8*)(lds + PG8_SA(b, h) + aoff + m * 2048 + k * 1024); } while (0)
; #define PG8_LDB(dst, b, h) do { _Pragma("unroll") for (int n = 0; n < 2; ++n) _Pragma("unroll") for (int k = 0; k < 2; ++k) dst[n][k] = *(const PG8_LAS bf16x8*)(lds + PG8_SB(b, h) + boff + n * 2048 + k * 1024); } while (0)
; #define PG8_MMA(ai, bj, At, Bt) do { __builtin_amdgcn_s_setprio(1); _Pragma("unroll") for (int m = 0; m < 4; ++m) _Pragma("unroll") for (int n = 0; n < 2; ++n) _Pragma("unroll") for (int k = 0; k < 2; ++k) \
;         acc[ai][bj][m][n] = __builtin_amdgcn_mfma_f32_16x16x32_bf16(Bt[n][k], At[m][k], acc[ai][bj][m][n], 0, 0, 0); __builtin_amdgcn_s_setprio(0); } while (0)
; #define PG8_WAIT_V(n) asm volatile("s_waitcnt vmcnt(" #n ")" ::: "memory")
; #define PG8_WAIT_L(n) asm volatile("s_waitcnt lgkmcnt(" #n ")" ::: "memory")
; #define PG8_BAR __builtin_amdgcn_s_barrier()
; #define PG8_SCHED __builtin_amdgcn_sched_barrier(0)
;     ...
;             const bool last = (t == nt - 2);
;             const char* a1 = PG8_KADV(cA, (size_t)(t + 1) * kstep);
;             const char* a2 = last ? nA : PG8_KADV(cA, (size_t)(t + 2) * kstep); const char* b2 = last ? nB : PG8_KADV(cB, (size_t)(t + 2) * kstep);
;             const char* a3 = PG8_KADV(a2, kstep); const char* b3 = PG8_KADV(b2, kstep);
;             if (last && has_next) S.a_ready(nxt);
;             if constexpr (SP2) {
;             PG8_LDB(B0, 0, 0); PG8_LDB(B1, 0, 1); PG8_SCHED; PG8_LDA(At, 0, 0); PG8_STAGE(PG8_SA(1, 1), a1 + hstep, voffA);
;             PG8_WAIT_V(8); PG8_WAIT_L(0); PG8_BAR; PG8_MMA(0, 0, At, B0); PG8_MMA(0, 1, At, B1); PG8_BAR; PG8_SCHED;
;             PG8_LDA(At, 0, 1); PG8_STAGE(PG8_SB(0, 0), b2, voffB); PG8_STAGE(PG8_SB(0, 1), b2 + hstep, voffB); PG8_STAGE(PG8_SA(0, 0), a2, voffA);
;             PG8_WAIT_V(8); PG8_WAIT_L(0); PG8_BAR; PG8_MMA(1, 0, At, B0); PG8_MMA(1, 1, At, B1); PG8_BAR; PG8_SCHED;
.LBB0_1065:
	s_add_u32 s2, s62, 0xffffff00
	s_addc_u32 s25, s63, -1
	s_mov_b32 s3, -2
	s_add_u32 s62, s60, 0xffffff00
	s_addc_u32 s63, s61, -1
	s_add_i32 s26, 0, 0x10000
	s_cmpk_eq_i32 s3, 0x54
	s_cselect_b32 s67, s5, s63
	s_cselect_b32 s66, s4, s62
	s_cselect_b32 s65, s59, s25
	s_cselect_b32 s64, s58, s2
	s_add_i32 s28, 0, 0x14000
	v_add_u32_e32 v152, s26, v166
	v_add_u32_e32 v164, s28, v166
	ds_read_b128 v[128:131], v152
	ds_read_b128 v[132:135], v152 offset:1024
	ds_read_b128 v[148:151], v152 offset:2048
	ds_read_b128 v[152:155], v152 offset:3072
	ds_read_b128 v[156:159], v164
	ds_read_b128 v[160:163], v164 offset:1024
	ds_read_b128 v[170:173], v164 offset:2048
	ds_read_b128 v[178:181], v164 offset:3072
	s_add_i32 m0, s13, 0xc000
	ds_read_b128 v[184:187], v183
	ds_read_b128 v[188:191], v183 offset:1024
	ds_read_b128 v[192:195], v183 offset:2048
	ds_read_b128 v[196:199], v183 offset:3072
	ds_read_b128 v[200:203], v183 offset:4096
	ds_read_b128 v[204:207], v183 offset:5120
	ds_read_b128 v[208:211], v183 offset:6144
	ds_read_b128 v[212:215], v183 offset:7168
	global_load_lds_dwordx4 v144, s[60:61]
	s_add_i32 m0, s13, 0xe000
	s_nop 0
	global_load_lds_dwordx4 v146, s[60:61]
	s_waitcnt vmcnt(8)
	s_waitcnt lgkmcnt(0)
	s_setprio 1
	s_barrier
	v_mfma_f32_16x16x32_bf16 v[124:127], v[128:131], v[184:187], 0
	v_mfma_f32_16x16x32_bf16 v[124:127], v[132:135], v[188:191], v[124:127]
	v_mfma_f32_16x16x32_bf16 v[112:115], v[128:131], v[192:195], 0
	v_mfma_f32_16x16x32_bf16 v[112:115], v[132:135], v[196:199], v[112:115]
	v_mfma_f32_16x16x32_bf16 v[92:95], v[128:131], v[200:203], 0
	v_mfma_f32_16x16x32_bf16 v[92:95], v[132:135], v[204:207], v[92:95]
	v_mfma_f32_16x16x32_bf16 v[80:83], v[128:131], v[208:211], 0
	v_mfma_f32_16x16x32_bf16 v[80:83], v[132:135], v[212:215], v[80:83]
	v_mfma_f32_16x16x32_bf16 v[120:123], v[148:151], v[184:187], 0
	v_mfma_f32_16x16x32_bf16 v[120:123], v[152:155], v[188:191], v[120:123]
	v_mfma_f32_16x16x32_bf16 v[104:107], v[148:151], v[192:195], 0
	v_mfma_f32_16x16x32_bf16 v[104:107], v[152:155], v[196:199], v[104:107]
	v_mfma_f32_16x16x32_bf16 v[88:91], v[148:151], v[200:203], 0
	v_mfma_f32_16x16x32_bf16 v[88:91], v[152:155], v[204:207], v[88:91]
	v_mfma_f32_16x16x32_bf16 v[72:75], v[148:151], v[208:211], 0
	v_mfma_f32_16x16x32_bf16 v[72:75], v[152:155], v[212:215], v[72:75]
	v_mfma_f32_16x16x32_bf16 v[116:119], v[156:159], v[184:187], 0
	v_mfma_f32_16x16x32_bf16 v[116:119], v[160:163], v[188:191], v[116:119]
	v_mfma_f32_16x16x32_bf16 v[100:103], v[156:159], v[192:195], 0
	v_mfma_f32_16x16x32_bf16 v[100:103], v[160:163], v[196:199], v[100:103]
	v_mfma_f32_16x16x32_bf16 v[84:87], v[156:159], v[200:203], 0
	v_mfma_f32_16x16x32_bf16 v[84:87], v[160:163], v[204:207], v[84:87]
	v_mfma_f32_16x16x32_bf16 v[68:71], v[156:159], v[208:211], 0
	v_mfma_f32_16x16x32_bf16 v[68:71], v[160:163], v[212:215], v[68:71]
	v_mfma_f32_16x16x32_bf16 v[108:111], v[170:173], v[184:187], 0
	v_mfma_f32_16x16x32_bf16 v[108:111], v[178:181], v[188:191], v[108:111]
	v_mfma_f32_16x16x32_bf16 v[96:99], v[170:173], v[192:195], 0
	v_mfma_f32_16x16x32_bf16 v[96:99], v[178:181], v[196:199], v[96:99]
	v_mfma_f32_16x16x32_bf16 v[76:79], v[170:173], v[200:203], 0
	v_mfma_f32_16x16x32_bf16 v[76:79], v[178:181], v[204:207], v[76:79]
	v_mfma_f32_16x16x32_bf16 v[64:67], v[170:173], v[208:211], 0
	v_mfma_f32_16x16x32_bf16 v[64:67], v[178:181], v[212:215], v[64:67]
	s_barrier
	s_setprio 0
	s_add_i32 s26, s26, s10
	s_mov_b32 m0, s26
	ds_read_b128 v[184:187], v183 offset:16384
	ds_read_b128 v[188:191], v183 offset:17408
	ds_read_b128 v[192:195], v183 offset:18432
	ds_read_b128 v[196:199], v183 offset:19456
	ds_read_b128 v[200:203], v183 offset:20480
	ds_read_b128 v[204:207], v183 offset:21504
	ds_read_b128 v[208:211], v183 offset:22528
	ds_read_b128 v[212:215], v183 offset:23552
	global_load_lds_dwordx4 v138, s[64:65]
	s_add_i32 m0, s26, 0x2000
	s_add_u32 s42, s64, 0x160000
	s_addc_u32 s43, s65, 0
	s_add_i32 s26, s28, s10
	global_load_lds_dwordx4 v142, s[64:65]
	s_mov_b32 m0, s26
	s_nop 0
	global_load_lds_dwordx4 v138, s[42:43]
	s_add_i32 m0, s26, 0x2000
	s_nop 0
	global_load_lds_dwordx4 v142, s[42:43]
	s_mov_b32 m0, s13
	s_nop 0
	global_load_lds_dwordx4 v136, s[66:67]
	s_mov_b32 m0, s18
	s_nop 0
	global_load_lds_dwordx4 v140, s[66:67]
	s_waitcnt vmcnt(8)
	s_waitcnt lgkmcnt(0)
	s_setprio 1
	s_barrier
	v_mfma_f32_16x16x32_bf16 v[60:63], v[128:131], v[184:187], 0
	v_mfma_f32_16x16x32_bf16 v[60:63], v[132:135], v[188:191], v[60:63]
	v_mfma_f32_16x16x32_bf16 v[48:51], v[128:131], v[192:195], 0
	v_mfma_f32_16x16x32_bf16 v[48:51], v[132:135], v[196:199], v[48:51]
	v_mfma_f32_16x16x32_bf16 v[28:31], v[128:131], v[200:203], 0
	v_mfma_f32_16x16x32_bf16 v[28:31], v[132:135], v[204:207], v[28:31]
	v_mfma_f32_16x16x32_bf16 v[16:19], v[128:131], v[208:211], 0
	v_mfma_f32_16x16x32_bf16 v[16:19], v[132:135], v[212:215], v[16:19]
	v_mfma_f32_16x16x32_bf16 v[56:59], v[148:151], v[184:187], 0
	v_mfma_f32_16x16x32_bf16 v[56:59], v[152:155], v[188:191], v[56:59]
	v_mfma_f32_16x16x32_bf16 v[40:43], v[148:151], v[192:195], 0
	v_mfma_f32_16x16x32_bf16 v[40:43], v[152:155], v[196:199], v[40:43]
	v_mfma_f32_16x16x32_bf16 v[24:27], v[148:151], v[200:203], 0
	v_mfma_f32_16x16x32_bf16 v[24:27], v[152:155], v[204:207], v[24:27]
	v_mfma_f32_16x16x32_bf16 v[8:11], v[148:151], v[208:211], 0
	v_mfma_f32_16x16x32_bf16 v[8:11], v[152:155], v[212:215], v[8:11]
	v_mfma_f32_16x16x32_bf16 v[52:55], v[156:159], v[184:187], 0
	v_mfma_f32_16x16x32_bf16 v[52:55], v[160:163], v[188:191], v[52:55]
	v_mfma_f32_16x16x32_bf16 v[36:39], v[156:159], v[192:195], 0
	v_mfma_f32_16x16x32_bf16 v[36:39], v[160:163], v[196:199], v[36:39]
	v_mfma_f32_16x16x32_bf16 v[20:23], v[156:159], v[200:203], 0
	v_mfma_f32_16x16x32_bf16 v[20:23], v[160:163], v[204:207], v[20:23]
	v_mfma_f32_16x16x32_bf16 v[4:7], v[156:159], v[208:211], 0
	v_mfma_f32_16x16x32_bf16 v[4:7], v[160:163], v[212:215], v[4:7]
	v_mfma_f32_16x16x32_bf16 v[44:47], v[170:173], v[184:187], 0
	v_mfma_f32_16x16x32_bf16 v[44:47], v[178:181], v[188:191], v[44:47]
	v_mfma_f32_16x16x32_bf16 v[32:35], v[170:173], v[192:195], 0
	v_mfma_f32_16x16x32_bf16 v[32:35], v[178:181], v[196:199], v[32:35]
	v_mfma_f32_16x16x32_bf16 v[12:15], v[170:173], v[200:203], 0
	v_mfma_f32_16x16x32_bf16 v[12:15], v[178:181], v[204:207], v[12:15]
	v_mfma_f32_16x16x32_bf16 v[0:3], v[170:173], v[208:211], 0
	v_mfma_f32_16x16x32_bf16 v[0:3], v[178:181], v[212:215], v[0:3]
	s_barrier
; #define PG8_STAGE(bufoff, gbase, voff) do { _Pragma("unroll") for (int _i = 0; _i < 2; ++_i) \
;         __builtin_amdgcn_global_load_lds((const unsigned*)((const char*)(gbase) + (voff)[_i]), (PG8_LAS unsigned*)(lds + (bufoff) + ldsw + _i * 8192), 16, 0, 0); } while (0)
; #define PG8_LDA(dst, b, h) do { _Pragma("unroll") for (int m = 0; m < 4; ++m) _Pragma("unroll") for (int k = 0; k < 2; ++k) dst[m][k] = *(const PG8_LAS bf16x8*)(lds + PG8_SA(b, h) + aoff + m * 2048 + k * 1024); } while (0)
; #define PG8_LDB(dst, b, h) do { _Pragma("unroll") for (int n = 0; n < 2; ++n) _Pragma("unroll") for (int k = 0; k < 2; ++k) dst[n][k] = *(const PG8_LAS bf16x8*)(lds + PG8_SB(b, h) + boff + n * 2048 + k * 1024); } while (0)
; #define PG8_MMA(ai, bj, At, Bt) do { __builtin_amdgcn_s_setprio(1); _Pragma("unroll") for (int m = 0; m < 4; ++m) _Pragma("unroll") for (int n = 0; n < 2; ++n) _Pragma("unroll") for (int k = 0; k < 2; ++k) \
;         acc[ai][bj][m][n] = __builtin_amdgcn_mfma_f32_16x16x32_bf16(Bt[n][k], At[m][k], acc[ai][bj][m][n], 0, 0, 0); __builtin_amdgcn_s_setprio(0); } while (0)
; #define PG8_WAIT_V(n) asm volatile("s_waitcnt vmcnt(" #n ")" ::: "memory")
; #define PG8_WAIT_L(n) asm volatile("s_waitcnt lgkmcnt(" #n ")" ::: "memory")
; #define PG8_BAR __builtin_amdgcn_s_barrier()
; #define PG8_SCHED __builtin_amdgcn_sched_barrier(0)
;     ...
;             PG8_LDB(B0, 1, 0); PG8_LDB(B1, 1, 1); PG8_SCHED; PG8_LDA(At, 1, 0); PG8_STAGE(PG8_SA(0, 1), a2 + hstep, voffA);
;             PG8_WAIT_V(8); PG8_WAIT_L(0); PG8_BAR; PG8_MMA(0, 0, At, B0); PG8_MMA(0, 1, At, B1); PG8_BAR; PG8_SCHED;
;             PG8_LDA(At, 1, 1); PG8_STAGE(PG8_SB(1, 0), b3, voffB); PG8_STAGE(PG8_SB(1, 1), b3 + hstep, voffB); PG8_STAGE(PG8_SA(1, 0), a3, voffA);
;             PG8_WAIT_V(8); PG8_WAIT_L(0); PG8_BAR; PG8_MMA(1, 0, At, B0); PG8_MMA(1, 1, At, B1); PG8_BAR; PG8_SCHED;
	s_setprio 0
	s_add_i32 s26, 0, 0x18000
	s_add_i32 s28, 0, 0x1c000
	v_add_u32_e32 v152, s26, v166
	v_add_u32_e32 v168, s28, v166
	ds_read_b128 v[128:131], v152
	ds_read_b128 v[132:135], v152 offset:1024
	ds_read_b128 v[148:151], v152 offset:2048
	ds_read_b128 v[152:155], v152 offset:3072
	ds_read_b128 v[156:159], v168
	ds_read_b128 v[160:163], v168 offset:1024
	ds_read_b128 v[170:173], v168 offset:2048
	ds_read_b128 v[178:181], v168 offset:3072
	s_add_u32 s42, s66, 0x160000
	s_addc_u32 s43, s67, 0
	s_mov_b32 m0, s19
	ds_read_b128 v[184:187], v183 offset:32768
	ds_read_b128 v[188:191], v183 offset:33792
	ds_read_b128 v[192:195], v183 offset:34816
	ds_read_b128 v[196:199], v183 offset:35840
	ds_read_b128 v[200:203], v183 offset:36864
	ds_read_b128 v[204:207], v183 offset:37888
	ds_read_b128 v[208:211], v183 offset:38912
	ds_read_b128 v[212:215], v183 offset:39936
	global_load_lds_dwordx4 v136, s[42:43]
	s_mov_b32 m0, s20
	s_nop 0
	global_load_lds_dwordx4 v140, s[42:43]
	s_waitcnt vmcnt(8)
	s_waitcnt lgkmcnt(0)
	s_setprio 1
	s_barrier
	v_mfma_f32_16x16x32_bf16 v[124:127], v[128:131], v[184:187], v[124:127]
	v_mfma_f32_16x16x32_bf16 v[124:127], v[132:135], v[188:191], v[124:127]
	v_mfma_f32_16x16x32_bf16 v[112:115], v[128:131], v[192:195], v[112:115]
	v_mfma_f32_16x16x32_bf16 v[112:115], v[132:135], v[196:199], v[112:115]
	v_mfma_f32_16x16x32_bf16 v[92:95], v[128:131], v[200:203], v[92:95]
	v_mfma_f32_16x16x32_bf16 v[92:95], v[132:135], v[204:207], v[92:95]
	v_mfma_f32_16x16x32_bf16 v[80:83], v[128:131], v[208:211], v[80:83]
	v_mfma_f32_16x16x32_bf16 v[80:83], v[132:135], v[212:215], v[80:83]
	v_mfma_f32_16x16x32_bf16 v[120:123], v[148:151], v[184:187], v[120:123]
	v_mfma_f32_16x16x32_bf16 v[120:123], v[152:155], v[188:191], v[120:123]
	v_mfma_f32_16x16x32_bf16 v[104:107], v[148:151], v[192:195], v[104:107]
	v_mfma_f32_16x16x32_bf16 v[104:107], v[152:155], v[196:199], v[104:107]
	v_mfma_f32_16x16x32_bf16 v[88:91], v[148:151], v[200:203], v[88:91]
	v_mfma_f32_16x16x32_bf16 v[88:91], v[152:155], v[204:207], v[88:91]
	v_mfma_f32_16x16x32_bf16 v[72:75], v[148:151], v[208:211], v[72:75]
	v_mfma_f32_16x16x32_bf16 v[72:75], v[152:155], v[212:215], v[72:75]
	v_mfma_f32_16x16x32_bf16 v[116:119], v[156:159], v[184:187], v[116:119]
	v_mfma_f32_16x16x32_bf16 v[116:119], v[160:163], v[188:191], v[116:119]
	v_mfma_f32_16x16x32_bf16 v[100:103], v[156:159], v[192:195], v[100:103]
	v_mfma_f32_16x16x32_bf16 v[100:103], v[160:163], v[196:199], v[100:103]
	v_mfma_f32_16x16x32_bf16 v[84:87], v[156:159], v[200:203], v[84:87]
	v_mfma_f32_16x16x32_bf16 v[84:87], v[160:163], v[204:207], v[84:87]
	v_mfma_f32_16x16x32_bf16 v[68:71], v[156:159], v[208:211], v[68:71]
	v_mfma_f32_16x16x32_bf16 v[68:71], v[160:163], v[212:215], v[68:71]
	v_mfma_f32_16x16x32_bf16 v[108:111], v[170:173], v[184:187], v[108:111]
	v_mfma_f32_16x16x32_bf16 v[108:111], v[178:181], v[188:191], v[108:111]
	v_mfma_f32_16x16x32_bf16 v[96:99], v[170:173], v[192:195], v[96:99]
	v_mfma_f32_16x16x32_bf16 v[96:99], v[178:181], v[196:199], v[96:99]
	v_mfma_f32_16x16x32_bf16 v[76:79], v[170:173], v[200:203], v[76:79]
	v_mfma_f32_16x16x32_bf16 v[76:79], v[178:181], v[204:207], v[76:79]
	v_mfma_f32_16x16x32_bf16 v[64:67], v[170:173], v[208:211], v[64:67]
	v_mfma_f32_16x16x32_bf16 v[64:67], v[178:181], v[212:215], v[64:67]
	s_barrier
	s_setprio 0
	s_add_i32 s26, s26, s10
	s_mov_b32 m0, s26
	ds_read_b128 v[184:187], v183 offset:49152
	ds_read_b128 v[188:191], v183 offset:50176
	ds_read_b128 v[192:195], v183 offset:51200
	ds_read_b128 v[196:199], v183 offset:52224
	ds_read_b128 v[200:203], v183 offset:53248
	ds_read_b128 v[204:207], v183 offset:54272
	ds_read_b128 v[208:211], v183 offset:55296
	ds_read_b128 v[212:215], v183 offset:56320
	s_add_u32 s100, s64, s38
	s_addc_u32 s101, s65, s39
	global_load_lds_dwordx4 v138, s[100:101]
	s_add_i32 m0, s26, 0x2000
	s_add_u32 s42, s64, 0x15ff80
	s_addc_u32 s43, s65, 0
	s_add_i32 s26, s28, s10
	global_load_lds_dwordx4 v142, s[100:101]
	s_mov_b32 m0, s26
	s_nop 0
	global_load_lds_dwordx4 v138, s[42:43]
	s_add_i32 m0, s26, 0x2000
	s_nop 0
	global_load_lds_dwordx4 v142, s[42:43]
	s_mov_b32 m0, s12
	s_nop 0
	s_add_u32 s100, s66, s38
	s_addc_u32 s101, s67, s39
	global_load_lds_dwordx4 v136, s[100:101]
	s_mov_b32 m0, s21
	s_nop 0
	global_load_lds_dwordx4 v140, s[100:101]
	s_waitcnt vmcnt(8)
	s_waitcnt lgkmcnt(0)
	s_setprio 1
	s_barrier
	v_mfma_f32_16x16x32_bf16 v[60:63], v[128:131], v[184:187], v[60:63]
	v_mfma_f32_16x16x32_bf16 v[60:63], v[132:135], v[188:191], v[60:63]
	v_mfma_f32_16x16x32_bf16 v[48:51], v[128:131], v[192:195], v[48:51]
	v_mfma_f32_16x16x32_bf16 v[48:51], v[132:135], v[196:199], v[48:51]
	v_mfma_f32_16x16x32_bf16 v[28:31], v[128:131], v[200:203], v[28:31]
	v_mfma_f32_16x16x32_bf16 v[28:31], v[132:135], v[204:207], v[28:31]
	v_mfma_f32_16x16x32_bf16 v[16:19], v[128:131], v[208:211], v[16:19]
	v_mfma_f32_16x16x32_bf16 v[16:19], v[132:135], v[212:215], v[16:19]
	v_mfma_f32_16x16x32_bf16 v[56:59], v[148:151], v[184:187], v[56:59]
	v_mfma_f32_16x16x32_bf16 v[56:59], v[152:155], v[188:191], v[56:59]
	v_mfma_f32_16x16x32_bf16 v[40:43], v[148:151], v[192:195], v[40:43]
	v_mfma_f32_16x16x32_bf16 v[40:43], v[152:155], v[196:199], v[40:43]
	v_mfma_f32_16x16x32_bf16 v[24:27], v[148:151], v[200:203], v[24:27]
	v_mfma_f32_16x16x32_bf16 v[24:27], v[152:155], v[204:207], v[24:27]
	v_mfma_f32_16x16x32_bf16 v[8:11], v[148:151], v[208:211], v[8:11]
	v_mfma_f32_16x16x32_bf16 v[8:11], v[152:155], v[212:215], v[8:11]
	v_mfma_f32_16x16x32_bf16 v[52:55], v[156:159], v[184:187], v[52:55]
	v_mfma_f32_16x16x32_bf16 v[52:55], v[160:163], v[188:191], v[52:55]
	v_mfma_f32_16x16x32_bf16 v[36:39], v[156:159], v[192:195], v[36:39]
	v_mfma_f32_16x16x32_bf16 v[36:39], v[160:163], v[196:199], v[36:39]
	v_mfma_f32_16x16x32_bf16 v[20:23], v[156:159], v[200:203], v[20:23]
	v_mfma_f32_16x16x32_bf16 v[20:23], v[160:163], v[204:207], v[20:23]
	v_mfma_f32_16x16x32_bf16 v[4:7], v[156:159], v[208:211], v[4:7]
	v_mfma_f32_16x16x32_bf16 v[4:7], v[160:163], v[212:215], v[4:7]
	v_mfma_f32_16x16x32_bf16 v[44:47], v[170:173], v[184:187], v[44:47]
	v_mfma_f32_16x16x32_bf16 v[44:47], v[178:181], v[188:191], v[44:47]
	v_mfma_f32_16x16x32_bf16 v[32:35], v[170:173], v[192:195], v[32:35]
	v_mfma_f32_16x16x32_bf16 v[32:35], v[178:181], v[196:199], v[32:35]
	v_mfma_f32_16x16x32_bf16 v[12:15], v[170:173], v[200:203], v[12:15]
	v_mfma_f32_16x16x32_bf16 v[12:15], v[178:181], v[204:207], v[12:15]
	v_mfma_f32_16x16x32_bf16 v[0:3], v[170:173], v[208:211], v[0:3]
	v_mfma_f32_16x16x32_bf16 v[0:3], v[178:181], v[212:215], v[0:3]
	s_barrier
	s_setprio 0
	s_add_i32 s3, s3, 2
	s_add_u32 s2, s2, 0xffffff00
	s_addc_u32 s25, s25, -1
	s_cmpk_gt_u32 s3, 0x55
	s_mov_b64 s[60:61], s[62:63]
